# xor-butterfly wave sums: ds_bpermute steps replaced by DPP / permlane-swap VALU moves (same pairing order)
# speedup vs baseline: 1.0130x; 1.0020x over previous
; __device__ __forceinline__ unsigned cvt_pk_bf16(float lo, float hi) { unsigned r; asm volatile("v_cvt_pk_bf16_f32 %0, %1, %2" : "=v"(r) : "v"(lo), "v"(hi)); return r; }
; __device__ __forceinline__ float bflo(unsigned w) { return __uint_as_float(w << 16); }
; __device__ __forceinline__ float bfhi(unsigned w) { return __uint_as_float(w & 0xffff0000u); }
; __device__ void phase_resid(const float* xin, float* xout, const bf16_t* Y, const float* pg, const float* ng, bf16_t* H2, int nrows) {
;     ...
;     for (; row < nrows; row += stride) {
;         f32x4 y[4], xv[4];
; #pragma unroll
;         for (int i = 0; i < 4; ++i) { y[i] = (f32x4){bflo(ny[i].x), bfhi(ny[i].x), bflo(ny[i].y), bfhi(ny[i].y)}; xv[i] = nx[i]; }
;         const int rn = row + stride;
;         if (rn < nrows) {
; #pragma unroll
;             for (int i = 0; i < 4; ++i) { ny[i] = *(const u32x2*)(Y + (size_t)rn * DM + i * 256 + lane * 4); nx[i] = *(const f32x4*)(xin + (size_t)rn * DM + i * 256 + lane * 4); }
;         }
;         float ss = 0.f;
; #pragma unroll
;         for (int i = 0; i < 4; ++i) ss += y[i][0] * y[i][0] + y[i][1] * y[i][1] + y[i][2] * y[i][2] + y[i][3] * y[i][3];
;         ss = wave_sum(ss);
;         const float r = rsqrtf(ss * (1.0f / DM) + EPS);
;         float s2 = 0.f;
; #pragma unroll
;         for (int i = 0; i < 4; ++i) { xv[i] = xv[i] + y[i] * r * pgv[i]; *(f32x4*)(xout + (size_t)row * DM + i * 256 + lane * 4) = xv[i];
;             s2 += xv[i][0] * xv[i][0] + xv[i][1] * xv[i][1] + xv[i][2] * xv[i][2] + xv[i][3] * xv[i][3]; }
;         if (ng) {
;             s2 = wave_sum(s2);
;             const float r2 = rsqrtf(s2 * (1.0f / DM) + EPS);
; #pragma unroll
;             for (int i = 0; i < 4; ++i) { const f32x4 h = xv[i] * r2 * ngv[i]; u32x2 w; w.x = cvt_pk_bf16(h[0], h[1]); w.y = cvt_pk_bf16(h[2], h[3]);
;                 *(u32x2*)(H2 + (size_t)row * DM + i * 256 + lane * 4) = w; }
;         }
.LBB0_109:
	s_or_b64 exec, exec, s[42:43]
	v_and_b32_e32 v101, 0xffff0000, v82
	v_and_b32_e32 v100, 0xffff0000, v76
	v_lshlrev_b32_e32 v99, 16, v82
	v_lshlrev_b32_e32 v98, 16, v76
	v_lshlrev_b32_e32 v102, 16, v77
	v_and_b32_e32 v82, 0xffff0000, v77
	v_lshlrev_b32_e32 v77, 16, v80
	v_lshlrev_b32_e32 v76, 16, v78
	v_and_b32_e32 v105, 0xffff0000, v80
	v_and_b32_e32 v104, 0xffff0000, v78
	v_lshlrev_b32_e32 v106, 16, v79
	v_and_b32_e32 v80, 0xffff0000, v79
	v_pk_mul_f32 v[78:79], v[100:101], v[100:101]
	v_lshlrev_b32_e32 v103, 16, v83
	v_pk_fma_f32 v[78:79], v[98:99], v[98:99], v[78:79]
	v_pk_mul_f32 v[108:109], v[104:105], v[104:105]
	v_and_b32_e32 v83, 0xffff0000, v83
	v_lshlrev_b32_e32 v107, 16, v81
	v_pk_fma_f32 v[78:79], v[102:103], v[102:103], v[78:79]
	v_pk_fma_f32 v[108:109], v[76:77], v[76:77], v[108:109]
	v_and_b32_e32 v81, 0xffff0000, v81
	v_pk_fma_f32 v[78:79], v[82:83], v[82:83], v[78:79]
	v_pk_fma_f32 v[108:109], v[106:107], v[106:107], v[108:109]
	v_add_f32_e32 v67, v78, v79
	v_pk_fma_f32 v[108:109], v[80:81], v[80:81], v[108:109]
	v_mov_b32_e32 v79, v100
	v_add_f32_e32 v67, v67, v108
	v_add_f32_e32 v67, v67, v109
	v_mov_b32_e32 v78, v67
	s_nop 1
	v_permlane32_swap_b32_e32 v78, v67
	s_nop 1
	v_mov_b32_e32 v109, v82
	v_mov_b32_e32 v100, v99
	s_waitcnt lgkmcnt(0)
	v_add_f32_e32 v67, v67, v78
	v_mov_b32_e32 v78, v67
	s_nop 1
	v_permlane16_swap_b32_e32 v78, v67
	s_nop 1
	s_waitcnt lgkmcnt(0)
	v_add_f32_e32 v67, v67, v78
	s_nop 1
	v_mov_b32_dpp v78, v67 row_ror:8 row_mask:0xf bank_mask:0xf
	s_waitcnt lgkmcnt(0)
	v_add_f32_e32 v67, v67, v78
	s_nop 1
	v_mov_b32_dpp v78, v67 row_shl:4 row_mask:0xf bank_mask:0x5
	s_nop 1
	v_mov_b32_dpp v78, v67 row_shr:4 row_mask:0xf bank_mask:0xa
	s_waitcnt lgkmcnt(0)
	v_add_f32_e32 v67, v67, v78
	s_nop 1
	v_mov_b32_dpp v78, v67 quad_perm:[2,3,0,1] row_mask:0xf bank_mask:0xf
	s_waitcnt lgkmcnt(0)
	v_add_f32_e32 v67, v67, v78
	s_nop 1
	v_mov_b32_dpp v108, v67 quad_perm:[1,0,3,2] row_mask:0xf bank_mask:0xf
	v_mov_b32_e32 v78, v98
	s_waitcnt lgkmcnt(0)
	v_add_f32_e32 v67, v67, v108
	v_fmamk_f32 v67, v67, 0x3a800000, v1
	v_mul_f32_e32 v98, 0x4b800000, v67
	v_cmp_gt_f32_e32 vcc, s33, v67
	v_mov_b32_e32 v108, v102
	s_nop 0
	v_cndmask_b32_e32 v67, v67, v98, vcc
	v_rsq_f32_e32 v67, v67
	s_nop 0
	v_mul_f32_e32 v82, 0x45800000, v67
	v_cndmask_b32_e32 v98, v67, v82, vcc
	v_pk_mul_f32 v[78:79], v[98:99], v[78:79] op_sel_hi:[0,1]
	v_pk_fma_f32 v[46:47], v[2:3], v[78:79], v[46:47]
	v_pk_mul_f32 v[78:79], v[98:99], v[100:101] op_sel_hi:[0,1]
	v_mov_b32_e32 v82, v103
	v_pk_mul_f32 v[82:83], v[98:99], v[82:83] op_sel_hi:[0,1]
	v_pk_fma_f32 v[42:43], v[14:15], v[78:79], v[42:43]
	v_mov_b32_e32 v78, v76
	v_mov_b32_e32 v79, v104
	v_pk_fma_f32 v[44:45], v[16:17], v[82:83], v[44:45]
	v_pk_mul_f32 v[78:79], v[98:99], v[78:79] op_sel_hi:[0,1]
	v_mov_b32_e32 v82, v106
	v_mov_b32_e32 v83, v80
	v_mov_b32_e32 v104, v77
	v_mov_b32_e32 v80, v107
	v_pk_mul_f32 v[108:109], v[98:99], v[108:109] op_sel_hi:[0,1]
	v_pk_mul_f32 v[82:83], v[98:99], v[82:83] op_sel_hi:[0,1]
	v_pk_fma_f32 v[38:39], v[18:19], v[78:79], v[38:39]
	v_pk_mul_f32 v[76:77], v[98:99], v[104:105] op_sel_hi:[0,1]
	v_pk_mul_f32 v[78:79], v[98:99], v[80:81] op_sel_hi:[0,1]
	v_pk_fma_f32 v[48:49], v[4:5], v[108:109], v[48:49]
	v_pk_fma_f32 v[40:41], v[20:21], v[82:83], v[40:41]
	v_pk_fma_f32 v[36:37], v[32:33], v[78:79], v[36:37]
	v_pk_fma_f32 v[34:35], v[30:31], v[76:77], v[34:35]
	s_and_b64 vcc, exec, s[36:37]
	global_store_dwordx4 v[74:75], v[46:49], off offset:-2048
	global_store_dwordx4 v[74:75], v[42:45], off offset:-1024
	global_store_dwordx4 v[74:75], v[38:41], off
	global_store_dwordx4 v[74:75], v[34:37], off offset:1024
	s_cbranch_vccnz .LBB0_106
	v_mov_b32_e32 v82, v47
	v_mov_b32_e32 v83, v43
	v_mov_b32_e32 v80, v46
	v_mov_b32_e32 v81, v42
	v_pk_mul_f32 v[82:83], v[82:83], v[82:83]
	v_mov_b32_e32 v98, v35
	v_mov_b32_e32 v99, v39
	v_mov_b32_e32 v78, v48
	v_mov_b32_e32 v79, v44
	v_pk_fma_f32 v[80:81], v[80:81], v[80:81], v[82:83]
	v_mov_b32_e32 v82, v34
	v_mov_b32_e32 v83, v38
	v_pk_mul_f32 v[98:99], v[98:99], v[98:99]
	v_mov_b32_e32 v76, v49
	v_mov_b32_e32 v77, v45
	v_pk_fma_f32 v[78:79], v[78:79], v[78:79], v[80:81]
	v_mov_b32_e32 v80, v36
	v_mov_b32_e32 v81, v40
	v_pk_fma_f32 v[82:83], v[82:83], v[82:83], v[98:99]
	v_pk_fma_f32 v[76:77], v[76:77], v[76:77], v[78:79]
	v_mov_b32_e32 v78, v37
	v_mov_b32_e32 v79, v41
	v_pk_fma_f32 v[80:81], v[80:81], v[80:81], v[82:83]
	v_add_f32_e32 v67, v76, v77
	v_pk_fma_f32 v[78:79], v[78:79], v[78:79], v[80:81]
	s_nop 0
	v_add_f32_e32 v67, v79, v67
	v_add_f32_e32 v67, v78, v67
	v_mov_b32_e32 v76, v67
	s_nop 1
	v_permlane32_swap_b32_e32 v76, v67
	s_nop 1
	s_waitcnt lgkmcnt(0)
	v_add_f32_e32 v67, v67, v76
	v_mov_b32_e32 v76, v67
	s_nop 1
	v_permlane16_swap_b32_e32 v76, v67
	s_nop 1
	s_waitcnt lgkmcnt(0)
	v_add_f32_e32 v67, v67, v76
	s_nop 1
	v_mov_b32_dpp v76, v67 row_ror:8 row_mask:0xf bank_mask:0xf
	s_waitcnt lgkmcnt(0)
	v_add_f32_e32 v67, v67, v76
	s_nop 1
	v_mov_b32_dpp v76, v67 row_shl:4 row_mask:0xf bank_mask:0x5
	s_nop 1
	v_mov_b32_dpp v76, v67 row_shr:4 row_mask:0xf bank_mask:0xa
	s_waitcnt lgkmcnt(0)
	v_add_f32_e32 v67, v67, v76
	s_nop 1
	v_mov_b32_dpp v76, v67 quad_perm:[2,3,0,1] row_mask:0xf bank_mask:0xf
	s_waitcnt lgkmcnt(0)
	v_add_f32_e32 v67, v67, v76
	s_nop 1
	v_mov_b32_dpp v76, v67 quad_perm:[1,0,3,2] row_mask:0xf bank_mask:0xf
	s_waitcnt lgkmcnt(0)
	v_add_f32_e32 v67, v67, v76
	v_fmamk_f32 v67, v67, 0x3a800000, v1
	v_mul_f32_e32 v76, 0x4b800000, v67
	v_cmp_gt_f32_e32 vcc, s33, v67
	s_nop 1
	v_cndmask_b32_e32 v67, v67, v76, vcc
	v_rsq_f32_e32 v67, v67
	s_nop 0
	v_mul_f32_e32 v76, 0x45800000, v67
	v_cndmask_b32_e32 v76, v67, v76, vcc
	v_pk_mul_f32 v[46:47], v[46:47], v[76:77] op_sel_hi:[1,0]
	v_pk_mul_f32 v[42:43], v[42:43], v[76:77] op_sel_hi:[1,0]
	v_pk_mul_f32 v[38:39], v[38:39], v[76:77] op_sel_hi:[1,0]
	v_pk_mul_f32 v[34:35], v[34:35], v[76:77] op_sel_hi:[1,0]
	v_pk_mul_f32 v[48:49], v[48:49], v[76:77] op_sel_hi:[1,0]
	v_pk_mul_f32 v[44:45], v[44:45], v[76:77] op_sel_hi:[1,0]
	v_pk_mul_f32 v[46:47], v[10:11], v[46:47]
	v_pk_mul_f32 v[42:43], v[6:7], v[42:43]
	v_pk_mul_f32 v[40:41], v[40:41], v[76:77] op_sel_hi:[1,0]
	v_pk_mul_f32 v[38:39], v[26:27], v[38:39]
	v_pk_mul_f32 v[36:37], v[36:37], v[76:77] op_sel_hi:[1,0]
	v_pk_mul_f32 v[34:35], v[22:23], v[34:35]
	v_pk_mul_f32 v[48:49], v[12:13], v[48:49]
	v_pk_mul_f32 v[44:45], v[8:9], v[44:45]
	v_cvt_pk_bf16_f32 v46, v46, v47
	v_cvt_pk_bf16_f32 v47, v48, v49
	global_store_dwordx2 v[72:73], v[46:47], off offset:-1024
	v_cvt_pk_bf16_f32 v42, v42, v43
	v_cvt_pk_bf16_f32 v43, v44, v45
	global_store_dwordx2 v[72:73], v[42:43], off offset:-512
	v_pk_mul_f32 v[40:41], v[28:29], v[40:41]
	v_cvt_pk_bf16_f32 v38, v38, v39
	v_pk_mul_f32 v[36:37], v[24:25], v[36:37]
	v_cvt_pk_bf16_f32 v39, v40, v41
	global_store_dwordx2 v[72:73], v[38:39], off
	v_cvt_pk_bf16_f32 v34, v34, v35
	v_cvt_pk_bf16_f32 v35, v36, v37
	global_store_dwordx2 v[72:73], v[34:35], off offset:512
	s_branch .LBB0_106

; #define LAS __attribute__((address_space(3)))
; __device__ __forceinline__ unsigned cvt_pk_bf16(float lo, float hi) { unsigned r; asm volatile("v_cvt_pk_bf16_f32 %0, %1, %2" : "=v"(r) : "v"(lo), "v"(hi)); return r; }
; __device__ void phase_norm_alow(const Params& P, int l, int half, LAS unsigned char* lds) {
;     ...
;     for (; row < TH; row += rstride) {
;         f32x4 v[4]; float ss = 0.f;
; #pragma unroll
;         for (int i = 0; i < 4; ++i) { v[i] = nv[i]; ss += v[i][0] * v[i][0] + v[i][1] * v[i][1] + v[i][2] * v[i][2] + v[i][3] * v[i][3]; }
;         if (row + rstride < TH) {
; #pragma unroll
;             for (int i = 0; i < 4; ++i) nv[i] = *(const f32x4*)(xs + (size_t)(row + rstride) * DM + i * 256 + lane * 4);
;         }
;         ss = wave_sum(ss);
;         const float r = rsqrtf(ss * (1.0f / DM) + EPS);
;         float a[16];
; #pragma unroll
;         for (int c = 0; c < 16; ++c) a[c] = 0.f;
; #pragma unroll
;         for (int i = 0; i < 4; ++i) { f32x4 h = v[i] * r * gv[i];
;             u32x2 w; w.x = cvt_pk_bf16(h[0], h[1]); w.y = cvt_pk_bf16(h[2], h[3]);
;             *(u32x2*)(H + (size_t)row * DM + i * 256 + lane * 4) = w;
; #pragma unroll
;             for (int c = 0; c < 16; ++c) { const f32x4 wv = *(const LAS f32x4*)(WaT + c * 1024 + i * 256 + lane * 4); a[c] += h[0] * wv[0] + h[1] * wv[1] + h[2] * wv[2] + h[3] * wv[3]; } }
.LBB0_120:
	s_or_b64 exec, exec, s[30:31]
	v_mul_f32_e32 v51, v47, v47
	v_mul_f32_e32 v58, v43, v43
	v_fmac_f32_e32 v51, v46, v46
	v_fmac_f32_e32 v58, v42, v42
	v_fmac_f32_e32 v51, v48, v48
	v_fmac_f32_e32 v58, v44, v44
	v_fmac_f32_e32 v51, v49, v49
	v_fmac_f32_e32 v58, v45, v45
	v_add_f32_e32 v51, v51, v58
	v_mul_f32_e32 v58, v39, v39
	v_fmac_f32_e32 v58, v38, v38
	v_fmac_f32_e32 v58, v40, v40
	v_fmac_f32_e32 v58, v41, v41
	v_add_f32_e32 v51, v51, v58
	v_mul_f32_e32 v58, v35, v35
	v_fmac_f32_e32 v58, v34, v34
	v_fmac_f32_e32 v58, v36, v36
	v_fmac_f32_e32 v58, v37, v37
	v_add_f32_e32 v51, v51, v58
	v_mov_b32_e32 v58, v51
	s_nop 1
	v_permlane32_swap_b32_e32 v58, v51
	s_nop 1
	v_lshl_add_u64 v[68:69], s[74:75], 0, v[56:57]
	s_waitcnt lgkmcnt(0)
	v_add_f32_e32 v51, v51, v58
	v_mov_b32_e32 v58, v51
	s_nop 1
	v_permlane16_swap_b32_e32 v58, v51
	s_nop 1
	s_waitcnt lgkmcnt(0)
	v_add_f32_e32 v51, v51, v58
	s_nop 1
	v_mov_b32_dpp v58, v51 row_ror:8 row_mask:0xf bank_mask:0xf
	s_waitcnt lgkmcnt(0)
	v_add_f32_e32 v51, v51, v58
	s_nop 1
	v_mov_b32_dpp v58, v51 row_shl:4 row_mask:0xf bank_mask:0x5
	s_nop 1
	v_mov_b32_dpp v58, v51 row_shr:4 row_mask:0xf bank_mask:0xa
	s_waitcnt lgkmcnt(0)
	v_add_f32_e32 v51, v51, v58
	s_nop 1
	v_mov_b32_dpp v58, v51 quad_perm:[2,3,0,1] row_mask:0xf bank_mask:0xf
	s_waitcnt lgkmcnt(0)
	v_add_f32_e32 v51, v51, v58
	s_nop 1
	v_mov_b32_dpp v58, v51 quad_perm:[1,0,3,2] row_mask:0xf bank_mask:0xf
	s_waitcnt lgkmcnt(0)
	v_add_f32_e32 v51, v51, v58
	v_fmamk_f32 v51, v51, 0x3a800000, v1
	v_cmp_gt_f32_e64 s[0:1], s33, v51
	v_mul_f32_e32 v58, 0x4b800000, v51
	s_nop 0
	v_cndmask_b32_e64 v51, v51, v58, s[0:1]
	v_rsq_f32_e32 v51, v51
	s_nop 0
	v_mul_f32_e32 v58, 0x45800000, v51
	v_cndmask_b32_e64 v58, v51, v58, s[0:1]
	v_pk_mul_f32 v[46:47], v[46:47], v[58:59] op_sel_hi:[1,0]
	s_mov_b32 s0, 0x5a88000
	v_pk_mul_f32 v[48:49], v[48:49], v[58:59] op_sel_hi:[1,0]
	v_pk_mul_f32 v[60:61], v[14:15], v[46:47]
	v_add_co_u32_e64 v46, s[0:1], s0, v68
	v_pk_mul_f32 v[48:49], v[16:17], v[48:49]
	v_cvt_pk_bf16_f32 v70, v60, v61
	s_nop 0
	v_addc_co_u32_e64 v47, s[0:1], 0, v69, s[0:1]
	v_cvt_pk_bf16_f32 v71, v48, v49
	global_store_dwordx2 v[46:47], v[70:71], off
	ds_read_b128 v[100:103], v67
	ds_read_b128 v[104:107], v67 offset:4096
	ds_read_b128 v[108:111], v67 offset:8192
	ds_read_b128 v[112:115], v67 offset:12288
	ds_read_b128 v[116:119], v67 offset:16384
	ds_read_b128 v[120:123], v67 offset:20480
	ds_read_b128 v[124:127], v67 offset:24576
	s_waitcnt lgkmcnt(6)
	v_mul_f32_e32 v51, v101, v61
	v_fmac_f32_e32 v51, v100, v60
	v_fmac_f32_e32 v51, v102, v48
	v_fmac_f32_e32 v51, v103, v49
	ds_read_b128 v[128:131], v67 offset:28672
	v_add_f32_e32 v69, 0, v51
	s_waitcnt lgkmcnt(6)
	v_mul_f32_e32 v51, v105, v61
	v_fmac_f32_e32 v51, v104, v60
	v_fmac_f32_e32 v51, v106, v48
	v_fmac_f32_e32 v51, v107, v49
	ds_read_b128 v[100:103], v67 offset:32768
	v_add_f32_e32 v51, 0, v51
	s_waitcnt lgkmcnt(6)
	v_mul_f32_e32 v68, v109, v61
	v_fmac_f32_e32 v68, v108, v60
	v_fmac_f32_e32 v68, v110, v48
	v_fmac_f32_e32 v68, v111, v49
	ds_read_b128 v[104:107], v67 offset:36864
	v_add_f32_e32 v68, 0, v68
	s_waitcnt lgkmcnt(6)
	v_mul_f32_e32 v71, v113, v61
	v_fmac_f32_e32 v71, v112, v60
	v_fmac_f32_e32 v71, v114, v48
	v_fmac_f32_e32 v71, v115, v49
	ds_read_b128 v[108:111], v67 offset:40960
	v_add_f32_e32 v70, 0, v71
	s_waitcnt lgkmcnt(6)
	v_mul_f32_e32 v71, v117, v61
	v_fmac_f32_e32 v71, v116, v60
	v_fmac_f32_e32 v71, v118, v48
	v_fmac_f32_e32 v71, v119, v49
	ds_read_b128 v[112:115], v67 offset:45056
	v_add_f32_e32 v71, 0, v71
	s_waitcnt lgkmcnt(6)
	v_mul_f32_e32 v73, v121, v61
	v_fmac_f32_e32 v73, v120, v60
	v_fmac_f32_e32 v73, v122, v48
	v_fmac_f32_e32 v73, v123, v49
	ds_read_b128 v[116:119], v67 offset:49152
	v_add_f32_e32 v72, 0, v73
	s_waitcnt lgkmcnt(6)
	v_mul_f32_e32 v73, v125, v61
	v_fmac_f32_e32 v73, v124, v60
	v_fmac_f32_e32 v73, v126, v48
	v_fmac_f32_e32 v73, v127, v49
	ds_read_b128 v[120:123], v67 offset:53248
	v_add_f32_e32 v73, 0, v73
	s_waitcnt lgkmcnt(6)
	v_mul_f32_e32 v75, v129, v61
	v_fmac_f32_e32 v75, v128, v60
	v_fmac_f32_e32 v75, v130, v48
	v_fmac_f32_e32 v75, v131, v49
	ds_read_b128 v[124:127], v67 offset:57344
	v_add_f32_e32 v74, 0, v75
	s_waitcnt lgkmcnt(6)
	v_mul_f32_e32 v75, v101, v61
	v_fmac_f32_e32 v75, v100, v60
	v_fmac_f32_e32 v75, v102, v48
	v_fmac_f32_e32 v75, v103, v49
	ds_read_b128 v[128:131], v67 offset:61440
	v_add_f32_e32 v75, 0, v75
	s_waitcnt lgkmcnt(6)
	v_mul_f32_e32 v77, v61, v105
	v_fmac_f32_e32 v77, v60, v104
	v_fmac_f32_e32 v77, v48, v106
	v_fmac_f32_e32 v77, v49, v107
	ds_read_b128 v[100:103], v67 offset:1024
	v_add_f32_e32 v76, 0, v77
	s_waitcnt lgkmcnt(6)
	v_mul_f32_e32 v77, v61, v109
	v_fmac_f32_e32 v77, v60, v108
	v_fmac_f32_e32 v77, v48, v110
	v_fmac_f32_e32 v77, v49, v111
	ds_read_b128 v[104:107], v67 offset:5120
	v_add_f32_e32 v77, 0, v77
	s_waitcnt lgkmcnt(6)
	v_mul_f32_e32 v79, v61, v113
	v_fmac_f32_e32 v79, v60, v112
	v_fmac_f32_e32 v79, v48, v114
	v_fmac_f32_e32 v79, v49, v115
	ds_read_b128 v[108:111], v67 offset:9216
	v_add_f32_e32 v78, 0, v79
	s_waitcnt lgkmcnt(6)
	v_mul_f32_e32 v79, v61, v117
	v_fmac_f32_e32 v79, v60, v116
	v_fmac_f32_e32 v79, v48, v118
	v_fmac_f32_e32 v79, v49, v119
	ds_read_b128 v[112:115], v67 offset:13312
	v_add_f32_e32 v79, 0, v79
	s_waitcnt lgkmcnt(6)
	v_mul_f32_e32 v81, v61, v121
	v_fmac_f32_e32 v81, v60, v120
	v_fmac_f32_e32 v81, v48, v122
	v_fmac_f32_e32 v81, v49, v123
	ds_read_b128 v[116:119], v67 offset:17408
	v_add_f32_e32 v80, 0, v81
	s_waitcnt lgkmcnt(6)
	v_mul_f32_e32 v81, v61, v125
	v_fmac_f32_e32 v81, v60, v124
	v_fmac_f32_e32 v81, v48, v126
	v_fmac_f32_e32 v81, v49, v127
	ds_read_b128 v[120:123], v67 offset:21504
	v_add_f32_e32 v81, 0, v81
	s_waitcnt lgkmcnt(6)
; #define LAS __attribute__((address_space(3)))
; __device__ __forceinline__ unsigned cvt_pk_bf16(float lo, float hi) { unsigned r; asm volatile("v_cvt_pk_bf16_f32 %0, %1, %2" : "=v"(r) : "v"(lo), "v"(hi)); return r; }
; __device__ void phase_norm_alow(const Params& P, int l, int half, LAS unsigned char* lds) {
;     ...
; #pragma unroll
;         for (int i = 0; i < 4; ++i) { f32x4 h = v[i] * r * gv[i];
;             u32x2 w; w.x = cvt_pk_bf16(h[0], h[1]); w.y = cvt_pk_bf16(h[2], h[3]);
;             *(u32x2*)(H + (size_t)row * DM + i * 256 + lane * 4) = w;
; #pragma unroll
;             for (int c = 0; c < 16; ++c) { const f32x4 wv = *(const LAS f32x4*)(WaT + c * 1024 + i * 256 + lane * 4); a[c] += h[0] * wv[0] + h[1] * wv[1] + h[2] * wv[2] + h[3] * wv[3]; } }
	v_mul_f32_e32 v61, v61, v129
	v_fmac_f32_e32 v61, v60, v128
	v_fmac_f32_e32 v61, v48, v130
	v_fmac_f32_e32 v61, v49, v131
	v_add_f32_e32 v48, 0, v61
	v_pk_mul_f32 v[60:61], v[42:43], v[58:59] op_sel_hi:[1,0]
	v_pk_mul_f32 v[42:43], v[44:45], v[58:59] op_sel_hi:[1,0]
	v_pk_mul_f32 v[44:45], v[10:11], v[60:61]
	v_pk_mul_f32 v[42:43], v[12:13], v[42:43]
	v_cvt_pk_bf16_f32 v60, v44, v45
	s_nop 0
	v_cvt_pk_bf16_f32 v61, v42, v43
	ds_read_b128 v[124:127], v67 offset:25600
	global_store_dwordx2 v[46:47], v[60:61], off offset:512
	s_waitcnt lgkmcnt(6)
	v_mul_f32_e32 v49, v45, v101
	v_fmac_f32_e32 v49, v44, v100
	v_fmac_f32_e32 v49, v42, v102
	v_fmac_f32_e32 v49, v43, v103
	ds_read_b128 v[128:131], v67 offset:29696
	v_add_f32_e32 v49, v69, v49
	s_waitcnt lgkmcnt(6)
	v_mul_f32_e32 v60, v45, v105
	v_fmac_f32_e32 v60, v44, v104
	v_fmac_f32_e32 v60, v42, v106
	v_fmac_f32_e32 v60, v43, v107
	ds_read_b128 v[100:103], v67 offset:33792
	v_add_f32_e32 v51, v51, v60
	s_waitcnt lgkmcnt(6)
	v_mul_f32_e32 v60, v45, v109
	v_fmac_f32_e32 v60, v44, v108
	v_fmac_f32_e32 v60, v42, v110
	v_fmac_f32_e32 v60, v43, v111
	ds_read_b128 v[104:107], v67 offset:37888
	v_add_f32_e32 v60, v68, v60
	s_waitcnt lgkmcnt(6)
	v_mul_f32_e32 v61, v45, v113
	v_fmac_f32_e32 v61, v44, v112
	v_fmac_f32_e32 v61, v42, v114
	v_fmac_f32_e32 v61, v43, v115
	ds_read_b128 v[108:111], v67 offset:41984
	v_add_f32_e32 v61, v70, v61
	s_waitcnt lgkmcnt(6)
	v_mul_f32_e32 v68, v45, v117
	v_fmac_f32_e32 v68, v44, v116
	v_fmac_f32_e32 v68, v42, v118
	v_fmac_f32_e32 v68, v43, v119
	ds_read_b128 v[112:115], v67 offset:46080
	v_add_f32_e32 v68, v71, v68
	s_waitcnt lgkmcnt(6)
	v_mul_f32_e32 v69, v45, v121
	v_fmac_f32_e32 v69, v44, v120
	v_fmac_f32_e32 v69, v42, v122
	v_fmac_f32_e32 v69, v43, v123
	ds_read_b128 v[116:119], v67 offset:50176
	v_add_f32_e32 v69, v72, v69
	s_waitcnt lgkmcnt(6)
	v_mul_f32_e32 v70, v45, v125
	v_fmac_f32_e32 v70, v44, v124
	v_fmac_f32_e32 v70, v42, v126
	v_fmac_f32_e32 v70, v43, v127
	ds_read_b128 v[120:123], v67 offset:54272
	v_add_f32_e32 v70, v73, v70
	s_waitcnt lgkmcnt(6)
	v_mul_f32_e32 v71, v45, v129
	v_fmac_f32_e32 v71, v44, v128
	v_fmac_f32_e32 v71, v42, v130
	v_fmac_f32_e32 v71, v43, v131
	ds_read_b128 v[124:127], v67 offset:58368
	v_add_f32_e32 v71, v74, v71
	s_waitcnt lgkmcnt(6)
	v_mul_f32_e32 v72, v45, v101
	v_fmac_f32_e32 v72, v44, v100
	v_fmac_f32_e32 v72, v42, v102
	v_fmac_f32_e32 v72, v43, v103
	ds_read_b128 v[128:131], v67 offset:62464
	v_add_f32_e32 v72, v75, v72
	s_waitcnt lgkmcnt(6)
	v_mul_f32_e32 v73, v45, v105
	v_fmac_f32_e32 v73, v44, v104
	v_fmac_f32_e32 v73, v42, v106
	v_fmac_f32_e32 v73, v43, v107
	ds_read_b128 v[100:103], v67 offset:2048
	v_add_f32_e32 v73, v76, v73
	s_waitcnt lgkmcnt(6)
	v_mul_f32_e32 v74, v45, v109
	v_fmac_f32_e32 v74, v44, v108
	v_fmac_f32_e32 v74, v42, v110
	v_fmac_f32_e32 v74, v43, v111
	ds_read_b128 v[104:107], v67 offset:6144
	v_add_f32_e32 v74, v77, v74
	s_waitcnt lgkmcnt(6)
	v_mul_f32_e32 v75, v45, v113
	v_fmac_f32_e32 v75, v44, v112
	v_fmac_f32_e32 v75, v42, v114
	v_fmac_f32_e32 v75, v43, v115
	ds_read_b128 v[108:111], v67 offset:10240
	v_add_f32_e32 v75, v78, v75
	s_waitcnt lgkmcnt(6)
	v_mul_f32_e32 v76, v45, v117
	v_fmac_f32_e32 v76, v44, v116
	v_fmac_f32_e32 v76, v42, v118
	v_fmac_f32_e32 v76, v43, v119
	ds_read_b128 v[112:115], v67 offset:14336
	v_add_f32_e32 v76, v79, v76
	s_waitcnt lgkmcnt(6)
	v_mul_f32_e32 v77, v45, v121
	v_fmac_f32_e32 v77, v44, v120
	v_fmac_f32_e32 v77, v42, v122
	v_fmac_f32_e32 v77, v43, v123
	ds_read_b128 v[116:119], v67 offset:18432
	v_add_f32_e32 v77, v80, v77
	s_waitcnt lgkmcnt(6)
	v_mul_f32_e32 v78, v45, v125
	v_fmac_f32_e32 v78, v44, v124
	v_fmac_f32_e32 v78, v42, v126
	v_fmac_f32_e32 v78, v43, v127
	v_add_f32_e32 v78, v81, v78
	ds_read_b128 v[120:123], v67 offset:22528
	s_waitcnt lgkmcnt(6)
	v_mul_f32_e32 v45, v45, v129
	v_fmac_f32_e32 v45, v44, v128
	v_fmac_f32_e32 v45, v42, v130
	v_fmac_f32_e32 v45, v43, v131
	v_pk_mul_f32 v[42:43], v[38:39], v[58:59] op_sel_hi:[1,0]
	v_pk_mul_f32 v[38:39], v[40:41], v[58:59] op_sel_hi:[1,0]
	v_pk_mul_f32 v[40:41], v[6:7], v[42:43]
	v_pk_mul_f32 v[38:39], v[8:9], v[38:39]
	v_cvt_pk_bf16_f32 v42, v40, v41
	v_add_f32_e32 v79, v48, v45
	v_cvt_pk_bf16_f32 v43, v38, v39
	global_store_dwordx2 v[46:47], v[42:43], off offset:1024
	ds_read_b128 v[124:127], v67 offset:26624
	ds_read_b128 v[128:131], v67 offset:30720
	s_waitcnt lgkmcnt(7)
	v_mul_f32_e32 v43, v41, v101
	v_fmac_f32_e32 v43, v40, v100
	v_fmac_f32_e32 v43, v38, v102
	v_fmac_f32_e32 v43, v39, v103
	v_add_f32_e32 v42, v49, v43
	s_waitcnt lgkmcnt(6)
	v_mul_f32_e32 v43, v41, v105
	v_fmac_f32_e32 v43, v40, v104
	v_fmac_f32_e32 v43, v38, v106
	v_fmac_f32_e32 v43, v39, v107
	ds_read_b128 v[100:103], v67 offset:34816
	v_add_f32_e32 v43, v51, v43
	s_waitcnt lgkmcnt(6)
	v_mul_f32_e32 v44, v41, v109
	v_fmac_f32_e32 v44, v40, v108
	v_fmac_f32_e32 v44, v38, v110
	v_fmac_f32_e32 v44, v39, v111
	ds_read_b128 v[104:107], v67 offset:38912
	v_add_f32_e32 v44, v60, v44
	s_waitcnt lgkmcnt(6)
	v_mul_f32_e32 v45, v41, v113
	v_fmac_f32_e32 v45, v40, v112
	v_fmac_f32_e32 v45, v38, v114
	v_fmac_f32_e32 v45, v39, v115
	ds_read_b128 v[108:111], v67 offset:43008
	v_add_f32_e32 v45, v61, v45
	s_waitcnt lgkmcnt(6)
	v_mul_f32_e32 v48, v41, v117
	v_fmac_f32_e32 v48, v40, v116
	v_fmac_f32_e32 v48, v38, v118
	v_fmac_f32_e32 v48, v39, v119
	ds_read_b128 v[112:115], v67 offset:47104
	v_add_f32_e32 v48, v68, v48
	s_waitcnt lgkmcnt(6)
	v_mul_f32_e32 v49, v41, v121
	v_fmac_f32_e32 v49, v40, v120
	v_fmac_f32_e32 v49, v38, v122
	v_fmac_f32_e32 v49, v39, v123
	ds_read_b128 v[116:119], v67 offset:51200
	v_add_f32_e32 v49, v69, v49
	s_waitcnt lgkmcnt(6)
; #define LAS __attribute__((address_space(3)))
; __device__ __forceinline__ unsigned cvt_pk_bf16(float lo, float hi) { unsigned r; asm volatile("v_cvt_pk_bf16_f32 %0, %1, %2" : "=v"(r) : "v"(lo), "v"(hi)); return r; }
; __device__ void phase_norm_alow(const Params& P, int l, int half, LAS unsigned char* lds) {
;     ...
; #pragma unroll
;         for (int i = 0; i < 4; ++i) { f32x4 h = v[i] * r * gv[i];
;             u32x2 w; w.x = cvt_pk_bf16(h[0], h[1]); w.y = cvt_pk_bf16(h[2], h[3]);
;             *(u32x2*)(H + (size_t)row * DM + i * 256 + lane * 4) = w;
; #pragma unroll
;             for (int c = 0; c < 16; ++c) { const f32x4 wv = *(const LAS f32x4*)(WaT + c * 1024 + i * 256 + lane * 4); a[c] += h[0] * wv[0] + h[1] * wv[1] + h[2] * wv[2] + h[3] * wv[3]; } }
	v_mul_f32_e32 v51, v41, v125
	v_fmac_f32_e32 v51, v40, v124
	v_fmac_f32_e32 v51, v38, v126
	v_fmac_f32_e32 v51, v39, v127
	ds_read_b128 v[120:123], v67 offset:55296
	v_add_f32_e32 v51, v70, v51
	s_waitcnt lgkmcnt(6)
	v_mul_f32_e32 v60, v41, v129
	v_fmac_f32_e32 v60, v40, v128
	v_fmac_f32_e32 v60, v38, v130
	v_fmac_f32_e32 v60, v39, v131
	v_add_f32_e32 v60, v71, v60
	ds_read_b128 v[124:127], v67 offset:59392
	s_waitcnt lgkmcnt(6)
	v_mul_f32_e32 v61, v41, v101
	v_fmac_f32_e32 v61, v40, v100
	v_fmac_f32_e32 v61, v38, v102
	v_fmac_f32_e32 v61, v39, v103
	ds_read_b128 v[128:131], v67 offset:63488
	v_add_f32_e32 v61, v72, v61
	s_waitcnt lgkmcnt(6)
	v_mul_f32_e32 v69, v41, v105
	v_fmac_f32_e32 v69, v40, v104
	v_fmac_f32_e32 v69, v38, v106
	v_fmac_f32_e32 v69, v39, v107
	v_add_f32_e32 v68, v73, v69
	ds_read_b128 v[100:103], v67 offset:3072
	s_waitcnt lgkmcnt(6)
	v_mul_f32_e32 v69, v41, v109
	v_fmac_f32_e32 v69, v40, v108
	v_fmac_f32_e32 v69, v38, v110
	v_fmac_f32_e32 v69, v39, v111
	ds_read_b128 v[104:107], v67 offset:7168
	v_add_f32_e32 v69, v74, v69
	s_waitcnt lgkmcnt(6)
	v_mul_f32_e32 v71, v41, v113
	v_fmac_f32_e32 v71, v40, v112
	v_fmac_f32_e32 v71, v38, v114
	v_fmac_f32_e32 v71, v39, v115
	v_add_f32_e32 v70, v75, v71
	ds_read_b128 v[108:111], v67 offset:11264
	s_waitcnt lgkmcnt(6)
	v_mul_f32_e32 v71, v41, v117
	v_fmac_f32_e32 v71, v40, v116
	v_fmac_f32_e32 v71, v38, v118
	v_fmac_f32_e32 v71, v39, v119
	ds_read_b128 v[112:115], v67 offset:15360
	v_add_f32_e32 v71, v76, v71
	s_waitcnt lgkmcnt(6)
	v_mul_f32_e32 v73, v41, v121
	v_fmac_f32_e32 v73, v40, v120
	v_fmac_f32_e32 v73, v38, v122
	v_fmac_f32_e32 v73, v39, v123
	v_add_f32_e32 v72, v77, v73
	ds_read_b128 v[116:119], v67 offset:19456
	s_waitcnt lgkmcnt(6)
	v_mul_f32_e32 v73, v41, v125
	v_fmac_f32_e32 v73, v40, v124
	v_fmac_f32_e32 v73, v38, v126
	v_fmac_f32_e32 v73, v39, v127
	ds_read_b128 v[120:123], v67 offset:23552
	v_add_f32_e32 v73, v78, v73
	s_waitcnt lgkmcnt(6)
	v_mul_f32_e32 v41, v41, v129
	v_fmac_f32_e32 v41, v40, v128
	v_fmac_f32_e32 v41, v38, v130
	v_fmac_f32_e32 v41, v39, v131
	v_add_f32_e32 v38, v79, v41
	v_pk_mul_f32 v[40:41], v[34:35], v[58:59] op_sel_hi:[1,0]
	v_pk_mul_f32 v[34:35], v[36:37], v[58:59] op_sel_hi:[1,0]
	v_pk_mul_f32 v[36:37], v[2:3], v[40:41]
	v_pk_mul_f32 v[34:35], v[4:5], v[34:35]
	v_cvt_pk_bf16_f32 v40, v36, v37
	s_nop 0
	v_cvt_pk_bf16_f32 v41, v34, v35
	ds_read_b128 v[124:127], v67 offset:27648
	global_store_dwordx2 v[46:47], v[40:41], off offset:1536
	s_waitcnt lgkmcnt(6)
	v_mul_f32_e32 v39, v37, v101
	v_fmac_f32_e32 v39, v36, v100
	v_fmac_f32_e32 v39, v34, v102
	v_fmac_f32_e32 v39, v35, v103
	ds_read_b128 v[128:131], v67 offset:31744
	v_add_f32_e32 v39, v42, v39
	s_waitcnt lgkmcnt(6)
	v_mul_f32_e32 v40, v37, v105
	v_fmac_f32_e32 v40, v36, v104
	v_fmac_f32_e32 v40, v34, v106
	v_fmac_f32_e32 v40, v35, v107
	ds_read_b128 v[100:103], v67 offset:35840
	v_add_f32_e32 v40, v43, v40
	s_waitcnt lgkmcnt(6)
	v_mul_f32_e32 v41, v37, v109
	v_fmac_f32_e32 v41, v36, v108
	v_fmac_f32_e32 v41, v34, v110
	v_fmac_f32_e32 v41, v35, v111
	ds_read_b128 v[104:107], v67 offset:39936
	v_add_f32_e32 v41, v44, v41
	s_waitcnt lgkmcnt(6)
	v_mul_f32_e32 v42, v37, v113
	v_fmac_f32_e32 v42, v36, v112
	v_fmac_f32_e32 v42, v34, v114
	v_fmac_f32_e32 v42, v35, v115
	v_add_f32_e32 v42, v45, v42
	ds_read_b128 v[108:111], v67 offset:44032
	s_waitcnt lgkmcnt(6)
	v_mul_f32_e32 v43, v37, v117
	v_fmac_f32_e32 v43, v36, v116
	v_fmac_f32_e32 v43, v34, v118
	v_fmac_f32_e32 v43, v35, v119
	ds_read_b128 v[112:115], v67 offset:48128
	v_add_f32_e32 v43, v48, v43
	s_waitcnt lgkmcnt(6)
	v_mul_f32_e32 v45, v37, v121
	v_fmac_f32_e32 v45, v36, v120
	v_fmac_f32_e32 v45, v34, v122
	v_fmac_f32_e32 v45, v35, v123
	v_add_f32_e32 v48, v49, v45
	ds_read_b128 v[116:119], v67 offset:52224
	s_waitcnt lgkmcnt(6)
	v_mul_f32_e32 v45, v37, v125
	v_fmac_f32_e32 v45, v36, v124
	v_fmac_f32_e32 v45, v34, v126
	v_fmac_f32_e32 v45, v35, v127
	v_add_f32_e32 v49, v51, v45
	ds_read_b128 v[120:123], v67 offset:56320
	s_waitcnt lgkmcnt(6)
	v_mul_f32_e32 v45, v37, v129
	v_fmac_f32_e32 v45, v36, v128
	v_fmac_f32_e32 v45, v34, v130
	v_fmac_f32_e32 v45, v35, v131
	v_add_f32_e32 v51, v60, v45
	ds_read_b128 v[124:127], v67 offset:60416
	s_waitcnt lgkmcnt(6)
; #define LAS __attribute__((address_space(3)))
; __device__ void phase_norm_alow(const Params& P, int l, int half, LAS unsigned char* lds) {
;     ...
;             for (int c = 0; c < 16; ++c) { const f32x4 wv = *(const LAS f32x4*)(WaT + c * 1024 + i * 256 + lane * 4); a[c] += h[0] * wv[0] + h[1] * wv[1] + h[2] * wv[2] + h[3] * wv[3]; } }
;         float b8[8], b4[4], b2[2], b1;
;         { const bool up = (lane & 32) != 0;
; #pragma unroll
;           for (int c = 0; c < 8; ++c) { const float keep = up ? a[c + 8] : a[c], send = up ? a[c] : a[c + 8]; b8[c] = keep + __shfl_xor(send, 32); } }
;         { const bool up = (lane & 16) != 0;
; #pragma unroll
;           for (int c = 0; c < 4; ++c) { const float keep = up ? b8[c + 4] : b8[c], send = up ? b8[c] : b8[c + 4]; b4[c] = keep + __shfl_xor(send, 16); } }
;         { const bool up = (lane & 8) != 0;
; #pragma unroll
;           for (int c = 0; c < 2; ++c) { const float keep = up ? b4[c + 2] : b4[c], send = up ? b4[c] : b4[c + 2]; b2[c] = keep + __shfl_xor(send, 8); } }
;         { const bool up = (lane & 4) != 0; const float keep = up ? b2[1] : b2[0], send = up ? b2[0] : b2[1]; b1 = keep + __shfl_xor(send, 4); }
;         b1 += __shfl_xor(b1, 2); b1 += __shfl_xor(b1, 1);
;         if ((lane & 3) == 0) { const int co = ((lane >> 5) & 1) * 8 + ((lane >> 4) & 1) * 4 + ((lane >> 3) & 1) * 2 + ((lane >> 2) & 1); AL[(size_t)row * 16 + co] = b1; }
	v_mul_f32_e32 v45, v37, v101
	v_fmac_f32_e32 v45, v36, v100
	v_fmac_f32_e32 v45, v34, v102
	v_fmac_f32_e32 v45, v35, v103
	v_add_f32_e32 v58, v61, v45
	ds_read_b128 v[128:131], v67 offset:64512
	s_waitcnt lgkmcnt(6)
	v_mul_f32_e32 v45, v37, v105
	v_fmac_f32_e32 v45, v36, v104
	v_fmac_f32_e32 v45, v34, v106
	v_fmac_f32_e32 v45, v35, v107
	v_add_f32_e32 v60, v68, v45
	s_waitcnt lgkmcnt(5)
	v_mul_f32_e32 v45, v37, v109
	v_fmac_f32_e32 v45, v36, v108
	v_fmac_f32_e32 v45, v34, v110
	v_fmac_f32_e32 v45, v35, v111
	v_add_f32_e32 v61, v69, v45
	s_waitcnt lgkmcnt(4)
	v_mul_f32_e32 v45, v37, v113
	v_fmac_f32_e32 v45, v36, v112
	v_fmac_f32_e32 v45, v34, v114
	v_fmac_f32_e32 v45, v35, v115
	v_add_f32_e32 v68, v70, v45
	s_waitcnt lgkmcnt(3)
	v_mul_f32_e32 v45, v37, v117
	v_fmac_f32_e32 v45, v36, v116
	v_fmac_f32_e32 v45, v34, v118
	v_fmac_f32_e32 v45, v35, v119
	v_add_f32_e32 v69, v71, v45
	s_waitcnt lgkmcnt(2)
	v_mul_f32_e32 v45, v37, v121
	v_fmac_f32_e32 v45, v36, v120
	v_fmac_f32_e32 v45, v34, v122
	v_fmac_f32_e32 v45, v35, v123
	v_add_f32_e32 v70, v72, v45
	s_waitcnt lgkmcnt(1)
	v_mul_f32_e32 v45, v37, v125
	v_fmac_f32_e32 v45, v36, v124
	v_fmac_f32_e32 v45, v34, v126
	v_fmac_f32_e32 v45, v35, v127
	v_add_f32_e32 v71, v73, v45
	s_waitcnt lgkmcnt(0)
	v_mul_f32_e32 v37, v37, v129
	v_fmac_f32_e32 v37, v36, v128
	v_fmac_f32_e32 v37, v34, v130
	v_fmac_f32_e32 v37, v35, v131
	v_cndmask_b32_e32 v36, v39, v58, vcc
	v_add_f32_e32 v34, v38, v37
	ds_bpermute_b32 v36, v59, v36
	v_cndmask_b32_e32 v37, v40, v60, vcc
	ds_bpermute_b32 v37, v59, v37
	v_cndmask_b32_e32 v38, v41, v61, vcc
	ds_bpermute_b32 v38, v59, v38
	v_cndmask_b32_e32 v35, v58, v39, vcc
	v_cndmask_b32_e32 v39, v42, v68, vcc
	s_waitcnt lgkmcnt(2)
	v_add_f32_e32 v35, v35, v36
	v_cndmask_b32_e32 v36, v60, v40, vcc
	ds_bpermute_b32 v39, v59, v39
	v_cndmask_b32_e32 v40, v43, v69, vcc
	s_waitcnt lgkmcnt(2)
	v_add_f32_e32 v36, v36, v37
	v_cndmask_b32_e32 v37, v61, v41, vcc
	ds_bpermute_b32 v40, v59, v40
	v_cndmask_b32_e32 v41, v48, v70, vcc
	s_waitcnt lgkmcnt(2)
	v_add_f32_e32 v37, v37, v38
	v_cndmask_b32_e32 v38, v68, v42, vcc
	ds_bpermute_b32 v41, v59, v41
	v_cndmask_b32_e32 v42, v49, v71, vcc
	ds_bpermute_b32 v42, v59, v42
	s_waitcnt lgkmcnt(3)
	v_add_f32_e32 v38, v38, v39
	v_cndmask_b32_e32 v39, v69, v43, vcc
	s_waitcnt lgkmcnt(2)
	v_add_f32_e32 v39, v39, v40
	v_cndmask_b32_e32 v40, v70, v48, vcc
	s_waitcnt lgkmcnt(1)
	v_add_f32_e32 v40, v40, v41
	v_cndmask_b32_e32 v41, v71, v49, vcc
	s_waitcnt lgkmcnt(0)
	v_add_f32_e32 v41, v41, v42
	v_cndmask_b32_e32 v42, v34, v51, vcc
	v_cndmask_b32_e32 v34, v51, v34, vcc
	ds_bpermute_b32 v34, v59, v34
	s_waitcnt lgkmcnt(0)
	v_add_f32_e32 v34, v42, v34
	v_cndmask_b32_e64 v42, v39, v35, s[36:37]
	v_cndmask_b32_e64 v35, v35, v39, s[36:37]
	v_cndmask_b32_e64 v39, v40, v36, s[36:37]
	v_cndmask_b32_e64 v36, v36, v40, s[36:37]
	ds_bpermute_b32 v36, v62, v36
	ds_bpermute_b32 v35, v62, v35
	s_waitcnt lgkmcnt(1)
	v_add_f32_e32 v36, v39, v36
	v_cndmask_b32_e64 v39, v41, v37, s[36:37]
	v_cndmask_b32_e64 v37, v37, v41, s[36:37]
	ds_bpermute_b32 v37, v62, v37
	s_waitcnt lgkmcnt(1)
	v_add_f32_e32 v35, v42, v35
	s_waitcnt lgkmcnt(0)
	v_add_f32_e32 v37, v39, v37
	v_cndmask_b32_e64 v39, v34, v38, s[36:37]
	v_cndmask_b32_e64 v34, v38, v34, s[36:37]
	ds_bpermute_b32 v34, v62, v34
	v_cndmask_b32_e64 v38, v37, v35, s[38:39]
	v_cndmask_b32_e64 v35, v35, v37, s[38:39]
	ds_bpermute_b32 v35, v63, v35
	s_waitcnt lgkmcnt(1)
	v_add_f32_e32 v34, v39, v34
	v_cndmask_b32_e64 v37, v34, v36, s[38:39]
	v_cndmask_b32_e64 v34, v36, v34, s[38:39]
	ds_bpermute_b32 v34, v63, v34
	s_waitcnt lgkmcnt(1)
	v_add_f32_e32 v35, v38, v35
	s_waitcnt lgkmcnt(0)
	v_add_f32_e32 v34, v37, v34
	v_cndmask_b32_e64 v36, v34, v35, s[40:41]
	v_cndmask_b32_e64 v34, v35, v34, s[40:41]
	ds_bpermute_b32 v34, v64, v34
	s_waitcnt lgkmcnt(0)
	v_add_f32_e32 v34, v36, v34
	s_nop 1
	v_mov_b32_dpp v35, v34 quad_perm:[2,3,0,1] row_mask:0xf bank_mask:0xf
	s_waitcnt lgkmcnt(0)
	v_add_f32_e32 v34, v34, v35
	s_nop 1
	v_mov_b32_dpp v35, v34 quad_perm:[1,0,3,2] row_mask:0xf bank_mask:0xf
	s_and_saveexec_b64 s[0:1], s[42:43]
	s_cbranch_execz .LBB0_117
	v_lshl_add_u64 v[36:37], s[74:75], 0, v[54:55]
	s_waitcnt lgkmcnt(0)
	v_add_f32_e32 v34, v34, v35
	global_store_dword v[36:37], v34, off
	s_branch .LBB0_117

;     __device__ __forceinline__ void exchange(const f32x4 (&v)[2][2][4][2], const Unit& u, int wr, int wc, int fr, int fq, LAS unsigned char* lds, unsigned* xs, unsigned* cnt) const {
;     ...
; #pragma unroll
;         for (int ai = 0; ai < 2; ++ai)
; #pragma unroll
;             for (int m = 0; m < 4; ++m) { float sq = 0.f;
; #pragma unroll
;                 for (int bj = 0; bj < 2; ++bj)
; #pragma unroll
;                     for (int n = 0; n < 2; ++n) { const f32x4 x = v[ai][bj][m][n]; sq += (x[0] * x[0] + x[1] * x[1]) + (x[2] * x[2] + x[3] * x[3]); }
;                 sq += __shfl_xor(sq, 16); sq += __shfl_xor(sq, 32);
;                 if (fq == 0) Pp[(ai * HALF + wr * 64 + m * 16 + fr) * 4 + wc] = sq; }
.LBB0_168:
	v_and_b32_e32 v132, 64, v230
	v_xor_b32_e32 v131, 16, v230
	v_add_u32_e32 v132, 64, v132
	v_cmp_lt_i32_e32 vcc, v131, v132
	v_mul_f32_e32 v133, v129, v129
	v_fmac_f32_e32 v133, v128, v128
	v_cndmask_b32_e32 v131, v230, v131, vcc
	v_lshlrev_b32_e32 v176, 2, v131
	v_mul_f32_e32 v131, v127, v127
	v_fmac_f32_e32 v131, v126, v126
	v_add_f32_e32 v131, v131, v133
	v_mul_f32_e32 v133, v123, v123
	v_mul_f32_e32 v134, v125, v125
	v_fmac_f32_e32 v133, v122, v122
	v_fmac_f32_e32 v134, v124, v124
	v_add_f32_e32 v133, v133, v134
	v_add_f32_e32 v131, v133, v131
	v_mul_f32_e32 v133, v115, v115
	v_mul_f32_e32 v134, v117, v117
	v_fmac_f32_e32 v133, v114, v114
	v_fmac_f32_e32 v134, v116, v116
	v_add_f32_e32 v133, v133, v134
	v_add_f32_e32 v131, v133, v131
	v_mul_f32_e32 v133, v111, v111
	v_mul_f32_e32 v134, v113, v113
	v_fmac_f32_e32 v133, v110, v110
	v_fmac_f32_e32 v134, v112, v112
	v_add_f32_e32 v133, v133, v134
	v_add_f32_e32 v131, v133, v131
	v_mov_b32_e32 v133, v131
	s_nop 1
	v_permlane16_swap_b32_e32 v133, v131
	s_nop 1
	v_xor_b32_e32 v134, 32, v230
	v_cmp_lt_i32_e32 vcc, v134, v132
	s_waitcnt vmcnt(0)
	s_lshl_b32 s7, s6, 2
	s_waitcnt lgkmcnt(0)
	v_add_f32_e32 v131, v131, v133
	v_cndmask_b32_e32 v132, v230, v134, vcc
	v_lshlrev_b32_e32 v177, 2, v132
	ds_bpermute_b32 v132, v177, v131
	v_mov_b32_e32 v130, v0
	v_cmp_eq_u32_e64 s[36:37], 0, v140
	s_add_i32 s7, s7, 0
	s_barrier
	s_and_saveexec_b64 s[30:31], s[36:37]
	s_cbranch_execz .LBB0_170
	s_lshl_b32 s8, s2, 10
	s_add_i32 s8, s7, s8
	v_lshl_add_u32 v133, v174, 4, s8
	s_waitcnt lgkmcnt(0)
	v_add_f32_e32 v131, v131, v132
	ds_write_b32 v133, v131
.LBB0_170:
	s_or_b64 exec, exec, s[30:31]
	v_mul_f32_e32 v131, v119, v119
	s_waitcnt lgkmcnt(0)
	v_mul_f32_e32 v132, v121, v121
	v_fmac_f32_e32 v131, v118, v118
	v_fmac_f32_e32 v132, v120, v120
	v_add_f32_e32 v131, v131, v132
	v_mul_f32_e32 v132, v107, v107
	v_mul_f32_e32 v133, v109, v109
	v_fmac_f32_e32 v132, v106, v106
	v_fmac_f32_e32 v133, v108, v108
	v_add_f32_e32 v132, v132, v133
	v_add_f32_e32 v131, v132, v131
	v_mul_f32_e32 v132, v103, v103
	v_mul_f32_e32 v133, v105, v105
	v_fmac_f32_e32 v132, v102, v102
	v_fmac_f32_e32 v133, v104, v104
	v_add_f32_e32 v132, v132, v133
	v_add_f32_e32 v131, v132, v131
	v_mul_f32_e32 v132, v95, v95
	v_mul_f32_e32 v133, v97, v97
	v_fmac_f32_e32 v132, v94, v94
	v_fmac_f32_e32 v133, v96, v96
	v_add_f32_e32 v132, v132, v133
	v_add_f32_e32 v131, v132, v131
	v_mov_b32_e32 v132, v131
	s_nop 1
	v_permlane16_swap_b32_e32 v132, v131
	s_nop 1
	s_waitcnt lgkmcnt(0)
	v_add_f32_e32 v131, v131, v132
	v_mov_b32_e32 v132, v131
	s_nop 1
	v_permlane32_swap_b32_e32 v132, v131
	s_nop 1
	s_and_saveexec_b64 s[30:31], s[36:37]
	s_cbranch_execz .LBB0_172
	s_lshl_b32 s8, s2, 10
	s_add_i32 s8, s7, s8
	v_lshl_add_u32 v133, v174, 4, s8
	s_waitcnt lgkmcnt(0)
	v_add_f32_e32 v131, v131, v132
	ds_write_b32 v133, v131 offset:256
.LBB0_172:
	s_or_b64 exec, exec, s[30:31]
	v_mul_f32_e32 v131, v99, v99
	s_waitcnt lgkmcnt(0)
	v_mul_f32_e32 v132, v101, v101
	v_fmac_f32_e32 v131, v98, v98
	v_fmac_f32_e32 v132, v100, v100
	v_add_f32_e32 v131, v131, v132
	v_mul_f32_e32 v132, v91, v91
	v_mul_f32_e32 v133, v93, v93
	v_fmac_f32_e32 v132, v90, v90
	v_fmac_f32_e32 v133, v92, v92
	v_add_f32_e32 v132, v132, v133
	v_add_f32_e32 v131, v132, v131
	v_mul_f32_e32 v132, v87, v87
	v_mul_f32_e32 v133, v89, v89
	v_fmac_f32_e32 v132, v86, v86
	v_fmac_f32_e32 v133, v88, v88
	v_add_f32_e32 v132, v132, v133
	v_add_f32_e32 v131, v132, v131
	v_mul_f32_e32 v132, v79, v79
	v_mul_f32_e32 v133, v81, v81
	v_fmac_f32_e32 v132, v78, v78
	v_fmac_f32_e32 v133, v80, v80
	v_add_f32_e32 v132, v132, v133
	v_add_f32_e32 v131, v132, v131
	v_mov_b32_e32 v132, v131
	s_nop 1
	v_permlane16_swap_b32_e32 v132, v131
	s_nop 1
	s_waitcnt lgkmcnt(0)
	v_add_f32_e32 v131, v131, v132
	v_mov_b32_e32 v132, v131
	s_nop 1
	v_permlane32_swap_b32_e32 v132, v131
	s_nop 1
	s_and_saveexec_b64 s[30:31], s[36:37]
	s_cbranch_execz .LBB0_174
	s_lshl_b32 s8, s2, 10
	s_add_i32 s8, s7, s8
	v_lshl_add_u32 v133, v174, 4, s8
	s_waitcnt lgkmcnt(0)
	v_add_f32_e32 v131, v131, v132
	ds_write_b32 v133, v131 offset:512
.LBB0_174:
	s_or_b64 exec, exec, s[30:31]
	v_mul_f32_e32 v131, v83, v83
	s_waitcnt lgkmcnt(0)
	v_mul_f32_e32 v132, v85, v85
	v_fmac_f32_e32 v131, v82, v82
	v_fmac_f32_e32 v132, v84, v84
	v_add_f32_e32 v131, v131, v132
	v_mul_f32_e32 v132, v75, v75
	v_mul_f32_e32 v133, v77, v77
	v_fmac_f32_e32 v132, v74, v74
	v_fmac_f32_e32 v133, v76, v76
	v_add_f32_e32 v132, v132, v133
	v_add_f32_e32 v131, v132, v131
	v_mul_f32_e32 v132, v71, v71
	v_mul_f32_e32 v133, v73, v73
	v_fmac_f32_e32 v132, v70, v70
	v_fmac_f32_e32 v133, v72, v72
	v_add_f32_e32 v132, v132, v133
	v_add_f32_e32 v131, v132, v131
	v_mul_f32_e32 v132, v67, v67
	v_mul_f32_e32 v133, v69, v69
	v_fmac_f32_e32 v132, v66, v66
	v_fmac_f32_e32 v133, v68, v68
	v_add_f32_e32 v132, v132, v133
	v_add_f32_e32 v131, v132, v131
	v_mov_b32_e32 v132, v131
	s_nop 1
	v_permlane16_swap_b32_e32 v132, v131
	s_nop 1
	s_waitcnt lgkmcnt(0)
	v_add_f32_e32 v131, v131, v132
	v_mov_b32_e32 v132, v131
	s_nop 1
	v_permlane32_swap_b32_e32 v132, v131
	s_nop 1
	s_and_saveexec_b64 s[30:31], s[36:37]
	s_cbranch_execz .LBB0_176
	s_lshl_b32 s8, s2, 10
	s_add_i32 s8, s7, s8
	v_lshl_add_u32 v133, v174, 4, s8
	s_waitcnt lgkmcnt(0)
	v_add_f32_e32 v131, v131, v132
	ds_write_b32 v133, v131 offset:768
;     __device__ __forceinline__ void exchange(const f32x4 (&v)[2][2][4][2], const Unit& u, int wr, int wc, int fr, int fq, LAS unsigned char* lds, unsigned* xs, unsigned* cnt) const {
;     ...
; #pragma unroll
;         for (int ai = 0; ai < 2; ++ai)
; #pragma unroll
;             for (int m = 0; m < 4; ++m) { float sq = 0.f;
; #pragma unroll
;                 for (int bj = 0; bj < 2; ++bj)
; #pragma unroll
;                     for (int n = 0; n < 2; ++n) { const f32x4 x = v[ai][bj][m][n]; sq += (x[0] * x[0] + x[1] * x[1]) + (x[2] * x[2] + x[3] * x[3]); }
;                 sq += __shfl_xor(sq, 16); sq += __shfl_xor(sq, 32);
;                 if (fq == 0) Pp[(ai * HALF + wr * 64 + m * 16 + fr) * 4 + wc] = sq; }
.LBB0_176:
	s_or_b64 exec, exec, s[30:31]
	v_mul_f32_e32 v131, v63, v63
	s_waitcnt lgkmcnt(0)
	v_mul_f32_e32 v132, v65, v65
	v_fmac_f32_e32 v131, v62, v62
	v_fmac_f32_e32 v132, v64, v64
	v_add_f32_e32 v131, v131, v132
	v_mul_f32_e32 v132, v59, v59
	v_mul_f32_e32 v133, v61, v61
	v_fmac_f32_e32 v132, v58, v58
	v_fmac_f32_e32 v133, v60, v60
	v_add_f32_e32 v132, v132, v133
	v_add_f32_e32 v131, v132, v131
	v_mul_f32_e32 v132, v55, v55
	v_mul_f32_e32 v133, v57, v57
	v_fmac_f32_e32 v132, v54, v54
	v_fmac_f32_e32 v133, v56, v56
	v_add_f32_e32 v132, v132, v133
	v_add_f32_e32 v131, v132, v131
	v_mul_f32_e32 v132, v47, v47
	v_mul_f32_e32 v133, v49, v49
	v_fmac_f32_e32 v132, v46, v46
	v_fmac_f32_e32 v133, v48, v48
	v_add_f32_e32 v132, v132, v133
	v_add_f32_e32 v131, v132, v131
	v_mov_b32_e32 v132, v131
	s_nop 1
	v_permlane16_swap_b32_e32 v132, v131
	s_nop 1
	s_waitcnt lgkmcnt(0)
	v_add_f32_e32 v131, v131, v132
	v_mov_b32_e32 v132, v131
	s_nop 1
	v_permlane32_swap_b32_e32 v132, v131
	s_nop 1
	s_and_saveexec_b64 s[30:31], s[36:37]
	s_cbranch_execz .LBB0_178
	s_lshl_b32 s8, s2, 10
	s_add_i32 s8, s7, s8
	v_lshl_add_u32 v133, v174, 4, s8
	s_waitcnt lgkmcnt(0)
	v_add_f32_e32 v131, v131, v132
	ds_write_b32 v133, v131 offset:2048
.LBB0_178:
	s_or_b64 exec, exec, s[30:31]
	v_mul_f32_e32 v131, v51, v51
	s_waitcnt lgkmcnt(0)
	v_mul_f32_e32 v132, v53, v53
	v_fmac_f32_e32 v131, v50, v50
	v_fmac_f32_e32 v132, v52, v52
	v_add_f32_e32 v131, v131, v132
	v_mul_f32_e32 v132, v43, v43
	v_mul_f32_e32 v133, v45, v45
	v_fmac_f32_e32 v132, v42, v42
	v_fmac_f32_e32 v133, v44, v44
	v_add_f32_e32 v132, v132, v133
	v_add_f32_e32 v131, v132, v131
	v_mul_f32_e32 v132, v39, v39
	v_mul_f32_e32 v133, v41, v41
	v_fmac_f32_e32 v132, v38, v38
	v_fmac_f32_e32 v133, v40, v40
	v_add_f32_e32 v132, v132, v133
	v_add_f32_e32 v131, v132, v131
	v_mul_f32_e32 v132, v31, v31
	v_mul_f32_e32 v133, v33, v33
	v_fmac_f32_e32 v132, v30, v30
	v_fmac_f32_e32 v133, v32, v32
	v_add_f32_e32 v132, v132, v133
	v_add_f32_e32 v131, v132, v131
	v_mov_b32_e32 v132, v131
	s_nop 1
	v_permlane16_swap_b32_e32 v132, v131
	s_nop 1
	s_waitcnt lgkmcnt(0)
	v_add_f32_e32 v131, v131, v132
	v_mov_b32_e32 v132, v131
	s_nop 1
	v_permlane32_swap_b32_e32 v132, v131
	s_nop 1
	s_and_saveexec_b64 s[30:31], s[36:37]
	s_cbranch_execz .LBB0_180
	s_lshl_b32 s8, s2, 10
	s_add_i32 s8, s7, s8
	v_lshl_add_u32 v133, v174, 4, s8
	s_waitcnt lgkmcnt(0)
	v_add_f32_e32 v131, v131, v132
	ds_write_b32 v133, v131 offset:2304
.LBB0_180:
	s_or_b64 exec, exec, s[30:31]
	v_mul_f32_e32 v131, v35, v35
	s_waitcnt lgkmcnt(0)
	v_mul_f32_e32 v132, v37, v37
	v_fmac_f32_e32 v131, v34, v34
	v_fmac_f32_e32 v132, v36, v36
	v_add_f32_e32 v131, v131, v132
	v_mul_f32_e32 v132, v27, v27
	v_mul_f32_e32 v133, v29, v29
	v_fmac_f32_e32 v132, v26, v26
	v_fmac_f32_e32 v133, v28, v28
	v_add_f32_e32 v132, v132, v133
	v_add_f32_e32 v131, v132, v131
	v_mul_f32_e32 v132, v23, v23
	v_mul_f32_e32 v133, v25, v25
	v_fmac_f32_e32 v132, v22, v22
	v_fmac_f32_e32 v133, v24, v24
	v_add_f32_e32 v132, v132, v133
	v_add_f32_e32 v131, v132, v131
	v_mul_f32_e32 v132, v15, v15
	v_mul_f32_e32 v133, v17, v17
	v_fmac_f32_e32 v132, v14, v14
	v_fmac_f32_e32 v133, v16, v16
	v_add_f32_e32 v132, v132, v133
	v_add_f32_e32 v131, v132, v131
	v_mov_b32_e32 v132, v131
	s_nop 1
	v_permlane16_swap_b32_e32 v132, v131
	s_nop 1
	s_waitcnt lgkmcnt(0)
	v_add_f32_e32 v131, v131, v132
	v_mov_b32_e32 v132, v131
	s_nop 1
	v_permlane32_swap_b32_e32 v132, v131
	s_nop 1
	s_and_saveexec_b64 s[30:31], s[36:37]
	s_cbranch_execz .LBB0_182
	s_lshl_b32 s8, s2, 10
	s_add_i32 s8, s7, s8
	v_lshl_add_u32 v133, v174, 4, s8
	s_waitcnt lgkmcnt(0)
	v_add_f32_e32 v131, v131, v132
	ds_write_b32 v133, v131 offset:2560
.LBB0_182:
	s_or_b64 exec, exec, s[30:31]
	v_mul_f32_e32 v131, v19, v19
	s_waitcnt lgkmcnt(0)
	v_mul_f32_e32 v132, v21, v21
	v_fmac_f32_e32 v131, v18, v18
	v_fmac_f32_e32 v132, v20, v20
	v_add_f32_e32 v131, v131, v132
	v_mul_f32_e32 v132, v11, v11
	v_mul_f32_e32 v133, v13, v13
	v_fmac_f32_e32 v132, v10, v10
	v_fmac_f32_e32 v133, v12, v12
	v_add_f32_e32 v132, v132, v133
	v_add_f32_e32 v131, v132, v131
	v_mul_f32_e32 v132, v7, v7
	v_mul_f32_e32 v133, v9, v9
	v_fmac_f32_e32 v132, v6, v6
	v_fmac_f32_e32 v133, v8, v8
	v_add_f32_e32 v132, v132, v133
	v_add_f32_e32 v131, v132, v131
	v_mul_f32_e32 v132, v3, v3
	v_mul_f32_e32 v133, v5, v5
	v_fmac_f32_e32 v132, v2, v2
	v_fmac_f32_e32 v133, v4, v4
	v_add_f32_e32 v132, v132, v133
	v_add_f32_e32 v131, v132, v131
	v_mov_b32_e32 v132, v131
	s_nop 1
	v_permlane16_swap_b32_e32 v132, v131
	s_nop 1
	s_waitcnt lgkmcnt(0)
	v_add_f32_e32 v131, v131, v132
	v_mov_b32_e32 v132, v131
	s_nop 1
	v_permlane32_swap_b32_e32 v132, v131
	s_nop 1
	s_and_saveexec_b64 s[30:31], s[36:37]
	s_cbranch_execz .LBB0_184
	s_lshl_b32 s8, s2, 10
	s_add_i32 s8, s7, s8
	v_lshl_add_u32 v133, v174, 4, s8
	s_waitcnt lgkmcnt(0)
	v_add_f32_e32 v131, v131, v132
	ds_write_b32 v133, v131 offset:2816

; #define LAS __attribute__((address_space(3)))
;     __device__ __forceinline__ void fused(f32x4 (&acc)[2][2][4][2], const Unit& u, int wr, int wc, int fr, int fq, LAS unsigned char* lds) const {
;         const LAS float* S = (const LAS float*)(lds + 4096);
;         const int col0 = u.pn * BM + wc * 32 + 4 * fq;
;         exchange(acc, u, wr, wc, fr, fq, lds, xs1, cnt1);
;         {
;             f32x4 gv[2][2];
; #pragma unroll
;             for (int bj = 0; bj < 2; ++bj)
; #pragma unroll
;                 for (int n = 0; n < 2; ++n) gv[bj][n] = *(const f32x4*)(g1 + col0 + bj * HALF + n * 16);
; #pragma unroll
;             for (int ai = 0; ai < 2; ++ai) {
;                 f32x4 xv[4][2][2];
; #pragma unroll
;                 for (int m = 0; m < 4; ++m)
; #pragma unroll
;                     for (int bj = 0; bj < 2; ++bj)
; #pragma unroll
;                         for (int n = 0; n < 2; ++n) xv[m][bj][n] = *(const f32x4*)(xin + (size_t)(u.pm * BM + ai * HALF + wr * 64 + m * 16 + fr) * DM + col0 + bj * HALF + n * 16);
; #pragma unroll
;                 for (int m = 0; m < 4; ++m) { const int r = ai * HALF + wr * 64 + m * 16 + fr; const float r1 = S[r];
; #pragma unroll
;                     for (int bj = 0; bj < 2; ++bj)
; #pragma unroll
;                         for (int n = 0; n < 2; ++n) { acc[ai][bj][m][n] = xv[m][bj][n] + acc[ai][bj][m][n] * r1 * gv[bj][n];
;                             *(f32x4*)(xout + (size_t)(u.pm * BM + r) * DM + col0 + bj * HALF + n * 16) = acc[ai][bj][m][n]; } }
.LBB0_200:
	s_or_b64 exec, exec, s[44:45]
	s_lshl_b32 s6, s6, 5
	s_lshl_b32 s9, s40, 8
	v_readlane_b32 s10, v255, 32
	s_or_b32 s6, s9, s6
	v_readlane_b32 s11, v255, 33
	s_and_b64 s[10:11], s[10:11], exec
	v_lshl_or_b32 v154, v140, 2, s6
	s_cselect_b32 s6, 0x1000000, 0
	s_lshl_b32 s9, s6, 2
	s_add_u32 s10, s0, s9
	s_addc_u32 s11, s1, 0
	v_readlane_b32 s12, v255, 29
	s_add_u32 s38, s72, s9
	v_readlane_b32 s13, v255, 30
	v_readlane_b32 s44, v252, 25
	s_addc_u32 s39, s73, 0
	s_lshl_b64 s[12:13], s[12:13], 12
	v_readlane_b32 s52, v252, 33
	v_readlane_b32 s53, v252, 34
	s_add_u32 s12, s52, s12
	s_addc_u32 s13, s53, s13
	s_add_i32 s5, s8, s5
	v_ashrrev_i32_e32 v155, 31, v154
	v_or_b32_e32 v152, s5, v174
	v_lshlrev_b64 v[172:173], 2, v[154:155]
	v_ashrrev_i32_e32 v153, 31, v152
	v_lshl_add_u64 v[150:151], s[10:11], 0, v[172:173]
	v_lshlrev_b64 v[130:131], 12, v[152:153]
	v_lshl_add_u64 v[134:135], s[12:13], 0, v[172:173]
	v_lshl_add_u64 v[158:159], v[150:151], 0, v[130:131]
	s_waitcnt lgkmcnt(0)
	s_waitcnt lgkmcnt(0)
	s_barrier
	global_load_dwordx4 v[130:133], v[158:159], off
	global_load_dwordx4 v[146:149], v[134:135], off
	global_load_dwordx4 v[142:145], v[134:135], off offset:64
	global_load_dwordx4 v[160:163], v[158:159], off offset:64
	global_load_dwordx4 v[166:169], v[158:159], off offset:512
	global_load_dwordx4 v[138:141], v[134:135], off offset:512
	s_nop 0
	global_load_dwordx4 v[134:137], v[134:135], off offset:576
	s_nop 0
	global_load_dwordx4 v[178:181], v[158:159], off offset:576
	v_or_b32_e32 v158, 16, v152
	v_ashrrev_i32_e32 v159, 31, v158
	v_lshlrev_b64 v[158:159], 12, v[158:159]
	v_lshl_add_u64 v[158:159], v[150:151], 0, v[158:159]
	global_load_dwordx4 v[182:185], v[158:159], off
	global_load_dwordx4 v[186:189], v[158:159], off offset:64
	global_load_dwordx4 v[190:193], v[158:159], off offset:512
	global_load_dwordx4 v[204:207], v[158:159], off offset:576
	v_or_b32_e32 v158, 32, v152
	v_ashrrev_i32_e32 v159, 31, v158
	v_lshlrev_b64 v[158:159], 12, v[158:159]
	v_lshl_add_u32 v175, v156, 2, 0
	v_lshl_add_u64 v[170:171], v[150:151], 0, v[158:159]
	v_add_u32_e32 v194, 0x1000, v175
	global_load_dwordx4 v[208:211], v[170:171], off
	global_load_dwordx4 v[212:215], v[170:171], off offset:64
	v_add_u32_e32 v164, s8, v156
	ds_read2_b32 v[156:157], v194 offset1:16
	global_load_dwordx4 v[216:219], v[170:171], off offset:512
	global_load_dwordx4 v[220:223], v[170:171], off offset:576
	v_or_b32_e32 v224, 48, v152
	v_add_u32_e32 v158, 16, v164
	v_ashrrev_i32_e32 v225, 31, v224
	v_ashrrev_i32_e32 v159, 31, v158
	v_lshlrev_b64 v[224:225], 12, v[224:225]
	v_lshlrev_b64 v[246:247], 12, v[158:159]
	s_waitcnt lgkmcnt(0)
	v_pk_mul_f32 v[126:127], v[126:127], v[156:157] op_sel_hi:[1,0]
	v_lshl_add_u64 v[248:249], v[150:151], 0, v[224:225]
	v_pk_mul_f32 v[128:129], v[128:129], v[156:157] op_sel_hi:[1,0]
	v_pk_mul_f32 v[122:123], v[122:123], v[156:157] op_sel_hi:[1,0]
	v_pk_mul_f32 v[124:125], v[124:125], v[156:157] op_sel_hi:[1,0]
	v_pk_mul_f32 v[114:115], v[114:115], v[156:157] op_sel_hi:[1,0]
	v_pk_mul_f32 v[116:117], v[116:117], v[156:157] op_sel_hi:[1,0]
	v_pk_mul_f32 v[110:111], v[110:111], v[156:157] op_sel_hi:[1,0]
	v_pk_mul_f32 v[112:113], v[112:113], v[156:157] op_sel_hi:[1,0]
	v_mov_b32_e32 v156, v157
	global_load_dwordx4 v[224:227], v[248:249], off
	global_load_dwordx4 v[238:241], v[248:249], off offset:64
	v_pk_mul_f32 v[228:229], v[120:121], v[156:157] op_sel_hi:[1,0]
	global_load_dwordx4 v[242:245], v[248:249], off offset:512
	v_lshl_add_u64 v[120:121], s[38:39], 0, v[246:247]
	global_load_dwordx4 v[246:249], v[248:249], off offset:576
	v_ashrrev_i32_e32 v165, 31, v164
	v_lshlrev_b64 v[170:171], 12, v[164:165]
	v_pk_mul_f32 v[236:237], v[118:119], v[156:157] op_sel_hi:[1,0]
	v_lshl_add_u64 v[118:119], s[38:39], 0, v[170:171]
	v_lshl_add_u64 v[170:171], v[118:119], 0, v[172:173]
	v_lshl_add_u64 v[200:201], v[120:121], 0, v[172:173]
	v_pk_mul_f32 v[106:107], v[106:107], v[156:157] op_sel_hi:[1,0]
	v_pk_mul_f32 v[108:109], v[108:109], v[156:157] op_sel_hi:[1,0]
	v_pk_mul_f32 v[102:103], v[102:103], v[156:157] op_sel_hi:[1,0]
	v_pk_mul_f32 v[104:105], v[104:105], v[156:157] op_sel_hi:[1,0]
	v_pk_mul_f32 v[94:95], v[94:95], v[156:157] op_sel_hi:[1,0]
	v_pk_mul_f32 v[96:97], v[96:97], v[156:157] op_sel_hi:[1,0]
	v_readlane_b32 s45, v252, 26
	v_readlane_b32 s46, v252, 27
	v_readlane_b32 s47, v252, 28
	v_readlane_b32 s48, v252, 29
	v_readlane_b32 s49, v252, 30
	v_readlane_b32 s50, v252, 31
	v_readlane_b32 s51, v252, 32
	v_readlane_b32 s54, v252, 35
	v_readlane_b32 s55, v252, 36
	v_readlane_b32 s56, v252, 37
	v_readlane_b32 s57, v252, 38
	v_readlane_b32 s58, v252, 39
	v_readlane_b32 s59, v252, 40
	s_waitcnt vmcnt(18)
	v_pk_fma_f32 v[132:133], v[148:149], v[128:129], v[132:133]
	v_pk_fma_f32 v[130:131], v[146:147], v[126:127], v[130:131]
	s_waitcnt vmcnt(16)
	v_pk_fma_f32 v[128:129], v[144:145], v[124:125], v[162:163]
	v_pk_fma_f32 v[126:127], v[142:143], v[122:123], v[160:161]
	s_waitcnt vmcnt(14)
	v_pk_fma_f32 v[124:125], v[140:141], v[116:117], v[168:169]
	v_pk_fma_f32 v[122:123], v[138:139], v[114:115], v[166:167]
	s_waitcnt vmcnt(12)
	v_pk_fma_f32 v[120:121], v[136:137], v[112:113], v[180:181]
	v_pk_fma_f32 v[118:119], v[134:135], v[110:111], v[178:179]
	global_store_dwordx4 v[170:171], v[130:133], off
	global_store_dwordx4 v[170:171], v[126:129], off offset:64
	global_store_dwordx4 v[170:171], v[122:125], off offset:512
	global_store_dwordx4 v[170:171], v[118:121], off offset:576
	ds_read2_b32 v[162:163], v194 offset0:32 offset1:48
	v_add_u32_e32 v160, 32, v164
	v_ashrrev_i32_e32 v161, 31, v160
	v_lshlrev_b64 v[156:157], 12, v[160:161]
	s_waitcnt vmcnt(14)
;     __device__ __forceinline__ void fused(f32x4 (&acc)[2][2][4][2], const Unit& u, int wr, int wc, int fr, int fq, LAS unsigned char* lds) const {
;     ...
;             for (int ai = 0; ai < 2; ++ai) {
;                 f32x4 xv[4][2][2];
; #pragma unroll
;                 for (int m = 0; m < 4; ++m)
; #pragma unroll
;                     for (int bj = 0; bj < 2; ++bj)
; #pragma unroll
;                         for (int n = 0; n < 2; ++n) xv[m][bj][n] = *(const f32x4*)(xin + (size_t)(u.pm * BM + ai * HALF + wr * 64 + m * 16 + fr) * DM + col0 + bj * HALF + n * 16);
; #pragma unroll
;                 for (int m = 0; m < 4; ++m) { const int r = ai * HALF + wr * 64 + m * 16 + fr; const float r1 = S[r];
; #pragma unroll
;                     for (int bj = 0; bj < 2; ++bj)
; #pragma unroll
;                         for (int n = 0; n < 2; ++n) { acc[ai][bj][m][n] = xv[m][bj][n] + acc[ai][bj][m][n] * r1 * gv[bj][n];
;                             *(f32x4*)(xout + (size_t)(u.pm * BM + r) * DM + col0 + bj * HALF + n * 16) = acc[ai][bj][m][n]; } }
	v_pk_fma_f32 v[116:117], v[144:145], v[108:109], v[188:189]
	v_pk_fma_f32 v[114:115], v[142:143], v[106:107], v[186:187]
	s_waitcnt vmcnt(13)
	v_pk_fma_f32 v[108:109], v[140:141], v[104:105], v[192:193]
	v_pk_fma_f32 v[106:107], v[138:139], v[102:103], v[190:191]
	s_waitcnt vmcnt(12)
	v_pk_fma_f32 v[104:105], v[136:137], v[96:97], v[206:207]
	v_pk_fma_f32 v[102:103], v[134:135], v[94:95], v[204:205]
	s_waitcnt lgkmcnt(0)
	v_pk_mul_f32 v[94:95], v[98:99], v[162:163] op_sel_hi:[1,0]
	v_pk_mul_f32 v[96:97], v[100:101], v[162:163] op_sel_hi:[1,0]
	v_lshl_add_u64 v[98:99], s[38:39], 0, v[156:157]
	v_pk_mul_f32 v[90:91], v[90:91], v[162:163] op_sel_hi:[1,0]
	v_pk_mul_f32 v[92:93], v[92:93], v[162:163] op_sel_hi:[1,0]
	v_pk_mul_f32 v[86:87], v[86:87], v[162:163] op_sel_hi:[1,0]
	v_pk_mul_f32 v[88:89], v[88:89], v[162:163] op_sel_hi:[1,0]
	v_pk_mul_f32 v[78:79], v[78:79], v[162:163] op_sel_hi:[1,0]
	v_pk_mul_f32 v[80:81], v[80:81], v[162:163] op_sel_hi:[1,0]
	s_waitcnt vmcnt(11)
	v_pk_fma_f32 v[96:97], v[148:149], v[96:97], v[210:211]
	v_pk_fma_f32 v[94:95], v[146:147], v[94:95], v[208:209]
	v_lshl_add_u64 v[156:157], v[98:99], 0, v[172:173]
	s_waitcnt vmcnt(10)
	v_pk_fma_f32 v[100:101], v[144:145], v[92:93], v[214:215]
	v_pk_fma_f32 v[98:99], v[142:143], v[90:91], v[212:213]
	s_waitcnt vmcnt(9)
	v_pk_fma_f32 v[92:93], v[140:141], v[88:89], v[218:219]
	v_pk_fma_f32 v[90:91], v[138:139], v[86:87], v[216:217]
	s_waitcnt vmcnt(8)
	v_pk_fma_f32 v[88:89], v[136:137], v[80:81], v[222:223]
	v_pk_fma_f32 v[86:87], v[134:135], v[78:79], v[220:221]
	global_store_dwordx4 v[156:157], v[94:97], off
	global_store_dwordx4 v[156:157], v[98:101], off offset:64
	global_store_dwordx4 v[156:157], v[90:93], off offset:512
	global_store_dwordx4 v[156:157], v[86:89], off offset:576
	v_add_u32_e32 v156, 48, v164
	v_ashrrev_i32_e32 v157, 31, v156
	v_lshlrev_b64 v[166:167], 12, v[156:157]
	v_mov_b32_e32 v162, v163
	v_pk_mul_f32 v[78:79], v[82:83], v[162:163] op_sel_hi:[1,0]
	v_pk_mul_f32 v[80:81], v[84:85], v[162:163] op_sel_hi:[1,0]
	v_lshl_add_u64 v[82:83], s[38:39], 0, v[166:167]
	v_pk_mul_f32 v[74:75], v[74:75], v[162:163] op_sel_hi:[1,0]
	v_pk_mul_f32 v[76:77], v[76:77], v[162:163] op_sel_hi:[1,0]
	v_pk_mul_f32 v[70:71], v[70:71], v[162:163] op_sel_hi:[1,0]
	v_pk_mul_f32 v[72:73], v[72:73], v[162:163] op_sel_hi:[1,0]
	v_pk_mul_f32 v[66:67], v[66:67], v[162:163] op_sel_hi:[1,0]
	v_pk_mul_f32 v[68:69], v[68:69], v[162:163] op_sel_hi:[1,0]
	s_waitcnt vmcnt(11)
	v_pk_fma_f32 v[80:81], v[148:149], v[80:81], v[226:227]
	v_pk_fma_f32 v[78:79], v[146:147], v[78:79], v[224:225]
	v_lshl_add_u64 v[82:83], v[82:83], 0, v[172:173]
	s_waitcnt vmcnt(10)
	v_pk_fma_f32 v[76:77], v[144:145], v[76:77], v[240:241]
	v_pk_fma_f32 v[74:75], v[142:143], v[74:75], v[238:239]
	s_waitcnt vmcnt(9)
	v_pk_fma_f32 v[72:73], v[140:141], v[72:73], v[244:245]
	v_pk_fma_f32 v[70:71], v[138:139], v[70:71], v[242:243]
	s_waitcnt vmcnt(8)
	v_pk_fma_f32 v[68:69], v[136:137], v[68:69], v[248:249]
	v_pk_fma_f32 v[66:67], v[134:135], v[66:67], v[246:247]
	global_store_dwordx4 v[82:83], v[78:81], off
	global_store_dwordx4 v[82:83], v[74:77], off offset:64
	global_store_dwordx4 v[82:83], v[70:73], off offset:512
	global_store_dwordx4 v[82:83], v[66:69], off offset:576
	v_add_u32_e32 v82, 0x80, v152
	v_ashrrev_i32_e32 v83, 31, v82
	v_pk_fma_f32 v[112:113], v[148:149], v[228:229], v[184:185]
	v_pk_fma_f32 v[110:111], v[146:147], v[236:237], v[182:183]
	v_lshlrev_b64 v[82:83], 12, v[82:83]
	global_store_dwordx4 v[200:201], v[110:113], off
	global_store_dwordx4 v[200:201], v[114:117], off offset:64
	global_store_dwordx4 v[200:201], v[106:109], off offset:512
	global_store_dwordx4 v[200:201], v[102:105], off offset:576
	v_lshl_add_u64 v[162:163], v[150:151], 0, v[82:83]
	global_load_dwordx4 v[82:85], v[162:163], off
	global_load_dwordx4 v[166:169], v[162:163], off offset:64
	global_load_dwordx4 v[178:181], v[162:163], off offset:512
	global_load_dwordx4 v[182:185], v[162:163], off offset:576
	v_add_u32_e32 v162, 0x90, v152
	v_ashrrev_i32_e32 v163, 31, v162
	v_lshlrev_b64 v[162:163], 12, v[162:163]
	v_lshl_add_u64 v[162:163], v[150:151], 0, v[162:163]
	global_load_dwordx4 v[186:189], v[162:163], off
	global_load_dwordx4 v[190:193], v[162:163], off offset:64
	global_load_dwordx4 v[204:207], v[162:163], off offset:512
	global_load_dwordx4 v[208:211], v[162:163], off offset:576
	v_add_u32_e32 v162, 0xa0, v152
	v_ashrrev_i32_e32 v163, 31, v162
	v_lshlrev_b64 v[162:163], 12, v[162:163]
	v_add_u32_e32 v152, 0xb0, v152
	v_lshl_add_u64 v[162:163], v[150:151], 0, v[162:163]
	v_ashrrev_i32_e32 v153, 31, v152
	global_load_dwordx4 v[212:215], v[162:163], off
	global_load_dwordx4 v[216:219], v[162:163], off offset:64
	global_load_dwordx4 v[220:223], v[162:163], off offset:512
	global_load_dwordx4 v[224:227], v[162:163], off offset:576
	v_lshlrev_b64 v[152:153], 12, v[152:153]
	v_lshl_add_u64 v[150:151], v[150:151], 0, v[152:153]
	global_load_dwordx4 v[238:241], v[150:151], off
	global_load_dwordx4 v[242:245], v[150:151], off offset:64
	ds_read2_b32 v[162:163], v194 offset0:128 offset1:144
	global_load_dwordx4 v[246:249], v[150:151], off offset:512
	s_nop 0
	global_load_dwordx4 v[150:153], v[150:151], off offset:576
	v_add_u32_e32 v170, 0x80, v164
	v_ashrrev_i32_e32 v171, 31, v170
	v_lshlrev_b64 v[200:201], 12, v[170:171]
	s_waitcnt lgkmcnt(0)
;     __device__ __forceinline__ void exchange(const f32x4 (&v)[2][2][4][2], const Unit& u, int wr, int wc, int fr, int fq, LAS unsigned char* lds, unsigned* xs, unsigned* cnt) const {
;     ...
;             for (int m = 0; m < 4; ++m) { float sq = 0.f;
; #pragma unroll
;                 for (int bj = 0; bj < 2; ++bj)
; #pragma unroll
;                     for (int n = 0; n < 2; ++n) { const f32x4 x = v[ai][bj][m][n]; sq += (x[0] * x[0] + x[1] * x[1]) + (x[2] * x[2] + x[3] * x[3]); }
;                 sq += __shfl_xor(sq, 16); sq += __shfl_xor(sq, 32);
;     __device__ __forceinline__ void fused(f32x4 (&acc)[2][2][4][2], const Unit& u, int wr, int wc, int fr, int fq, LAS unsigned char* lds) const {
;     ...
;             for (int ai = 0; ai < 2; ++ai) {
;                 f32x4 xv[4][2][2];
; #pragma unroll
;                 for (int m = 0; m < 4; ++m)
; #pragma unroll
;                     for (int bj = 0; bj < 2; ++bj)
; #pragma unroll
;                         for (int n = 0; n < 2; ++n) xv[m][bj][n] = *(const f32x4*)(xin + (size_t)(u.pm * BM + ai * HALF + wr * 64 + m * 16 + fr) * DM + col0 + bj * HALF + n * 16);
; #pragma unroll
;                 for (int m = 0; m < 4; ++m) { const int r = ai * HALF + wr * 64 + m * 16 + fr; const float r1 = S[r];
; #pragma unroll
;                     for (int bj = 0; bj < 2; ++bj)
; #pragma unroll
;                         for (int n = 0; n < 2; ++n) { acc[ai][bj][m][n] = xv[m][bj][n] + acc[ai][bj][m][n] * r1 * gv[bj][n];
;                             *(f32x4*)(xout + (size_t)(u.pm * BM + r) * DM + col0 + bj * HALF + n * 16) = acc[ai][bj][m][n]; } }
;             }
;         }
;         asm volatile("s_waitcnt lgkmcnt(0)" ::: "memory"); __syncthreads();
;         exchange(acc, u, wr, wc, fr, fq, lds, xs2, cnt2);
	v_pk_mul_f32 v[62:63], v[62:63], v[162:163] op_sel_hi:[1,0]
	v_pk_mul_f32 v[58:59], v[58:59], v[162:163] op_sel_hi:[1,0]
	v_pk_mul_f32 v[54:55], v[54:55], v[162:163] op_sel_hi:[1,0]
	v_pk_mul_f32 v[64:65], v[64:65], v[162:163] op_sel_hi:[1,0]
	v_pk_mul_f32 v[60:61], v[60:61], v[162:163] op_sel_hi:[1,0]
	v_pk_mul_f32 v[56:57], v[56:57], v[162:163] op_sel_hi:[1,0]
	v_pk_mul_f32 v[46:47], v[46:47], v[162:163] op_sel_hi:[1,0]
	v_pk_mul_f32 v[48:49], v[48:49], v[162:163] op_sel_hi:[1,0]
	v_mov_b32_e32 v162, v163
	v_pk_mul_f32 v[44:45], v[44:45], v[162:163] op_sel_hi:[1,0]
	v_pk_mul_f32 v[32:33], v[32:33], v[162:163] op_sel_hi:[1,0]
	v_pk_mul_f32 v[42:43], v[42:43], v[162:163] op_sel_hi:[1,0]
	v_pk_mul_f32 v[38:39], v[38:39], v[162:163] op_sel_hi:[1,0]
	v_pk_mul_f32 v[40:41], v[40:41], v[162:163] op_sel_hi:[1,0]
	v_pk_mul_f32 v[30:31], v[30:31], v[162:163] op_sel_hi:[1,0]
	s_waitcnt vmcnt(15)
	v_pk_fma_f32 v[82:83], v[146:147], v[62:63], v[82:83]
	v_lshl_add_u64 v[62:63], s[38:39], 0, v[200:201]
	v_lshl_add_u64 v[200:201], v[62:63], 0, v[172:173]
	s_waitcnt vmcnt(14)
	v_pk_fma_f32 v[62:63], v[142:143], v[58:59], v[166:167]
	s_waitcnt vmcnt(13)
	v_pk_fma_f32 v[58:59], v[138:139], v[54:55], v[178:179]
	ds_read2_b32 v[178:179], v194 offset0:160 offset1:176
	v_pk_fma_f32 v[84:85], v[148:149], v[64:65], v[84:85]
	v_pk_fma_f32 v[64:65], v[144:145], v[60:61], v[168:169]
	v_pk_fma_f32 v[60:61], v[140:141], v[56:57], v[180:181]
	s_waitcnt vmcnt(12)
	v_pk_fma_f32 v[56:57], v[136:137], v[48:49], v[184:185]
	v_pk_mul_f32 v[48:49], v[50:51], v[162:163] op_sel_hi:[1,0]
	v_pk_mul_f32 v[50:51], v[52:53], v[162:163] op_sel_hi:[1,0]
	s_waitcnt lgkmcnt(0)
	v_pk_mul_f32 v[34:35], v[34:35], v[178:179] op_sel_hi:[1,0]
	v_pk_mul_f32 v[36:37], v[36:37], v[178:179] op_sel_hi:[1,0]
	v_pk_mul_f32 v[26:27], v[26:27], v[178:179] op_sel_hi:[1,0]
	v_pk_mul_f32 v[28:29], v[28:29], v[178:179] op_sel_hi:[1,0]
	v_pk_mul_f32 v[22:23], v[22:23], v[178:179] op_sel_hi:[1,0]
	v_pk_mul_f32 v[24:25], v[24:25], v[178:179] op_sel_hi:[1,0]
	v_pk_mul_f32 v[14:15], v[14:15], v[178:179] op_sel_hi:[1,0]
	v_pk_mul_f32 v[16:17], v[16:17], v[178:179] op_sel_hi:[1,0]
	v_mov_b32_e32 v178, v179
	s_waitcnt vmcnt(11)
	v_pk_fma_f32 v[52:53], v[148:149], v[50:51], v[188:189]
	v_pk_fma_f32 v[50:51], v[146:147], v[48:49], v[186:187]
	s_waitcnt vmcnt(10)
	v_pk_fma_f32 v[48:49], v[144:145], v[44:45], v[192:193]
	s_waitcnt vmcnt(7)
	v_pk_fma_f32 v[44:45], v[148:149], v[36:37], v[214:215]
	s_waitcnt vmcnt(6)
	v_pk_fma_f32 v[36:37], v[144:145], v[28:29], v[218:219]
	s_waitcnt vmcnt(5)
	v_pk_fma_f32 v[28:29], v[140:141], v[24:25], v[222:223]
	s_waitcnt vmcnt(4)
	v_pk_fma_f32 v[24:25], v[136:137], v[16:17], v[226:227]
	v_pk_mul_f32 v[16:17], v[20:21], v[178:179] op_sel_hi:[1,0]
	v_mul_f32_e32 v20, v131, v131
	v_mul_f32_e32 v21, v133, v133
	v_pk_mul_f32 v[4:5], v[4:5], v[178:179] op_sel_hi:[1,0]
	v_fmac_f32_e32 v20, v130, v130
	v_fmac_f32_e32 v21, v132, v132
	v_add_u32_e32 v168, 0x90, v164
	v_pk_fma_f32 v[32:33], v[136:137], v[32:33], v[210:211]
	s_waitcnt vmcnt(0)
	v_pk_fma_f32 v[4:5], v[136:137], v[4:5], v[152:153]
	v_add_f32_e32 v20, v20, v21
	v_mul_f32_e32 v21, v127, v127
	v_mul_f32_e32 v136, v129, v129
	v_ashrrev_i32_e32 v169, 31, v168
	v_fmac_f32_e32 v21, v126, v126
	v_fmac_f32_e32 v136, v128, v128
	v_pk_fma_f32 v[54:55], v[134:135], v[46:47], v[182:183]
	v_lshlrev_b64 v[46:47], 12, v[168:169]
	v_add_f32_e32 v21, v21, v136
	v_lshl_add_u64 v[46:47], s[38:39], 0, v[46:47]
	v_add_f32_e32 v20, v20, v21
	v_mul_f32_e32 v21, v123, v123
	v_mul_f32_e32 v136, v125, v125
	v_lshl_add_u64 v[166:167], v[46:47], 0, v[172:173]
	v_pk_fma_f32 v[46:47], v[142:143], v[42:43], v[190:191]
	v_pk_fma_f32 v[40:41], v[140:141], v[40:41], v[206:207]
	v_pk_fma_f32 v[38:39], v[138:139], v[38:39], v[204:205]
	v_pk_fma_f32 v[30:31], v[134:135], v[30:31], v[208:209]
	v_fmac_f32_e32 v21, v122, v122
	v_fmac_f32_e32 v136, v124, v124
	global_store_dwordx4 v[166:167], v[50:53], off
	global_store_dwordx4 v[166:167], v[46:49], off offset:64
	global_store_dwordx4 v[166:167], v[38:41], off offset:512
	global_store_dwordx4 v[166:167], v[30:33], off offset:576
	v_add_u32_e32 v166, 0xa0, v164
	v_add_f32_e32 v21, v21, v136
	v_ashrrev_i32_e32 v167, 31, v166
	v_add_f32_e32 v20, v21, v20
	v_mul_f32_e32 v21, v119, v119
	v_mul_f32_e32 v136, v121, v121
	v_lshlrev_b64 v[162:163], 12, v[166:167]
	v_fmac_f32_e32 v21, v118, v118
	v_fmac_f32_e32 v136, v120, v120
	v_pk_fma_f32 v[42:43], v[146:147], v[34:35], v[212:213]
	v_lshl_add_u64 v[34:35], s[38:39], 0, v[162:163]
	v_add_f32_e32 v21, v21, v136
	v_lshl_add_u64 v[162:163], v[34:35], 0, v[172:173]
	v_pk_fma_f32 v[34:35], v[142:143], v[26:27], v[216:217]
	v_pk_fma_f32 v[26:27], v[138:139], v[22:23], v[220:221]
	v_pk_fma_f32 v[22:23], v[134:135], v[14:15], v[224:225]
	v_add_f32_e32 v20, v21, v20
	global_store_dwordx4 v[162:163], v[42:45], off
	global_store_dwordx4 v[162:163], v[34:37], off offset:64
	global_store_dwordx4 v[162:163], v[26:29], off offset:512
	global_store_dwordx4 v[162:163], v[22:25], off offset:576
	v_add_u32_e32 v162, 0xb0, v164
	ds_bpermute_b32 v21, v176, v20
	v_ashrrev_i32_e32 v163, 31, v162
	v_lshlrev_b64 v[180:181], 12, v[162:163]
	v_pk_mul_f32 v[14:15], v[18:19], v[178:179] op_sel_hi:[1,0]
	v_lshl_add_u64 v[18:19], s[38:39], 0, v[180:181]
	v_pk_mul_f32 v[10:11], v[10:11], v[178:179] op_sel_hi:[1,0]
	v_pk_mul_f32 v[12:13], v[12:13], v[178:179] op_sel_hi:[1,0]
	v_pk_mul_f32 v[6:7], v[6:7], v[178:179] op_sel_hi:[1,0]
	v_pk_mul_f32 v[8:9], v[8:9], v[178:179] op_sel_hi:[1,0]
	v_pk_mul_f32 v[2:3], v[2:3], v[178:179] op_sel_hi:[1,0]
	v_pk_fma_f32 v[16:17], v[148:149], v[16:17], v[240:241]
	v_pk_fma_f32 v[14:15], v[146:147], v[14:15], v[238:239]
	v_lshl_add_u64 v[18:19], v[18:19], 0, v[172:173]
	v_pk_fma_f32 v[12:13], v[144:145], v[12:13], v[244:245]
	v_pk_fma_f32 v[10:11], v[142:143], v[10:11], v[242:243]
	v_pk_fma_f32 v[8:9], v[140:141], v[8:9], v[248:249]
	v_pk_fma_f32 v[6:7], v[138:139], v[6:7], v[246:247]
	v_pk_fma_f32 v[2:3], v[134:135], v[2:3], v[150:151]
	global_store_dwordx4 v[18:19], v[14:17], off
	global_store_dwordx4 v[18:19], v[10:13], off offset:64
	global_store_dwordx4 v[18:19], v[6:9], off offset:512
	global_store_dwordx4 v[18:19], v[2:5], off offset:576
	s_waitcnt lgkmcnt(0)
	v_add_f32_e32 v18, v20, v21
	ds_bpermute_b32 v19, v177, v18
	global_store_dwordx4 v[200:201], v[82:85], off
	global_store_dwordx4 v[200:201], v[62:65], off offset:64
	global_store_dwordx4 v[200:201], v[58:61], off offset:512
	global_store_dwordx4 v[200:201], v[54:57], off offset:576
	s_waitcnt lgkmcnt(0)
	v_mov_b32_e32 v20, v0
	s_waitcnt lgkmcnt(0)
	s_barrier
;     __device__ __forceinline__ void exchange(const f32x4 (&v)[2][2][4][2], const Unit& u, int wr, int wc, int fr, int fq, LAS unsigned char* lds, unsigned* xs, unsigned* cnt) const {
;     ...
; #pragma unroll
;         for (int ai = 0; ai < 2; ++ai)
; #pragma unroll
;             for (int m = 0; m < 4; ++m) { float sq = 0.f;
; #pragma unroll
;                 for (int bj = 0; bj < 2; ++bj)
; #pragma unroll
;                     for (int n = 0; n < 2; ++n) { const f32x4 x = v[ai][bj][m][n]; sq += (x[0] * x[0] + x[1] * x[1]) + (x[2] * x[2] + x[3] * x[3]); }
;                 sq += __shfl_xor(sq, 16); sq += __shfl_xor(sq, 32);
;                 if (fq == 0) Pp[(ai * HALF + wr * 64 + m * 16 + fr) * 4 + wc] = sq; }
	s_and_saveexec_b64 s[38:39], s[36:37]
	s_lshl_b32 s5, s2, 10
	s_add_i32 s5, s7, s5
	v_lshl_add_u32 v21, v174, 4, s5
	v_add_f32_e32 v18, v18, v19
	ds_write_b32 v21, v18
	s_or_b64 exec, exec, s[38:39]
	v_mul_f32_e32 v18, v111, v111
	v_mul_f32_e32 v19, v113, v113
	v_fmac_f32_e32 v18, v110, v110
	v_fmac_f32_e32 v19, v112, v112
	v_add_f32_e32 v18, v18, v19
	v_mul_f32_e32 v19, v115, v115
	v_mul_f32_e32 v21, v117, v117
	v_fmac_f32_e32 v19, v114, v114
	v_fmac_f32_e32 v21, v116, v116
	v_add_f32_e32 v19, v19, v21
	v_add_f32_e32 v18, v18, v19
	v_mul_f32_e32 v19, v107, v107
	v_mul_f32_e32 v21, v109, v109
	v_fmac_f32_e32 v19, v106, v106
	v_fmac_f32_e32 v21, v108, v108
	v_add_f32_e32 v19, v19, v21
	v_add_f32_e32 v18, v19, v18
	v_mul_f32_e32 v19, v103, v103
	v_mul_f32_e32 v21, v105, v105
	v_fmac_f32_e32 v19, v102, v102
	v_fmac_f32_e32 v21, v104, v104
	v_add_f32_e32 v19, v19, v21
	v_add_f32_e32 v18, v19, v18
	v_mov_b32_e32 v19, v18
	s_nop 1
	v_permlane16_swap_b32_e32 v19, v18
	s_nop 1
	s_waitcnt lgkmcnt(0)
	v_add_f32_e32 v18, v18, v19
	v_mov_b32_e32 v19, v18
	s_nop 1
	v_permlane32_swap_b32_e32 v19, v18
	s_nop 1
	s_and_saveexec_b64 s[38:39], s[36:37]
	s_cbranch_execz .LBB0_204
	s_lshl_b32 s5, s2, 10
	s_add_i32 s5, s7, s5
	v_lshl_add_u32 v21, v174, 4, s5
	s_waitcnt lgkmcnt(0)
	v_add_f32_e32 v18, v18, v19
	ds_write_b32 v21, v18 offset:256
.LBB0_204:
	s_or_b64 exec, exec, s[38:39]
	v_mul_f32_e32 v18, v95, v95
	s_waitcnt lgkmcnt(0)
	v_mul_f32_e32 v19, v97, v97
	v_fmac_f32_e32 v18, v94, v94
	v_fmac_f32_e32 v19, v96, v96
	v_add_f32_e32 v18, v18, v19
	v_mul_f32_e32 v19, v99, v99
	v_mul_f32_e32 v21, v101, v101
	v_fmac_f32_e32 v19, v98, v98
	v_fmac_f32_e32 v21, v100, v100
	v_add_f32_e32 v19, v19, v21
	v_add_f32_e32 v18, v18, v19
	v_mul_f32_e32 v19, v91, v91
	v_mul_f32_e32 v21, v93, v93
	v_fmac_f32_e32 v19, v90, v90
	v_fmac_f32_e32 v21, v92, v92
	v_add_f32_e32 v19, v19, v21
	v_add_f32_e32 v18, v19, v18
	v_mul_f32_e32 v19, v87, v87
	v_mul_f32_e32 v21, v89, v89
	v_fmac_f32_e32 v19, v86, v86
	v_fmac_f32_e32 v21, v88, v88
	v_add_f32_e32 v19, v19, v21
	v_add_f32_e32 v18, v19, v18
	v_mov_b32_e32 v19, v18
	s_nop 1
	v_permlane16_swap_b32_e32 v19, v18
	s_nop 1
	s_waitcnt lgkmcnt(0)
	v_add_f32_e32 v18, v18, v19
	v_mov_b32_e32 v19, v18
	s_nop 1
	v_permlane32_swap_b32_e32 v19, v18
	s_nop 1
	s_and_saveexec_b64 s[38:39], s[36:37]
	s_cbranch_execz .LBB0_206
	s_lshl_b32 s5, s2, 10
	s_add_i32 s5, s7, s5
	v_lshl_add_u32 v21, v174, 4, s5
	s_waitcnt lgkmcnt(0)
	v_add_f32_e32 v18, v18, v19
	ds_write_b32 v21, v18 offset:512
.LBB0_206:
	s_or_b64 exec, exec, s[38:39]
	v_mul_f32_e32 v18, v79, v79
	s_waitcnt lgkmcnt(0)
	v_mul_f32_e32 v19, v81, v81
	v_fmac_f32_e32 v18, v78, v78
	v_fmac_f32_e32 v19, v80, v80
	v_add_f32_e32 v18, v18, v19
	v_mul_f32_e32 v19, v75, v75
	v_mul_f32_e32 v21, v77, v77
	v_fmac_f32_e32 v19, v74, v74
	v_fmac_f32_e32 v21, v76, v76
	v_add_f32_e32 v19, v19, v21
	v_add_f32_e32 v18, v18, v19
	v_mul_f32_e32 v19, v71, v71
	v_mul_f32_e32 v21, v73, v73
	v_fmac_f32_e32 v19, v70, v70
	v_fmac_f32_e32 v21, v72, v72
	v_add_f32_e32 v19, v19, v21
	v_add_f32_e32 v18, v19, v18
	v_mul_f32_e32 v19, v67, v67
	v_mul_f32_e32 v21, v69, v69
	v_fmac_f32_e32 v19, v66, v66
	v_fmac_f32_e32 v21, v68, v68
	v_add_f32_e32 v19, v19, v21
	v_add_f32_e32 v18, v19, v18
	v_mov_b32_e32 v19, v18
	s_nop 1
	v_permlane16_swap_b32_e32 v19, v18
	s_nop 1
	s_waitcnt lgkmcnt(0)
	v_add_f32_e32 v18, v18, v19
	v_mov_b32_e32 v19, v18
	s_nop 1
	v_permlane32_swap_b32_e32 v19, v18
	s_nop 1
	s_and_saveexec_b64 s[38:39], s[36:37]
	s_cbranch_execz .LBB0_208
	s_lshl_b32 s5, s2, 10
	s_add_i32 s5, s7, s5
	v_lshl_add_u32 v21, v174, 4, s5
	s_waitcnt lgkmcnt(0)
	v_add_f32_e32 v18, v18, v19
	ds_write_b32 v21, v18 offset:768
;     __device__ __forceinline__ void exchange(const f32x4 (&v)[2][2][4][2], const Unit& u, int wr, int wc, int fr, int fq, LAS unsigned char* lds, unsigned* xs, unsigned* cnt) const {
;     ...
; #pragma unroll
;         for (int ai = 0; ai < 2; ++ai)
; #pragma unroll
;             for (int m = 0; m < 4; ++m) { float sq = 0.f;
; #pragma unroll
;                 for (int bj = 0; bj < 2; ++bj)
; #pragma unroll
;                     for (int n = 0; n < 2; ++n) { const f32x4 x = v[ai][bj][m][n]; sq += (x[0] * x[0] + x[1] * x[1]) + (x[2] * x[2] + x[3] * x[3]); }
;                 sq += __shfl_xor(sq, 16); sq += __shfl_xor(sq, 32);
;                 if (fq == 0) Pp[(ai * HALF + wr * 64 + m * 16 + fr) * 4 + wc] = sq; }
.LBB0_208:
	s_or_b64 exec, exec, s[38:39]
	v_mul_f32_e32 v18, v83, v83
	s_waitcnt lgkmcnt(0)
	v_mul_f32_e32 v19, v85, v85
	v_fmac_f32_e32 v18, v82, v82
	v_fmac_f32_e32 v19, v84, v84
	v_add_f32_e32 v18, v18, v19
	v_mul_f32_e32 v19, v63, v63
	v_mul_f32_e32 v21, v65, v65
	v_fmac_f32_e32 v19, v62, v62
	v_fmac_f32_e32 v21, v64, v64
	v_add_f32_e32 v19, v19, v21
	v_add_f32_e32 v18, v18, v19
	v_mul_f32_e32 v19, v59, v59
	v_mul_f32_e32 v21, v61, v61
	v_fmac_f32_e32 v19, v58, v58
	v_fmac_f32_e32 v21, v60, v60
	v_add_f32_e32 v19, v19, v21
	v_add_f32_e32 v18, v19, v18
	v_mul_f32_e32 v19, v55, v55
	v_mul_f32_e32 v21, v57, v57
	v_fmac_f32_e32 v19, v54, v54
	v_fmac_f32_e32 v21, v56, v56
	v_add_f32_e32 v19, v19, v21
	v_add_f32_e32 v18, v19, v18
	v_mov_b32_e32 v19, v18
	s_nop 1
	v_permlane16_swap_b32_e32 v19, v18
	s_nop 1
	s_waitcnt lgkmcnt(0)
	v_add_f32_e32 v18, v18, v19
	v_mov_b32_e32 v19, v18
	s_nop 1
	v_permlane32_swap_b32_e32 v19, v18
	s_nop 1
	s_and_saveexec_b64 s[38:39], s[36:37]
	s_cbranch_execz .LBB0_210
	s_lshl_b32 s5, s2, 10
	s_add_i32 s5, s7, s5
	v_lshl_add_u32 v21, v174, 4, s5
	s_waitcnt lgkmcnt(0)
	v_add_f32_e32 v18, v18, v19
	ds_write_b32 v21, v18 offset:2048
.LBB0_210:
	s_or_b64 exec, exec, s[38:39]
	v_mul_f32_e32 v18, v51, v51
	s_waitcnt lgkmcnt(0)
	v_mul_f32_e32 v19, v53, v53
	v_fmac_f32_e32 v18, v50, v50
	v_fmac_f32_e32 v19, v52, v52
	v_add_f32_e32 v18, v18, v19
	v_mul_f32_e32 v19, v47, v47
	v_mul_f32_e32 v21, v49, v49
	v_fmac_f32_e32 v19, v46, v46
	v_fmac_f32_e32 v21, v48, v48
	v_add_f32_e32 v19, v19, v21
	v_add_f32_e32 v18, v18, v19
	v_mul_f32_e32 v19, v39, v39
	v_mul_f32_e32 v21, v41, v41
	v_fmac_f32_e32 v19, v38, v38
	v_fmac_f32_e32 v21, v40, v40
	v_add_f32_e32 v19, v19, v21
	v_add_f32_e32 v18, v19, v18
	v_mul_f32_e32 v19, v31, v31
	v_mul_f32_e32 v21, v33, v33
	v_fmac_f32_e32 v19, v30, v30
	v_fmac_f32_e32 v21, v32, v32
	v_add_f32_e32 v19, v19, v21
	v_add_f32_e32 v18, v19, v18
	v_mov_b32_e32 v19, v18
	s_nop 1
	v_permlane16_swap_b32_e32 v19, v18
	s_nop 1
	s_waitcnt lgkmcnt(0)
	v_add_f32_e32 v18, v18, v19
	v_mov_b32_e32 v19, v18
	s_nop 1
	v_permlane32_swap_b32_e32 v19, v18
	s_nop 1
	s_and_saveexec_b64 s[38:39], s[36:37]
	s_cbranch_execz .LBB0_212
	s_lshl_b32 s5, s2, 10
	s_add_i32 s5, s7, s5
	v_lshl_add_u32 v21, v174, 4, s5
	s_waitcnt lgkmcnt(0)
	v_add_f32_e32 v18, v18, v19
	ds_write_b32 v21, v18 offset:2304
.LBB0_212:
	s_or_b64 exec, exec, s[38:39]
	v_mul_f32_e32 v18, v43, v43
	s_waitcnt lgkmcnt(0)
	v_mul_f32_e32 v19, v45, v45
	v_fmac_f32_e32 v18, v42, v42
	v_fmac_f32_e32 v19, v44, v44
	v_add_f32_e32 v18, v18, v19
	v_mul_f32_e32 v19, v35, v35
	v_mul_f32_e32 v21, v37, v37
	v_fmac_f32_e32 v19, v34, v34
	v_fmac_f32_e32 v21, v36, v36
	v_add_f32_e32 v19, v19, v21
	v_add_f32_e32 v18, v18, v19
	v_mul_f32_e32 v19, v27, v27
	v_mul_f32_e32 v21, v29, v29
	v_fmac_f32_e32 v19, v26, v26
	v_fmac_f32_e32 v21, v28, v28
	v_add_f32_e32 v19, v19, v21
	v_add_f32_e32 v18, v19, v18
	v_mul_f32_e32 v19, v23, v23
	v_mul_f32_e32 v21, v25, v25
	v_fmac_f32_e32 v19, v22, v22
	v_fmac_f32_e32 v21, v24, v24
	v_add_f32_e32 v19, v19, v21
	v_add_f32_e32 v18, v19, v18
	v_mov_b32_e32 v19, v18
	s_nop 1
	v_permlane16_swap_b32_e32 v19, v18
	s_nop 1
	s_waitcnt lgkmcnt(0)
	v_add_f32_e32 v18, v18, v19
	v_mov_b32_e32 v19, v18
	s_nop 1
	v_permlane32_swap_b32_e32 v19, v18
	s_nop 1
	s_and_saveexec_b64 s[38:39], s[36:37]
	s_cbranch_execz .LBB0_214
	s_lshl_b32 s5, s2, 10
	s_add_i32 s5, s7, s5
	v_lshl_add_u32 v21, v174, 4, s5
	s_waitcnt lgkmcnt(0)
	v_add_f32_e32 v18, v18, v19
	ds_write_b32 v21, v18 offset:2560
.LBB0_214:
	s_or_b64 exec, exec, s[38:39]
	v_mul_f32_e32 v18, v15, v15
	s_waitcnt lgkmcnt(0)
	v_mul_f32_e32 v19, v17, v17
	v_fmac_f32_e32 v18, v14, v14
	v_fmac_f32_e32 v19, v16, v16
	v_add_f32_e32 v18, v18, v19
	v_mul_f32_e32 v19, v11, v11
	v_mul_f32_e32 v21, v13, v13
	v_fmac_f32_e32 v19, v10, v10
	v_fmac_f32_e32 v21, v12, v12
	v_add_f32_e32 v19, v19, v21
	v_add_f32_e32 v18, v18, v19
	v_mul_f32_e32 v19, v7, v7
	v_mul_f32_e32 v21, v9, v9
	v_fmac_f32_e32 v19, v6, v6
	v_fmac_f32_e32 v21, v8, v8
	v_add_f32_e32 v19, v19, v21
	v_add_f32_e32 v18, v19, v18
	v_mul_f32_e32 v19, v3, v3
	v_mul_f32_e32 v21, v5, v5
	v_fmac_f32_e32 v19, v2, v2
	v_fmac_f32_e32 v21, v4, v4
	v_add_f32_e32 v19, v19, v21
	v_add_f32_e32 v18, v19, v18
	v_mov_b32_e32 v19, v18
	s_nop 1
	v_permlane16_swap_b32_e32 v19, v18
	s_nop 1
	s_waitcnt lgkmcnt(0)
	v_add_f32_e32 v18, v18, v19
	v_mov_b32_e32 v19, v18
	s_nop 1
	v_permlane32_swap_b32_e32 v19, v18
	s_nop 1
	s_and_saveexec_b64 s[38:39], s[36:37]
	s_cbranch_execz .LBB0_216
	s_lshl_b32 s2, s2, 10
	s_add_i32 s7, s7, s2
	v_lshl_add_u32 v21, v174, 4, s7
	s_waitcnt lgkmcnt(0)
	v_add_f32_e32 v18, v18, v19
	ds_write_b32 v21, v18 offset:2816

; #define LAS __attribute__((address_space(3)))
; __device__ __forceinline__ unsigned cvt_pk_bf16(float lo, float hi) { unsigned r; asm volatile("v_cvt_pk_bf16_f32 %0, %1, %2" : "=v"(r) : "v"(lo), "v"(hi)); return r; }
; __device__ void phase_norm_alow(const Params& P, int l, int half, LAS unsigned char* lds) {
;     ...
;     for (; row < TH; row += rstride) {
;         f32x4 v[4]; float ss = 0.f;
; #pragma unroll
;         for (int i = 0; i < 4; ++i) { v[i] = nv[i]; ss += v[i][0] * v[i][0] + v[i][1] * v[i][1] + v[i][2] * v[i][2] + v[i][3] * v[i][3]; }
;         if (row + rstride < TH) {
; #pragma unroll
;             for (int i = 0; i < 4; ++i) nv[i] = *(const f32x4*)(xs + (size_t)(row + rstride) * DM + i * 256 + lane * 4);
;         }
;         ss = wave_sum(ss);
;         const float r = rsqrtf(ss * (1.0f / DM) + EPS);
;         float a[16];
; #pragma unroll
;         for (int c = 0; c < 16; ++c) a[c] = 0.f;
; #pragma unroll
;         for (int i = 0; i < 4; ++i) { f32x4 h = v[i] * r * gv[i];
;             u32x2 w; w.x = cvt_pk_bf16(h[0], h[1]); w.y = cvt_pk_bf16(h[2], h[3]);
;             *(u32x2*)(H + (size_t)row * DM + i * 256 + lane * 4) = w;
; #pragma unroll
;             for (int c = 0; c < 16; ++c) { const f32x4 wv = *(const LAS f32x4*)(WaT + c * 1024 + i * 256 + lane * 4); a[c] += h[0] * wv[0] + h[1] * wv[1] + h[2] * wv[2] + h[3] * wv[3]; } }
.LBB0_242:
	s_or_b64 exec, exec, s[30:31]
	v_mul_f32_e32 v51, v47, v47
	v_mul_f32_e32 v58, v43, v43
	v_fmac_f32_e32 v51, v46, v46
	v_fmac_f32_e32 v58, v42, v42
	v_fmac_f32_e32 v51, v48, v48
	v_fmac_f32_e32 v58, v44, v44
	v_fmac_f32_e32 v51, v49, v49
	v_fmac_f32_e32 v58, v45, v45
	v_add_f32_e32 v51, v51, v58
	v_mul_f32_e32 v58, v39, v39
	v_fmac_f32_e32 v58, v38, v38
	v_fmac_f32_e32 v58, v40, v40
	v_fmac_f32_e32 v58, v41, v41
	v_add_f32_e32 v51, v51, v58
	v_mul_f32_e32 v58, v35, v35
	v_fmac_f32_e32 v58, v34, v34
	v_fmac_f32_e32 v58, v36, v36
	v_fmac_f32_e32 v58, v37, v37
	v_add_f32_e32 v51, v51, v58
	v_mov_b32_e32 v58, v51
	s_nop 1
	v_permlane32_swap_b32_e32 v58, v51
	s_nop 1
	v_lshl_add_u64 v[68:69], s[74:75], 0, v[54:55]
	s_waitcnt lgkmcnt(0)
	v_add_f32_e32 v51, v51, v58
	v_mov_b32_e32 v58, v51
	s_nop 1
	v_permlane16_swap_b32_e32 v58, v51
	s_nop 1
	s_waitcnt lgkmcnt(0)
	v_add_f32_e32 v51, v51, v58
	s_nop 1
	v_mov_b32_dpp v58, v51 row_ror:8 row_mask:0xf bank_mask:0xf
	s_waitcnt lgkmcnt(0)
	v_add_f32_e32 v51, v51, v58
	s_nop 1
	v_mov_b32_dpp v58, v51 row_shl:4 row_mask:0xf bank_mask:0x5
	s_nop 1
	v_mov_b32_dpp v58, v51 row_shr:4 row_mask:0xf bank_mask:0xa
	s_waitcnt lgkmcnt(0)
	v_add_f32_e32 v51, v51, v58
	s_nop 1
	v_mov_b32_dpp v58, v51 quad_perm:[2,3,0,1] row_mask:0xf bank_mask:0xf
	s_waitcnt lgkmcnt(0)
	v_add_f32_e32 v51, v51, v58
	s_nop 1
	v_mov_b32_dpp v58, v51 quad_perm:[1,0,3,2] row_mask:0xf bank_mask:0xf
	s_waitcnt lgkmcnt(0)
	v_add_f32_e32 v51, v51, v58
	v_fmamk_f32 v51, v51, 0x3a800000, v1
	v_cmp_gt_f32_e64 s[0:1], s33, v51
	v_mul_f32_e32 v58, 0x4b800000, v51
	s_nop 0
	v_cndmask_b32_e64 v51, v51, v58, s[0:1]
	v_rsq_f32_e32 v51, v51
	s_nop 0
	v_mul_f32_e32 v58, 0x45800000, v51
	v_cndmask_b32_e64 v58, v51, v58, s[0:1]
	v_pk_mul_f32 v[46:47], v[46:47], v[58:59] op_sel_hi:[1,0]
	s_mov_b32 s0, 0x5a88000
	v_pk_mul_f32 v[48:49], v[48:49], v[58:59] op_sel_hi:[1,0]
	v_pk_mul_f32 v[60:61], v[14:15], v[46:47]
	v_add_co_u32_e64 v46, s[0:1], s0, v68
	v_pk_mul_f32 v[48:49], v[16:17], v[48:49]
	v_cvt_pk_bf16_f32 v70, v60, v61
	s_nop 0
	v_addc_co_u32_e64 v47, s[0:1], 0, v69, s[0:1]
	v_cvt_pk_bf16_f32 v71, v48, v49
	global_store_dwordx2 v[46:47], v[70:71], off
	ds_read_b128 v[100:103], v67
	ds_read_b128 v[104:107], v67 offset:4096
	ds_read_b128 v[108:111], v67 offset:8192
	ds_read_b128 v[112:115], v67 offset:12288
	ds_read_b128 v[116:119], v67 offset:16384
	ds_read_b128 v[120:123], v67 offset:20480
	ds_read_b128 v[124:127], v67 offset:24576
	s_waitcnt lgkmcnt(6)
	v_mul_f32_e32 v51, v101, v61
	v_fmac_f32_e32 v51, v100, v60
	v_fmac_f32_e32 v51, v102, v48
	v_fmac_f32_e32 v51, v103, v49
	ds_read_b128 v[128:131], v67 offset:28672
	v_add_f32_e32 v69, 0, v51
	s_waitcnt lgkmcnt(6)
	v_mul_f32_e32 v51, v105, v61
	v_fmac_f32_e32 v51, v104, v60
	v_fmac_f32_e32 v51, v106, v48
	v_fmac_f32_e32 v51, v107, v49
	ds_read_b128 v[100:103], v67 offset:32768
	v_add_f32_e32 v51, 0, v51
	s_waitcnt lgkmcnt(6)
	v_mul_f32_e32 v68, v109, v61
	v_fmac_f32_e32 v68, v108, v60
	v_fmac_f32_e32 v68, v110, v48
	v_fmac_f32_e32 v68, v111, v49
	ds_read_b128 v[104:107], v67 offset:36864
	v_add_f32_e32 v68, 0, v68
	s_waitcnt lgkmcnt(6)
	v_mul_f32_e32 v71, v113, v61
	v_fmac_f32_e32 v71, v112, v60
	v_fmac_f32_e32 v71, v114, v48
	v_fmac_f32_e32 v71, v115, v49
	ds_read_b128 v[108:111], v67 offset:40960
	v_add_f32_e32 v70, 0, v71
	s_waitcnt lgkmcnt(6)
	v_mul_f32_e32 v71, v117, v61
	v_fmac_f32_e32 v71, v116, v60
	v_fmac_f32_e32 v71, v118, v48
	v_fmac_f32_e32 v71, v119, v49
	ds_read_b128 v[112:115], v67 offset:45056
	v_add_f32_e32 v71, 0, v71
	s_waitcnt lgkmcnt(6)
	v_mul_f32_e32 v73, v121, v61
	v_fmac_f32_e32 v73, v120, v60
	v_fmac_f32_e32 v73, v122, v48
	v_fmac_f32_e32 v73, v123, v49
	ds_read_b128 v[116:119], v67 offset:49152
	v_add_f32_e32 v72, 0, v73
	s_waitcnt lgkmcnt(6)
	v_mul_f32_e32 v73, v125, v61
	v_fmac_f32_e32 v73, v124, v60
	v_fmac_f32_e32 v73, v126, v48
	v_fmac_f32_e32 v73, v127, v49
	ds_read_b128 v[120:123], v67 offset:53248
	v_add_f32_e32 v73, 0, v73
	s_waitcnt lgkmcnt(6)
	v_mul_f32_e32 v75, v129, v61
	v_fmac_f32_e32 v75, v128, v60
	v_fmac_f32_e32 v75, v130, v48
	v_fmac_f32_e32 v75, v131, v49
	ds_read_b128 v[124:127], v67 offset:57344
	v_add_f32_e32 v74, 0, v75
	s_waitcnt lgkmcnt(6)
	v_mul_f32_e32 v75, v101, v61
	v_fmac_f32_e32 v75, v100, v60
	v_fmac_f32_e32 v75, v102, v48
	v_fmac_f32_e32 v75, v103, v49
	ds_read_b128 v[128:131], v67 offset:61440
	v_add_f32_e32 v75, 0, v75
	s_waitcnt lgkmcnt(6)
	v_mul_f32_e32 v77, v61, v105
	v_fmac_f32_e32 v77, v60, v104
	v_fmac_f32_e32 v77, v48, v106
	v_fmac_f32_e32 v77, v49, v107
	ds_read_b128 v[100:103], v67 offset:1024
	v_add_f32_e32 v76, 0, v77
	s_waitcnt lgkmcnt(6)
	v_mul_f32_e32 v77, v61, v109
	v_fmac_f32_e32 v77, v60, v108
	v_fmac_f32_e32 v77, v48, v110
	v_fmac_f32_e32 v77, v49, v111
	ds_read_b128 v[104:107], v67 offset:5120
	v_add_f32_e32 v77, 0, v77
	s_waitcnt lgkmcnt(6)
	v_mul_f32_e32 v79, v61, v113
	v_fmac_f32_e32 v79, v60, v112
	v_fmac_f32_e32 v79, v48, v114
	v_fmac_f32_e32 v79, v49, v115
	ds_read_b128 v[108:111], v67 offset:9216
	v_add_f32_e32 v78, 0, v79
	s_waitcnt lgkmcnt(6)
	v_mul_f32_e32 v79, v61, v117
	v_fmac_f32_e32 v79, v60, v116
	v_fmac_f32_e32 v79, v48, v118
	v_fmac_f32_e32 v79, v49, v119
	ds_read_b128 v[112:115], v67 offset:13312
	v_add_f32_e32 v79, 0, v79
	s_waitcnt lgkmcnt(6)
	v_mul_f32_e32 v81, v61, v121
	v_fmac_f32_e32 v81, v60, v120
	v_fmac_f32_e32 v81, v48, v122
	v_fmac_f32_e32 v81, v49, v123
	ds_read_b128 v[116:119], v67 offset:17408
	v_add_f32_e32 v80, 0, v81
	s_waitcnt lgkmcnt(6)
	v_mul_f32_e32 v81, v61, v125
	v_fmac_f32_e32 v81, v60, v124
	v_fmac_f32_e32 v81, v48, v126
	v_fmac_f32_e32 v81, v49, v127
	ds_read_b128 v[120:123], v67 offset:21504
	v_add_f32_e32 v81, 0, v81
	s_waitcnt lgkmcnt(6)
; #define LAS __attribute__((address_space(3)))
; __device__ __forceinline__ unsigned cvt_pk_bf16(float lo, float hi) { unsigned r; asm volatile("v_cvt_pk_bf16_f32 %0, %1, %2" : "=v"(r) : "v"(lo), "v"(hi)); return r; }
; __device__ void phase_norm_alow(const Params& P, int l, int half, LAS unsigned char* lds) {
;     ...
;         for (int i = 0; i < 4; ++i) { f32x4 h = v[i] * r * gv[i];
;             u32x2 w; w.x = cvt_pk_bf16(h[0], h[1]); w.y = cvt_pk_bf16(h[2], h[3]);
;             *(u32x2*)(H + (size_t)row * DM + i * 256 + lane * 4) = w;
; #pragma unroll
;             for (int c = 0; c < 16; ++c) { const f32x4 wv = *(const LAS f32x4*)(WaT + c * 1024 + i * 256 + lane * 4); a[c] += h[0] * wv[0] + h[1] * wv[1] + h[2] * wv[2] + h[3] * wv[3]; } }
	v_mul_f32_e32 v61, v61, v129
	v_fmac_f32_e32 v61, v60, v128
	v_fmac_f32_e32 v61, v48, v130
	v_fmac_f32_e32 v61, v49, v131
	v_add_f32_e32 v48, 0, v61
	v_pk_mul_f32 v[60:61], v[42:43], v[58:59] op_sel_hi:[1,0]
	v_pk_mul_f32 v[42:43], v[44:45], v[58:59] op_sel_hi:[1,0]
	v_pk_mul_f32 v[44:45], v[10:11], v[60:61]
	v_pk_mul_f32 v[42:43], v[12:13], v[42:43]
	v_cvt_pk_bf16_f32 v60, v44, v45
	s_nop 0
	v_cvt_pk_bf16_f32 v61, v42, v43
	ds_read_b128 v[124:127], v67 offset:25600
	global_store_dwordx2 v[46:47], v[60:61], off offset:512
	s_waitcnt lgkmcnt(6)
	v_mul_f32_e32 v49, v45, v101
	v_fmac_f32_e32 v49, v44, v100
	v_fmac_f32_e32 v49, v42, v102
	v_fmac_f32_e32 v49, v43, v103
	ds_read_b128 v[128:131], v67 offset:29696
	v_add_f32_e32 v49, v69, v49
	s_waitcnt lgkmcnt(6)
	v_mul_f32_e32 v60, v45, v105
	v_fmac_f32_e32 v60, v44, v104
	v_fmac_f32_e32 v60, v42, v106
	v_fmac_f32_e32 v60, v43, v107
	ds_read_b128 v[100:103], v67 offset:33792
	v_add_f32_e32 v51, v51, v60
	s_waitcnt lgkmcnt(6)
	v_mul_f32_e32 v60, v45, v109
	v_fmac_f32_e32 v60, v44, v108
	v_fmac_f32_e32 v60, v42, v110
	v_fmac_f32_e32 v60, v43, v111
	ds_read_b128 v[104:107], v67 offset:37888
	v_add_f32_e32 v60, v68, v60
	s_waitcnt lgkmcnt(6)
	v_mul_f32_e32 v61, v45, v113
	v_fmac_f32_e32 v61, v44, v112
	v_fmac_f32_e32 v61, v42, v114
	v_fmac_f32_e32 v61, v43, v115
	ds_read_b128 v[108:111], v67 offset:41984
	v_add_f32_e32 v61, v70, v61
	s_waitcnt lgkmcnt(6)
	v_mul_f32_e32 v68, v45, v117
	v_fmac_f32_e32 v68, v44, v116
	v_fmac_f32_e32 v68, v42, v118
	v_fmac_f32_e32 v68, v43, v119
	ds_read_b128 v[112:115], v67 offset:46080
	v_add_f32_e32 v68, v71, v68
	s_waitcnt lgkmcnt(6)
	v_mul_f32_e32 v69, v45, v121
	v_fmac_f32_e32 v69, v44, v120
	v_fmac_f32_e32 v69, v42, v122
	v_fmac_f32_e32 v69, v43, v123
	ds_read_b128 v[116:119], v67 offset:50176
	v_add_f32_e32 v69, v72, v69
	s_waitcnt lgkmcnt(6)
	v_mul_f32_e32 v70, v45, v125
	v_fmac_f32_e32 v70, v44, v124
	v_fmac_f32_e32 v70, v42, v126
	v_fmac_f32_e32 v70, v43, v127
	ds_read_b128 v[120:123], v67 offset:54272
	v_add_f32_e32 v70, v73, v70
	s_waitcnt lgkmcnt(6)
	v_mul_f32_e32 v71, v45, v129
	v_fmac_f32_e32 v71, v44, v128
	v_fmac_f32_e32 v71, v42, v130
	v_fmac_f32_e32 v71, v43, v131
	ds_read_b128 v[124:127], v67 offset:58368
	v_add_f32_e32 v71, v74, v71
	s_waitcnt lgkmcnt(6)
	v_mul_f32_e32 v72, v45, v101
	v_fmac_f32_e32 v72, v44, v100
	v_fmac_f32_e32 v72, v42, v102
	v_fmac_f32_e32 v72, v43, v103
	ds_read_b128 v[128:131], v67 offset:62464
	v_add_f32_e32 v72, v75, v72
	s_waitcnt lgkmcnt(6)
	v_mul_f32_e32 v73, v45, v105
	v_fmac_f32_e32 v73, v44, v104
	v_fmac_f32_e32 v73, v42, v106
	v_fmac_f32_e32 v73, v43, v107
	ds_read_b128 v[100:103], v67 offset:2048
	v_add_f32_e32 v73, v76, v73
	s_waitcnt lgkmcnt(6)
	v_mul_f32_e32 v74, v45, v109
	v_fmac_f32_e32 v74, v44, v108
	v_fmac_f32_e32 v74, v42, v110
	v_fmac_f32_e32 v74, v43, v111
	ds_read_b128 v[104:107], v67 offset:6144
	v_add_f32_e32 v74, v77, v74
	s_waitcnt lgkmcnt(6)
	v_mul_f32_e32 v75, v45, v113
	v_fmac_f32_e32 v75, v44, v112
	v_fmac_f32_e32 v75, v42, v114
	v_fmac_f32_e32 v75, v43, v115
	ds_read_b128 v[108:111], v67 offset:10240
	v_add_f32_e32 v75, v78, v75
	s_waitcnt lgkmcnt(6)
	v_mul_f32_e32 v76, v45, v117
	v_fmac_f32_e32 v76, v44, v116
	v_fmac_f32_e32 v76, v42, v118
	v_fmac_f32_e32 v76, v43, v119
	ds_read_b128 v[112:115], v67 offset:14336
	v_add_f32_e32 v76, v79, v76
	s_waitcnt lgkmcnt(6)
	v_mul_f32_e32 v77, v45, v121
	v_fmac_f32_e32 v77, v44, v120
	v_fmac_f32_e32 v77, v42, v122
	v_fmac_f32_e32 v77, v43, v123
	ds_read_b128 v[116:119], v67 offset:18432
	v_add_f32_e32 v77, v80, v77
	s_waitcnt lgkmcnt(6)
	v_mul_f32_e32 v78, v45, v125
	v_fmac_f32_e32 v78, v44, v124
	v_fmac_f32_e32 v78, v42, v126
	v_fmac_f32_e32 v78, v43, v127
	v_add_f32_e32 v78, v81, v78
	ds_read_b128 v[120:123], v67 offset:22528
	s_waitcnt lgkmcnt(6)
	v_mul_f32_e32 v45, v45, v129
	v_fmac_f32_e32 v45, v44, v128
	v_fmac_f32_e32 v45, v42, v130
	v_fmac_f32_e32 v45, v43, v131
	v_pk_mul_f32 v[42:43], v[38:39], v[58:59] op_sel_hi:[1,0]
	v_pk_mul_f32 v[38:39], v[40:41], v[58:59] op_sel_hi:[1,0]
	v_pk_mul_f32 v[40:41], v[6:7], v[42:43]
	v_pk_mul_f32 v[38:39], v[8:9], v[38:39]
	v_cvt_pk_bf16_f32 v42, v40, v41
	v_add_f32_e32 v79, v48, v45
	v_cvt_pk_bf16_f32 v43, v38, v39
	global_store_dwordx2 v[46:47], v[42:43], off offset:1024
	ds_read_b128 v[124:127], v67 offset:26624
	ds_read_b128 v[128:131], v67 offset:30720
	s_waitcnt lgkmcnt(7)
	v_mul_f32_e32 v43, v41, v101
	v_fmac_f32_e32 v43, v40, v100
	v_fmac_f32_e32 v43, v38, v102
	v_fmac_f32_e32 v43, v39, v103
	v_add_f32_e32 v42, v49, v43
	s_waitcnt lgkmcnt(6)
	v_mul_f32_e32 v43, v41, v105
	v_fmac_f32_e32 v43, v40, v104
	v_fmac_f32_e32 v43, v38, v106
	v_fmac_f32_e32 v43, v39, v107
	ds_read_b128 v[100:103], v67 offset:34816
	v_add_f32_e32 v43, v51, v43
	s_waitcnt lgkmcnt(6)
	v_mul_f32_e32 v44, v41, v109
	v_fmac_f32_e32 v44, v40, v108
	v_fmac_f32_e32 v44, v38, v110
	v_fmac_f32_e32 v44, v39, v111
	ds_read_b128 v[104:107], v67 offset:38912
	v_add_f32_e32 v44, v60, v44
	s_waitcnt lgkmcnt(6)
	v_mul_f32_e32 v45, v41, v113
	v_fmac_f32_e32 v45, v40, v112
	v_fmac_f32_e32 v45, v38, v114
	v_fmac_f32_e32 v45, v39, v115
	ds_read_b128 v[108:111], v67 offset:43008
	v_add_f32_e32 v45, v61, v45
	s_waitcnt lgkmcnt(6)
	v_mul_f32_e32 v48, v41, v117
	v_fmac_f32_e32 v48, v40, v116
	v_fmac_f32_e32 v48, v38, v118
	v_fmac_f32_e32 v48, v39, v119
	ds_read_b128 v[112:115], v67 offset:47104
	v_add_f32_e32 v48, v68, v48
	s_waitcnt lgkmcnt(6)
	v_mul_f32_e32 v49, v41, v121
	v_fmac_f32_e32 v49, v40, v120
	v_fmac_f32_e32 v49, v38, v122
	v_fmac_f32_e32 v49, v39, v123
	ds_read_b128 v[116:119], v67 offset:51200
	v_add_f32_e32 v49, v69, v49
	s_waitcnt lgkmcnt(6)
; #define LAS __attribute__((address_space(3)))
; __device__ __forceinline__ unsigned cvt_pk_bf16(float lo, float hi) { unsigned r; asm volatile("v_cvt_pk_bf16_f32 %0, %1, %2" : "=v"(r) : "v"(lo), "v"(hi)); return r; }
; __device__ void phase_norm_alow(const Params& P, int l, int half, LAS unsigned char* lds) {
;     ...
;         for (int i = 0; i < 4; ++i) { f32x4 h = v[i] * r * gv[i];
;             u32x2 w; w.x = cvt_pk_bf16(h[0], h[1]); w.y = cvt_pk_bf16(h[2], h[3]);
;             *(u32x2*)(H + (size_t)row * DM + i * 256 + lane * 4) = w;
; #pragma unroll
;             for (int c = 0; c < 16; ++c) { const f32x4 wv = *(const LAS f32x4*)(WaT + c * 1024 + i * 256 + lane * 4); a[c] += h[0] * wv[0] + h[1] * wv[1] + h[2] * wv[2] + h[3] * wv[3]; } }
	v_mul_f32_e32 v51, v41, v125
	v_fmac_f32_e32 v51, v40, v124
	v_fmac_f32_e32 v51, v38, v126
	v_fmac_f32_e32 v51, v39, v127
	ds_read_b128 v[120:123], v67 offset:55296
	v_add_f32_e32 v51, v70, v51
	s_waitcnt lgkmcnt(6)
	v_mul_f32_e32 v60, v41, v129
	v_fmac_f32_e32 v60, v40, v128
	v_fmac_f32_e32 v60, v38, v130
	v_fmac_f32_e32 v60, v39, v131
	v_add_f32_e32 v60, v71, v60
	ds_read_b128 v[124:127], v67 offset:59392
	s_waitcnt lgkmcnt(6)
	v_mul_f32_e32 v61, v41, v101
	v_fmac_f32_e32 v61, v40, v100
	v_fmac_f32_e32 v61, v38, v102
	v_fmac_f32_e32 v61, v39, v103
	ds_read_b128 v[128:131], v67 offset:63488
	v_add_f32_e32 v61, v72, v61
	s_waitcnt lgkmcnt(6)
	v_mul_f32_e32 v69, v41, v105
	v_fmac_f32_e32 v69, v40, v104
	v_fmac_f32_e32 v69, v38, v106
	v_fmac_f32_e32 v69, v39, v107
	v_add_f32_e32 v68, v73, v69
	ds_read_b128 v[100:103], v67 offset:3072
	s_waitcnt lgkmcnt(6)
	v_mul_f32_e32 v69, v41, v109
	v_fmac_f32_e32 v69, v40, v108
	v_fmac_f32_e32 v69, v38, v110
	v_fmac_f32_e32 v69, v39, v111
	ds_read_b128 v[104:107], v67 offset:7168
	v_add_f32_e32 v69, v74, v69
	s_waitcnt lgkmcnt(6)
	v_mul_f32_e32 v71, v41, v113
	v_fmac_f32_e32 v71, v40, v112
	v_fmac_f32_e32 v71, v38, v114
	v_fmac_f32_e32 v71, v39, v115
	v_add_f32_e32 v70, v75, v71
	ds_read_b128 v[108:111], v67 offset:11264
	s_waitcnt lgkmcnt(6)
	v_mul_f32_e32 v71, v41, v117
	v_fmac_f32_e32 v71, v40, v116
	v_fmac_f32_e32 v71, v38, v118
	v_fmac_f32_e32 v71, v39, v119
	ds_read_b128 v[112:115], v67 offset:15360
	v_add_f32_e32 v71, v76, v71
	s_waitcnt lgkmcnt(6)
	v_mul_f32_e32 v73, v41, v121
	v_fmac_f32_e32 v73, v40, v120
	v_fmac_f32_e32 v73, v38, v122
	v_fmac_f32_e32 v73, v39, v123
	v_add_f32_e32 v72, v77, v73
	ds_read_b128 v[116:119], v67 offset:19456
	s_waitcnt lgkmcnt(6)
	v_mul_f32_e32 v73, v41, v125
	v_fmac_f32_e32 v73, v40, v124
	v_fmac_f32_e32 v73, v38, v126
	v_fmac_f32_e32 v73, v39, v127
	ds_read_b128 v[120:123], v67 offset:23552
	v_add_f32_e32 v73, v78, v73
	s_waitcnt lgkmcnt(6)
	v_mul_f32_e32 v41, v41, v129
	v_fmac_f32_e32 v41, v40, v128
	v_fmac_f32_e32 v41, v38, v130
	v_fmac_f32_e32 v41, v39, v131
	v_add_f32_e32 v38, v79, v41
	v_pk_mul_f32 v[40:41], v[34:35], v[58:59] op_sel_hi:[1,0]
	v_pk_mul_f32 v[34:35], v[36:37], v[58:59] op_sel_hi:[1,0]
	v_pk_mul_f32 v[36:37], v[2:3], v[40:41]
	v_pk_mul_f32 v[34:35], v[4:5], v[34:35]
	v_cvt_pk_bf16_f32 v40, v36, v37
	s_nop 0
	v_cvt_pk_bf16_f32 v41, v34, v35
	ds_read_b128 v[124:127], v67 offset:27648
	global_store_dwordx2 v[46:47], v[40:41], off offset:1536
	s_waitcnt lgkmcnt(6)
	v_mul_f32_e32 v39, v37, v101
	v_fmac_f32_e32 v39, v36, v100
	v_fmac_f32_e32 v39, v34, v102
	v_fmac_f32_e32 v39, v35, v103
	ds_read_b128 v[128:131], v67 offset:31744
	v_add_f32_e32 v39, v42, v39
	s_waitcnt lgkmcnt(6)
	v_mul_f32_e32 v40, v37, v105
	v_fmac_f32_e32 v40, v36, v104
	v_fmac_f32_e32 v40, v34, v106
	v_fmac_f32_e32 v40, v35, v107
	ds_read_b128 v[100:103], v67 offset:35840
	v_add_f32_e32 v40, v43, v40
	s_waitcnt lgkmcnt(6)
	v_mul_f32_e32 v41, v37, v109
	v_fmac_f32_e32 v41, v36, v108
	v_fmac_f32_e32 v41, v34, v110
	v_fmac_f32_e32 v41, v35, v111
	ds_read_b128 v[104:107], v67 offset:39936
	v_add_f32_e32 v41, v44, v41
	s_waitcnt lgkmcnt(6)
	v_mul_f32_e32 v42, v37, v113
	v_fmac_f32_e32 v42, v36, v112
	v_fmac_f32_e32 v42, v34, v114
	v_fmac_f32_e32 v42, v35, v115
	v_add_f32_e32 v42, v45, v42
	ds_read_b128 v[108:111], v67 offset:44032
	s_waitcnt lgkmcnt(6)
	v_mul_f32_e32 v43, v37, v117
	v_fmac_f32_e32 v43, v36, v116
	v_fmac_f32_e32 v43, v34, v118
	v_fmac_f32_e32 v43, v35, v119
	ds_read_b128 v[112:115], v67 offset:48128
	v_add_f32_e32 v43, v48, v43
	s_waitcnt lgkmcnt(6)
	v_mul_f32_e32 v45, v37, v121
	v_fmac_f32_e32 v45, v36, v120
	v_fmac_f32_e32 v45, v34, v122
	v_fmac_f32_e32 v45, v35, v123
	v_add_f32_e32 v48, v49, v45
	ds_read_b128 v[116:119], v67 offset:52224
	s_waitcnt lgkmcnt(6)
	v_mul_f32_e32 v45, v37, v125
	v_fmac_f32_e32 v45, v36, v124
	v_fmac_f32_e32 v45, v34, v126
	v_fmac_f32_e32 v45, v35, v127
	v_add_f32_e32 v49, v51, v45
	ds_read_b128 v[120:123], v67 offset:56320
	s_waitcnt lgkmcnt(6)
	v_mul_f32_e32 v45, v37, v129
	v_fmac_f32_e32 v45, v36, v128
	v_fmac_f32_e32 v45, v34, v130
	v_fmac_f32_e32 v45, v35, v131
	v_add_f32_e32 v51, v60, v45
	ds_read_b128 v[124:127], v67 offset:60416
	s_waitcnt lgkmcnt(6)
; #define LAS __attribute__((address_space(3)))
; __device__ __forceinline__ unsigned cvt_pk_bf16(float lo, float hi) { unsigned r; asm volatile("v_cvt_pk_bf16_f32 %0, %1, %2" : "=v"(r) : "v"(lo), "v"(hi)); return r; }
; __device__ void phase_norm_alow(const Params& P, int l, int half, LAS unsigned char* lds) {
;     ...
;         for (int i = 0; i < 4; ++i) { f32x4 h = v[i] * r * gv[i];
;             u32x2 w; w.x = cvt_pk_bf16(h[0], h[1]); w.y = cvt_pk_bf16(h[2], h[3]);
;             *(u32x2*)(H + (size_t)row * DM + i * 256 + lane * 4) = w;
; #pragma unroll
;             for (int c = 0; c < 16; ++c) { const f32x4 wv = *(const LAS f32x4*)(WaT + c * 1024 + i * 256 + lane * 4); a[c] += h[0] * wv[0] + h[1] * wv[1] + h[2] * wv[2] + h[3] * wv[3]; } }
;         float b8[8], b4[4], b2[2], b1;
;         { const bool up = (lane & 32) != 0;
; #pragma unroll
;           for (int c = 0; c < 8; ++c) { const float keep = up ? a[c + 8] : a[c], send = up ? a[c] : a[c + 8]; b8[c] = keep + __shfl_xor(send, 32); } }
;         { const bool up = (lane & 16) != 0;
; #pragma unroll
;           for (int c = 0; c < 4; ++c) { const float keep = up ? b8[c + 4] : b8[c], send = up ? b8[c] : b8[c + 4]; b4[c] = keep + __shfl_xor(send, 16); } }
;         { const bool up = (lane & 8) != 0;
; #pragma unroll
;           for (int c = 0; c < 2; ++c) { const float keep = up ? b4[c + 2] : b4[c], send = up ? b4[c] : b4[c + 2]; b2[c] = keep + __shfl_xor(send, 8); } }
;         { const bool up = (lane & 4) != 0; const float keep = up ? b2[1] : b2[0], send = up ? b2[0] : b2[1]; b1 = keep + __shfl_xor(send, 4); }
;         b1 += __shfl_xor(b1, 2); b1 += __shfl_xor(b1, 1);
;         if ((lane & 3) == 0) { const int co = ((lane >> 5) & 1) * 8 + ((lane >> 4) & 1) * 4 + ((lane >> 3) & 1) * 2 + ((lane >> 2) & 1); AL[(size_t)row * 16 + co] = b1; }
	v_mul_f32_e32 v45, v37, v101
	v_fmac_f32_e32 v45, v36, v100
	v_fmac_f32_e32 v45, v34, v102
	v_fmac_f32_e32 v45, v35, v103
	v_add_f32_e32 v58, v61, v45
	ds_read_b128 v[128:131], v67 offset:64512
	s_waitcnt lgkmcnt(6)
	v_mul_f32_e32 v45, v37, v105
	v_fmac_f32_e32 v45, v36, v104
	v_fmac_f32_e32 v45, v34, v106
	v_fmac_f32_e32 v45, v35, v107
	v_add_f32_e32 v60, v68, v45
	s_waitcnt lgkmcnt(5)
	v_mul_f32_e32 v45, v37, v109
	v_fmac_f32_e32 v45, v36, v108
	v_fmac_f32_e32 v45, v34, v110
	v_fmac_f32_e32 v45, v35, v111
	v_add_f32_e32 v61, v69, v45
	s_waitcnt lgkmcnt(4)
	v_mul_f32_e32 v45, v37, v113
	v_fmac_f32_e32 v45, v36, v112
	v_fmac_f32_e32 v45, v34, v114
	v_fmac_f32_e32 v45, v35, v115
	v_add_f32_e32 v68, v70, v45
	s_waitcnt lgkmcnt(3)
	v_mul_f32_e32 v45, v37, v117
	v_fmac_f32_e32 v45, v36, v116
	v_fmac_f32_e32 v45, v34, v118
	v_fmac_f32_e32 v45, v35, v119
	v_add_f32_e32 v69, v71, v45
	s_waitcnt lgkmcnt(2)
	v_mul_f32_e32 v45, v37, v121
	v_fmac_f32_e32 v45, v36, v120
	v_fmac_f32_e32 v45, v34, v122
	v_fmac_f32_e32 v45, v35, v123
	v_add_f32_e32 v70, v72, v45
	s_waitcnt lgkmcnt(1)
	v_mul_f32_e32 v45, v37, v125
	v_fmac_f32_e32 v45, v36, v124
	v_fmac_f32_e32 v45, v34, v126
	v_fmac_f32_e32 v45, v35, v127
	v_add_f32_e32 v71, v73, v45
	s_waitcnt lgkmcnt(0)
	v_mul_f32_e32 v37, v37, v129
	v_fmac_f32_e32 v37, v36, v128
	v_fmac_f32_e32 v37, v34, v130
	v_fmac_f32_e32 v37, v35, v131
	v_cndmask_b32_e32 v36, v39, v58, vcc
	v_add_f32_e32 v34, v38, v37
	ds_bpermute_b32 v36, v59, v36
	v_cndmask_b32_e32 v37, v40, v60, vcc
	ds_bpermute_b32 v37, v59, v37
	v_cndmask_b32_e32 v38, v41, v61, vcc
	ds_bpermute_b32 v38, v59, v38
	v_cndmask_b32_e32 v35, v58, v39, vcc
	v_cndmask_b32_e32 v39, v42, v68, vcc
	s_waitcnt lgkmcnt(2)
	v_add_f32_e32 v35, v35, v36
	v_cndmask_b32_e32 v36, v60, v40, vcc
	ds_bpermute_b32 v39, v59, v39
	v_cndmask_b32_e32 v40, v43, v69, vcc
	s_waitcnt lgkmcnt(2)
	v_add_f32_e32 v36, v36, v37
	v_cndmask_b32_e32 v37, v61, v41, vcc
	ds_bpermute_b32 v40, v59, v40
	v_cndmask_b32_e32 v41, v48, v70, vcc
	s_waitcnt lgkmcnt(2)
	v_add_f32_e32 v37, v37, v38
	v_cndmask_b32_e32 v38, v68, v42, vcc
	ds_bpermute_b32 v41, v59, v41
	v_cndmask_b32_e32 v42, v49, v71, vcc
	ds_bpermute_b32 v42, v59, v42
	s_waitcnt lgkmcnt(3)
	v_add_f32_e32 v38, v38, v39
	v_cndmask_b32_e32 v39, v69, v43, vcc
	s_waitcnt lgkmcnt(2)
	v_add_f32_e32 v39, v39, v40
	v_cndmask_b32_e32 v40, v70, v48, vcc
	s_waitcnt lgkmcnt(1)
	v_add_f32_e32 v40, v40, v41
	v_cndmask_b32_e32 v41, v71, v49, vcc
	s_waitcnt lgkmcnt(0)
	v_add_f32_e32 v41, v41, v42
	v_cndmask_b32_e32 v42, v34, v51, vcc
	v_cndmask_b32_e32 v34, v51, v34, vcc
	ds_bpermute_b32 v34, v59, v34
	s_waitcnt lgkmcnt(0)
	v_add_f32_e32 v34, v42, v34
	v_cndmask_b32_e64 v42, v39, v35, s[36:37]
	v_cndmask_b32_e64 v35, v35, v39, s[36:37]
	v_cndmask_b32_e64 v39, v40, v36, s[36:37]
	v_cndmask_b32_e64 v36, v36, v40, s[36:37]
	ds_bpermute_b32 v36, v62, v36
	ds_bpermute_b32 v35, v62, v35
	s_waitcnt lgkmcnt(1)
	v_add_f32_e32 v36, v39, v36
	v_cndmask_b32_e64 v39, v41, v37, s[36:37]
	v_cndmask_b32_e64 v37, v37, v41, s[36:37]
	ds_bpermute_b32 v37, v62, v37
	s_waitcnt lgkmcnt(1)
	v_add_f32_e32 v35, v42, v35
	s_waitcnt lgkmcnt(0)
	v_add_f32_e32 v37, v39, v37
	v_cndmask_b32_e64 v39, v34, v38, s[36:37]
	v_cndmask_b32_e64 v34, v38, v34, s[36:37]
	ds_bpermute_b32 v34, v62, v34
	v_cndmask_b32_e64 v38, v37, v35, s[38:39]
	v_cndmask_b32_e64 v35, v35, v37, s[38:39]
	ds_bpermute_b32 v35, v63, v35
	s_waitcnt lgkmcnt(1)
	v_add_f32_e32 v34, v39, v34
	v_cndmask_b32_e64 v37, v34, v36, s[38:39]
	v_cndmask_b32_e64 v34, v36, v34, s[38:39]
	ds_bpermute_b32 v34, v63, v34
	s_waitcnt lgkmcnt(1)
	v_add_f32_e32 v35, v38, v35
	s_waitcnt lgkmcnt(0)
	v_add_f32_e32 v34, v37, v34
	v_cndmask_b32_e64 v36, v34, v35, s[40:41]
	v_cndmask_b32_e64 v34, v35, v34, s[40:41]
	ds_bpermute_b32 v34, v64, v34
	s_waitcnt lgkmcnt(0)
	v_add_f32_e32 v34, v36, v34
	s_nop 1
	v_mov_b32_dpp v35, v34 quad_perm:[2,3,0,1] row_mask:0xf bank_mask:0xf
	s_waitcnt lgkmcnt(0)
	v_add_f32_e32 v34, v34, v35
	s_nop 1
	v_mov_b32_dpp v35, v34 quad_perm:[1,0,3,2] row_mask:0xf bank_mask:0xf
	s_and_saveexec_b64 s[0:1], s[42:43]
	s_cbranch_execz .LBB0_239
	v_lshl_add_u64 v[36:37], s[74:75], 0, v[52:53]
	s_waitcnt lgkmcnt(0)
	v_add_f32_e32 v34, v34, v35
	global_store_dword v[36:37], v34, off
	s_branch .LBB0_239

; __device__ __forceinline__ float bflo(unsigned w) { return __uint_as_float(w << 16); }
; __device__ __forceinline__ float bfhi(unsigned w) { return __uint_as_float(w & 0xffff0000u); }
; __device__ void phase_resid(const float* xin, float* xout, const bf16_t* Y, const float* pg, const float* ng, bf16_t* H2, int nrows) {
;     ...
;     for (; row < nrows; row += stride) {
;         f32x4 y[4], xv[4];
; #pragma unroll
;         for (int i = 0; i < 4; ++i) { y[i] = (f32x4){bflo(ny[i].x), bfhi(ny[i].x), bflo(ny[i].y), bfhi(ny[i].y)}; xv[i] = nx[i]; }
;         const int rn = row + stride;
;         if (rn < nrows) {
; #pragma unroll
;             for (int i = 0; i < 4; ++i) { ny[i] = *(const u32x2*)(Y + (size_t)rn * DM + i * 256 + lane * 4); nx[i] = *(const f32x4*)(xin + (size_t)rn * DM + i * 256 + lane * 4); }
;         }
;         float ss = 0.f;
; #pragma unroll
;         for (int i = 0; i < 4; ++i) ss += y[i][0] * y[i][0] + y[i][1] * y[i][1] + y[i][2] * y[i][2] + y[i][3] * y[i][3];
;         ss = wave_sum(ss);
;         const float r = rsqrtf(ss * (1.0f / DM) + EPS);
;         float s2 = 0.f;
; #pragma unroll
;         for (int i = 0; i < 4; ++i) { xv[i] = xv[i] + y[i] * r * pgv[i]; *(f32x4*)(xout + (size_t)row * DM + i * 256 + lane * 4) = xv[i];
;             s2 += xv[i][0] * xv[i][0] + xv[i][1] * xv[i][1] + xv[i][2] * xv[i][2] + xv[i][3] * xv[i][3]; }
.LBB0_609:
	s_or_b64 exec, exec, s[38:39]
	v_and_b32_e32 v83, 0xffff0000, v72
	v_and_b32_e32 v82, 0xffff0000, v70
	v_lshlrev_b32_e32 v81, 16, v72
	v_lshlrev_b32_e32 v80, 16, v70
	v_lshlrev_b32_e32 v84, 16, v71
	v_and_b32_e32 v72, 0xffff0000, v71
	v_lshlrev_b32_e32 v71, 16, v68
	v_lshlrev_b32_e32 v70, 16, v66
	s_waitcnt lgkmcnt(1)
	v_and_b32_e32 v87, 0xffff0000, v68
	v_and_b32_e32 v86, 0xffff0000, v66
	v_lshlrev_b32_e32 v88, 16, v67
	v_and_b32_e32 v68, 0xffff0000, v67
	v_pk_mul_f32 v[66:67], v[82:83], v[82:83]
	v_lshlrev_b32_e32 v85, 16, v73
	v_pk_fma_f32 v[66:67], v[80:81], v[80:81], v[66:67]
	v_pk_mul_f32 v[90:91], v[86:87], v[86:87]
	v_and_b32_e32 v73, 0xffff0000, v73
	v_lshlrev_b32_e32 v89, 16, v69
	v_pk_fma_f32 v[66:67], v[84:85], v[84:85], v[66:67]
	v_pk_fma_f32 v[90:91], v[70:71], v[70:71], v[90:91]
	v_and_b32_e32 v69, 0xffff0000, v69
	v_pk_fma_f32 v[66:67], v[72:73], v[72:73], v[66:67]
	v_pk_fma_f32 v[90:91], v[88:89], v[88:89], v[90:91]
	v_add_f32_e32 v66, v66, v67
	v_pk_fma_f32 v[90:91], v[68:69], v[68:69], v[90:91]
	s_and_b64 s[0:1], exec, vcc
	v_add_f32_e32 v66, v66, v90
	v_add_f32_e32 v66, v66, v91
	v_mov_b32_e32 v67, v66
	s_nop 1
	v_permlane32_swap_b32_e32 v67, v66
	s_nop 1
	v_mov_b32_e32 v90, v80
	v_mov_b32_e32 v93, v72
	v_mov_b32_e32 v92, v84
	s_or_b64 s[36:37], s[0:1], s[36:37]
	s_waitcnt lgkmcnt(0)
	v_add_f32_e32 v66, v66, v67
	v_mov_b32_e32 v67, v66
	s_nop 1
	v_permlane16_swap_b32_e32 v67, v66
	s_nop 1
	v_lshl_add_u64 v[56:57], v[56:57], 0, s[22:23]
	v_lshl_add_u64 v[54:55], v[54:55], 0, s[70:71]
	s_waitcnt lgkmcnt(0)
	v_add_f32_e32 v66, v66, v67
	s_nop 1
	v_mov_b32_dpp v67, v66 row_ror:8 row_mask:0xf bank_mask:0xf
	s_waitcnt lgkmcnt(0)
	v_add_f32_e32 v66, v66, v67
	s_nop 1
	v_mov_b32_dpp v67, v66 row_shl:4 row_mask:0xf bank_mask:0x5
	s_nop 1
	v_mov_b32_dpp v67, v66 row_shr:4 row_mask:0xf bank_mask:0xa
	s_waitcnt lgkmcnt(0)
	v_add_f32_e32 v66, v66, v67
	ds_bpermute_b32 v67, v77, v66
	s_waitcnt lgkmcnt(0)
	v_add_f32_e32 v79, v66, v67
	s_nop 1
	v_mov_b32_dpp v91, v79 quad_perm:[1,0,3,2] row_mask:0xf bank_mask:0xf
	v_lshl_add_u64 v[66:67], v[52:53], 0, v[194:195]
	v_lshl_add_u64 v[52:53], v[52:53], 0, s[70:71]
	s_waitcnt lgkmcnt(0)
	v_add_f32_e32 v79, v79, v91
	v_fmamk_f32 v79, v79, 0x3a800000, v1
	v_mul_f32_e32 v80, 0x4b800000, v79
	v_cmp_gt_f32_e32 vcc, s33, v79
	v_mov_b32_e32 v91, v82
	v_mov_b32_e32 v82, v81
	v_cndmask_b32_e32 v79, v79, v80, vcc
	v_rsq_f32_e32 v79, v79
	s_nop 0
	v_mul_f32_e32 v72, 0x45800000, v79
	v_cndmask_b32_e32 v80, v79, v72, vcc
	v_pk_mul_f32 v[90:91], v[80:81], v[90:91] op_sel_hi:[0,1]
	v_pk_mul_f32 v[92:93], v[80:81], v[92:93] op_sel_hi:[0,1]
	v_pk_fma_f32 v[32:33], v[4:5], v[92:93], v[32:33]
	v_pk_fma_f32 v[30:31], v[2:3], v[90:91], v[30:31]
	v_mov_b32_e32 v72, v85
	global_store_dwordx4 v[66:67], v[30:33], off
	s_nop 1
	v_pk_mul_f32 v[30:31], v[80:81], v[82:83] op_sel_hi:[0,1]
	v_pk_mul_f32 v[32:33], v[80:81], v[72:73] op_sel_hi:[0,1]
	v_pk_fma_f32 v[28:29], v[8:9], v[32:33], v[28:29]
	v_pk_fma_f32 v[26:27], v[6:7], v[30:31], v[26:27]
	global_store_dwordx4 v[66:67], v[26:29], off offset:1024
	s_waitcnt vmcnt(9)
	v_mov_b64_e32 v[30:31], v[34:35]
	v_mov_b64_e32 v[32:33], v[36:37]
	v_mov_b32_e32 v26, v70
	v_mov_b32_e32 v27, v86
	v_mov_b32_e32 v28, v88
	v_mov_b32_e32 v29, v68
	v_pk_mul_f32 v[26:27], v[80:81], v[26:27] op_sel_hi:[0,1]
	v_pk_mul_f32 v[28:29], v[80:81], v[28:29] op_sel_hi:[0,1]
	s_waitcnt vmcnt(3)
	v_pk_fma_f32 v[24:25], v[12:13], v[28:29], v[24:25]
	v_pk_fma_f32 v[22:23], v[10:11], v[26:27], v[22:23]
	v_mov_b32_e32 v86, v71
	v_mov_b32_e32 v68, v89
	global_store_dwordx4 v[66:67], v[22:25], off offset:2048
	v_mov_b64_e32 v[26:27], v[38:39]
	v_mov_b64_e32 v[28:29], v[40:41]
	v_pk_mul_f32 v[22:23], v[80:81], v[86:87] op_sel_hi:[0,1]
	v_pk_mul_f32 v[24:25], v[80:81], v[68:69] op_sel_hi:[0,1]
	s_waitcnt vmcnt(3)
	v_pk_fma_f32 v[20:21], v[16:17], v[24:25], v[20:21]
	v_pk_fma_f32 v[18:19], v[14:15], v[22:23], v[18:19]
	global_store_dwordx4 v[66:67], v[18:21], off offset:3072
	v_mov_b64_e32 v[22:23], v[46:47]
	v_mov_b64_e32 v[24:25], v[48:49]
	v_mov_b64_e32 v[18:19], v[42:43]
	v_mov_b64_e32 v[20:21], v[44:45]
	v_mov_b64_e32 v[70:71], v[58:59]
	v_mov_b64_e32 v[72:73], v[60:61]
	v_mov_b64_e32 v[66:67], v[62:63]
	v_mov_b64_e32 v[68:69], v[64:65]
	s_andn2_b64 exec, exec, s[36:37]
	s_cbranch_execz .LBB0_612

; #define LAS __attribute__((address_space(3)))
; __device__ __forceinline__ unsigned cvt_pk_bf16(float lo, float hi) { unsigned r; asm volatile("v_cvt_pk_bf16_f32 %0, %1, %2" : "=v"(r) : "v"(lo), "v"(hi)); return r; }
; __device__ __forceinline__ float wave_sum(float v) {
; #pragma unroll
;     for (int o = 32; o >= 1; o >>= 1) v += __shfl_xor(v, o);
;     return v;
; }
; __device__ void phase_norm_alow(const Params& P, int l, int half, LAS unsigned char* lds) {
;     ...
;         f32x4 v[4]; float ss = 0.f;
; #pragma unroll
;         for (int i = 0; i < 4; ++i) { v[i] = nv[i]; ss += v[i][0] * v[i][0] + v[i][1] * v[i][1] + v[i][2] * v[i][2] + v[i][3] * v[i][3]; }
;         if (row + rstride < TH) {
; #pragma unroll
;             for (int i = 0; i < 4; ++i) nv[i] = *(const f32x4*)(xs + (size_t)(row + rstride) * DM + i * 256 + lane * 4);
;         }
;         ss = wave_sum(ss);
;         const float r = rsqrtf(ss * (1.0f / DM) + EPS);
;         float a[16];
; #pragma unroll
;         for (int c = 0; c < 16; ++c) a[c] = 0.f;
; #pragma unroll
;         for (int i = 0; i < 4; ++i) { f32x4 h = v[i] * r * gv[i];
;             u32x2 w; w.x = cvt_pk_bf16(h[0], h[1]); w.y = cvt_pk_bf16(h[2], h[3]);
;             *(u32x2*)(H + (size_t)row * DM + i * 256 + lane * 4) = w;
; #pragma unroll
;             for (int c = 0; c < 16; ++c) { const f32x4 wv = *(const LAS f32x4*)(WaT + c * 1024 + i * 256 + lane * 4); a[c] += h[0] * wv[0] + h[1] * wv[1] + h[2] * wv[2] + h[3] * wv[3]; } }
.LBB0_680:
	s_or_b64 exec, exec, s[30:31]
	v_mul_f32_e32 v51, v47, v47
	v_mul_f32_e32 v58, v43, v43
	v_fmac_f32_e32 v51, v46, v46
	v_fmac_f32_e32 v58, v42, v42
	v_fmac_f32_e32 v51, v48, v48
	v_fmac_f32_e32 v58, v44, v44
	v_fmac_f32_e32 v51, v49, v49
	v_fmac_f32_e32 v58, v45, v45
	v_add_f32_e32 v51, v51, v58
	v_mul_f32_e32 v58, v39, v39
	v_fmac_f32_e32 v58, v38, v38
	v_fmac_f32_e32 v58, v40, v40
	v_fmac_f32_e32 v58, v41, v41
	v_add_f32_e32 v51, v51, v58
	v_mul_f32_e32 v58, v35, v35
	v_fmac_f32_e32 v58, v34, v34
	v_fmac_f32_e32 v58, v36, v36
	v_fmac_f32_e32 v58, v37, v37
	v_add_f32_e32 v51, v51, v58
	v_mov_b32_e32 v58, v51
	s_nop 1
	v_permlane32_swap_b32_e32 v58, v51
	s_nop 1
	v_lshl_add_u64 v[68:69], s[74:75], 0, v[56:57]
	s_waitcnt lgkmcnt(0)
	v_add_f32_e32 v51, v51, v58
	v_mov_b32_e32 v58, v51
	s_nop 1
	v_permlane16_swap_b32_e32 v58, v51
	s_nop 1
	s_waitcnt lgkmcnt(0)
	v_add_f32_e32 v51, v51, v58
	s_nop 1
	v_mov_b32_dpp v58, v51 row_ror:8 row_mask:0xf bank_mask:0xf
	s_waitcnt lgkmcnt(0)
	v_add_f32_e32 v51, v51, v58
	s_nop 1
	v_mov_b32_dpp v58, v51 row_shl:4 row_mask:0xf bank_mask:0x5
	s_nop 1
	v_mov_b32_dpp v58, v51 row_shr:4 row_mask:0xf bank_mask:0xa
	s_waitcnt lgkmcnt(0)
	v_add_f32_e32 v51, v51, v58
	s_nop 1
	v_mov_b32_dpp v58, v51 quad_perm:[2,3,0,1] row_mask:0xf bank_mask:0xf
	s_waitcnt lgkmcnt(0)
	v_add_f32_e32 v51, v51, v58
	s_nop 1
	v_mov_b32_dpp v58, v51 quad_perm:[1,0,3,2] row_mask:0xf bank_mask:0xf
	s_waitcnt lgkmcnt(0)
	v_add_f32_e32 v51, v51, v58
	v_fmamk_f32 v51, v51, 0x3a800000, v1
	v_cmp_gt_f32_e64 s[0:1], s33, v51
	v_mul_f32_e32 v58, 0x4b800000, v51
	s_nop 0
	v_cndmask_b32_e64 v51, v51, v58, s[0:1]
	v_rsq_f32_e32 v51, v51
	s_nop 0
	v_mul_f32_e32 v58, 0x45800000, v51
	v_cndmask_b32_e64 v58, v51, v58, s[0:1]
	v_pk_mul_f32 v[46:47], v[46:47], v[58:59] op_sel_hi:[1,0]
	s_mov_b32 s0, 0x3a88000
	v_pk_mul_f32 v[48:49], v[48:49], v[58:59] op_sel_hi:[1,0]
	v_pk_mul_f32 v[60:61], v[14:15], v[46:47]
	v_add_co_u32_e64 v46, s[0:1], s0, v68
	v_pk_mul_f32 v[48:49], v[16:17], v[48:49]
	v_cvt_pk_bf16_f32 v70, v60, v61
	s_nop 0
	v_addc_co_u32_e64 v47, s[0:1], 0, v69, s[0:1]
	v_cvt_pk_bf16_f32 v71, v48, v49
	global_store_dwordx2 v[46:47], v[70:71], off
	ds_read_b128 v[100:103], v67
	ds_read_b128 v[104:107], v67 offset:4096
	ds_read_b128 v[108:111], v67 offset:8192
	ds_read_b128 v[112:115], v67 offset:12288
	ds_read_b128 v[116:119], v67 offset:16384
	ds_read_b128 v[120:123], v67 offset:20480
	ds_read_b128 v[124:127], v67 offset:24576
	s_waitcnt lgkmcnt(6)
	v_mul_f32_e32 v51, v101, v61
	v_fmac_f32_e32 v51, v100, v60
	v_fmac_f32_e32 v51, v102, v48
	v_fmac_f32_e32 v51, v103, v49
	ds_read_b128 v[128:131], v67 offset:28672
	v_add_f32_e32 v69, 0, v51
	s_waitcnt lgkmcnt(6)
	v_mul_f32_e32 v51, v105, v61
	v_fmac_f32_e32 v51, v104, v60
	v_fmac_f32_e32 v51, v106, v48
	v_fmac_f32_e32 v51, v107, v49
	ds_read_b128 v[100:103], v67 offset:32768
	v_add_f32_e32 v51, 0, v51
	s_waitcnt lgkmcnt(6)
	v_mul_f32_e32 v68, v109, v61
	v_fmac_f32_e32 v68, v108, v60
	v_fmac_f32_e32 v68, v110, v48
	v_fmac_f32_e32 v68, v111, v49
	ds_read_b128 v[104:107], v67 offset:36864
	v_add_f32_e32 v68, 0, v68
	s_waitcnt lgkmcnt(6)
	v_mul_f32_e32 v71, v113, v61
	v_fmac_f32_e32 v71, v112, v60
	v_fmac_f32_e32 v71, v114, v48
	v_fmac_f32_e32 v71, v115, v49
	ds_read_b128 v[108:111], v67 offset:40960
	v_add_f32_e32 v70, 0, v71
	s_waitcnt lgkmcnt(6)
	v_mul_f32_e32 v71, v117, v61
	v_fmac_f32_e32 v71, v116, v60
	v_fmac_f32_e32 v71, v118, v48
	v_fmac_f32_e32 v71, v119, v49
	ds_read_b128 v[112:115], v67 offset:45056
	v_add_f32_e32 v71, 0, v71
	s_waitcnt lgkmcnt(6)
	v_mul_f32_e32 v73, v121, v61
	v_fmac_f32_e32 v73, v120, v60
	v_fmac_f32_e32 v73, v122, v48
	v_fmac_f32_e32 v73, v123, v49
	ds_read_b128 v[116:119], v67 offset:49152
	v_add_f32_e32 v72, 0, v73
	s_waitcnt lgkmcnt(6)
	v_mul_f32_e32 v73, v125, v61
	v_fmac_f32_e32 v73, v124, v60
	v_fmac_f32_e32 v73, v126, v48
	v_fmac_f32_e32 v73, v127, v49
	ds_read_b128 v[120:123], v67 offset:53248
	v_add_f32_e32 v73, 0, v73
	s_waitcnt lgkmcnt(6)
	v_mul_f32_e32 v75, v129, v61
	v_fmac_f32_e32 v75, v128, v60
	v_fmac_f32_e32 v75, v130, v48
	v_fmac_f32_e32 v75, v131, v49
	ds_read_b128 v[124:127], v67 offset:57344
	v_add_f32_e32 v74, 0, v75
	s_waitcnt lgkmcnt(6)
	v_mul_f32_e32 v75, v101, v61
	v_fmac_f32_e32 v75, v100, v60
	v_fmac_f32_e32 v75, v102, v48
	v_fmac_f32_e32 v75, v103, v49
	ds_read_b128 v[128:131], v67 offset:61440
	v_add_f32_e32 v75, 0, v75
	s_waitcnt lgkmcnt(6)
	v_mul_f32_e32 v77, v61, v105
	v_fmac_f32_e32 v77, v60, v104
	v_fmac_f32_e32 v77, v48, v106
	v_fmac_f32_e32 v77, v49, v107
	ds_read_b128 v[100:103], v67 offset:1024
	v_add_f32_e32 v76, 0, v77
	s_waitcnt lgkmcnt(6)
	v_mul_f32_e32 v77, v61, v109
	v_fmac_f32_e32 v77, v60, v108
	v_fmac_f32_e32 v77, v48, v110
	v_fmac_f32_e32 v77, v49, v111
	ds_read_b128 v[104:107], v67 offset:5120
	v_add_f32_e32 v77, 0, v77
	s_waitcnt lgkmcnt(6)
	v_mul_f32_e32 v79, v61, v113
	v_fmac_f32_e32 v79, v60, v112
	v_fmac_f32_e32 v79, v48, v114
	v_fmac_f32_e32 v79, v49, v115
	ds_read_b128 v[108:111], v67 offset:9216
	v_add_f32_e32 v78, 0, v79
	s_waitcnt lgkmcnt(6)
	v_mul_f32_e32 v79, v61, v117
	v_fmac_f32_e32 v79, v60, v116
	v_fmac_f32_e32 v79, v48, v118
	v_fmac_f32_e32 v79, v49, v119
	ds_read_b128 v[112:115], v67 offset:13312
	v_add_f32_e32 v79, 0, v79
	s_waitcnt lgkmcnt(6)
	v_mul_f32_e32 v81, v61, v121
	v_fmac_f32_e32 v81, v60, v120
	v_fmac_f32_e32 v81, v48, v122
	v_fmac_f32_e32 v81, v49, v123
	ds_read_b128 v[116:119], v67 offset:17408
	v_add_f32_e32 v80, 0, v81
	s_waitcnt lgkmcnt(6)
	v_mul_f32_e32 v81, v61, v125
	v_fmac_f32_e32 v81, v60, v124
	v_fmac_f32_e32 v81, v48, v126
	v_fmac_f32_e32 v81, v49, v127
	ds_read_b128 v[120:123], v67 offset:21504
	v_add_f32_e32 v81, 0, v81
	s_waitcnt lgkmcnt(6)
; #define LAS __attribute__((address_space(3)))
; __device__ __forceinline__ unsigned cvt_pk_bf16(float lo, float hi) { unsigned r; asm volatile("v_cvt_pk_bf16_f32 %0, %1, %2" : "=v"(r) : "v"(lo), "v"(hi)); return r; }
; __device__ void phase_norm_alow(const Params& P, int l, int half, LAS unsigned char* lds) {
;     ...
;         for (int i = 0; i < 4; ++i) { f32x4 h = v[i] * r * gv[i];
;             u32x2 w; w.x = cvt_pk_bf16(h[0], h[1]); w.y = cvt_pk_bf16(h[2], h[3]);
;             *(u32x2*)(H + (size_t)row * DM + i * 256 + lane * 4) = w;
; #pragma unroll
;             for (int c = 0; c < 16; ++c) { const f32x4 wv = *(const LAS f32x4*)(WaT + c * 1024 + i * 256 + lane * 4); a[c] += h[0] * wv[0] + h[1] * wv[1] + h[2] * wv[2] + h[3] * wv[3]; } }
	v_mul_f32_e32 v61, v61, v129
	v_fmac_f32_e32 v61, v60, v128
	v_fmac_f32_e32 v61, v48, v130
	v_fmac_f32_e32 v61, v49, v131
	v_add_f32_e32 v48, 0, v61
	v_pk_mul_f32 v[60:61], v[42:43], v[58:59] op_sel_hi:[1,0]
	v_pk_mul_f32 v[42:43], v[44:45], v[58:59] op_sel_hi:[1,0]
	v_pk_mul_f32 v[44:45], v[10:11], v[60:61]
	v_pk_mul_f32 v[42:43], v[12:13], v[42:43]
	v_cvt_pk_bf16_f32 v60, v44, v45
	s_nop 0
	v_cvt_pk_bf16_f32 v61, v42, v43
	ds_read_b128 v[124:127], v67 offset:25600
	global_store_dwordx2 v[46:47], v[60:61], off offset:512
	s_waitcnt lgkmcnt(6)
	v_mul_f32_e32 v49, v45, v101
	v_fmac_f32_e32 v49, v44, v100
	v_fmac_f32_e32 v49, v42, v102
	v_fmac_f32_e32 v49, v43, v103
	ds_read_b128 v[128:131], v67 offset:29696
	v_add_f32_e32 v49, v69, v49
	s_waitcnt lgkmcnt(6)
	v_mul_f32_e32 v60, v45, v105
	v_fmac_f32_e32 v60, v44, v104
	v_fmac_f32_e32 v60, v42, v106
	v_fmac_f32_e32 v60, v43, v107
	ds_read_b128 v[100:103], v67 offset:33792
	v_add_f32_e32 v51, v51, v60
	s_waitcnt lgkmcnt(6)
	v_mul_f32_e32 v60, v45, v109
	v_fmac_f32_e32 v60, v44, v108
	v_fmac_f32_e32 v60, v42, v110
	v_fmac_f32_e32 v60, v43, v111
	ds_read_b128 v[104:107], v67 offset:37888
	v_add_f32_e32 v60, v68, v60
	s_waitcnt lgkmcnt(6)
	v_mul_f32_e32 v61, v45, v113
	v_fmac_f32_e32 v61, v44, v112
	v_fmac_f32_e32 v61, v42, v114
	v_fmac_f32_e32 v61, v43, v115
	ds_read_b128 v[108:111], v67 offset:41984
	v_add_f32_e32 v61, v70, v61
	s_waitcnt lgkmcnt(6)
	v_mul_f32_e32 v68, v45, v117
	v_fmac_f32_e32 v68, v44, v116
	v_fmac_f32_e32 v68, v42, v118
	v_fmac_f32_e32 v68, v43, v119
	ds_read_b128 v[112:115], v67 offset:46080
	v_add_f32_e32 v68, v71, v68
	s_waitcnt lgkmcnt(6)
	v_mul_f32_e32 v69, v45, v121
	v_fmac_f32_e32 v69, v44, v120
	v_fmac_f32_e32 v69, v42, v122
	v_fmac_f32_e32 v69, v43, v123
	ds_read_b128 v[116:119], v67 offset:50176
	v_add_f32_e32 v69, v72, v69
	s_waitcnt lgkmcnt(6)
	v_mul_f32_e32 v70, v45, v125
	v_fmac_f32_e32 v70, v44, v124
	v_fmac_f32_e32 v70, v42, v126
	v_fmac_f32_e32 v70, v43, v127
	ds_read_b128 v[120:123], v67 offset:54272
	v_add_f32_e32 v70, v73, v70
	s_waitcnt lgkmcnt(6)
	v_mul_f32_e32 v71, v45, v129
	v_fmac_f32_e32 v71, v44, v128
	v_fmac_f32_e32 v71, v42, v130
	v_fmac_f32_e32 v71, v43, v131
	ds_read_b128 v[124:127], v67 offset:58368
	v_add_f32_e32 v71, v74, v71
	s_waitcnt lgkmcnt(6)
	v_mul_f32_e32 v72, v45, v101
	v_fmac_f32_e32 v72, v44, v100
	v_fmac_f32_e32 v72, v42, v102
	v_fmac_f32_e32 v72, v43, v103
	ds_read_b128 v[128:131], v67 offset:62464
	v_add_f32_e32 v72, v75, v72
	s_waitcnt lgkmcnt(6)
	v_mul_f32_e32 v73, v45, v105
	v_fmac_f32_e32 v73, v44, v104
	v_fmac_f32_e32 v73, v42, v106
	v_fmac_f32_e32 v73, v43, v107
	ds_read_b128 v[100:103], v67 offset:2048
	v_add_f32_e32 v73, v76, v73
	s_waitcnt lgkmcnt(6)
	v_mul_f32_e32 v74, v45, v109
	v_fmac_f32_e32 v74, v44, v108
	v_fmac_f32_e32 v74, v42, v110
	v_fmac_f32_e32 v74, v43, v111
	ds_read_b128 v[104:107], v67 offset:6144
	v_add_f32_e32 v74, v77, v74
	s_waitcnt lgkmcnt(6)
	v_mul_f32_e32 v75, v45, v113
	v_fmac_f32_e32 v75, v44, v112
	v_fmac_f32_e32 v75, v42, v114
	v_fmac_f32_e32 v75, v43, v115
	ds_read_b128 v[108:111], v67 offset:10240
	v_add_f32_e32 v75, v78, v75
	s_waitcnt lgkmcnt(6)
	v_mul_f32_e32 v76, v45, v117
	v_fmac_f32_e32 v76, v44, v116
	v_fmac_f32_e32 v76, v42, v118
	v_fmac_f32_e32 v76, v43, v119
	ds_read_b128 v[112:115], v67 offset:14336
	v_add_f32_e32 v76, v79, v76
	s_waitcnt lgkmcnt(6)
	v_mul_f32_e32 v77, v45, v121
	v_fmac_f32_e32 v77, v44, v120
	v_fmac_f32_e32 v77, v42, v122
	v_fmac_f32_e32 v77, v43, v123
	ds_read_b128 v[116:119], v67 offset:18432
	v_add_f32_e32 v77, v80, v77
	s_waitcnt lgkmcnt(6)
	v_mul_f32_e32 v78, v45, v125
	v_fmac_f32_e32 v78, v44, v124
	v_fmac_f32_e32 v78, v42, v126
	v_fmac_f32_e32 v78, v43, v127
	v_add_f32_e32 v78, v81, v78
	ds_read_b128 v[120:123], v67 offset:22528
	s_waitcnt lgkmcnt(6)
	v_mul_f32_e32 v45, v45, v129
	v_fmac_f32_e32 v45, v44, v128
	v_fmac_f32_e32 v45, v42, v130
	v_fmac_f32_e32 v45, v43, v131
	v_pk_mul_f32 v[42:43], v[38:39], v[58:59] op_sel_hi:[1,0]
	v_pk_mul_f32 v[38:39], v[40:41], v[58:59] op_sel_hi:[1,0]
	v_pk_mul_f32 v[40:41], v[6:7], v[42:43]
	v_pk_mul_f32 v[38:39], v[8:9], v[38:39]
	v_cvt_pk_bf16_f32 v42, v40, v41
	v_add_f32_e32 v79, v48, v45
	v_cvt_pk_bf16_f32 v43, v38, v39
	global_store_dwordx2 v[46:47], v[42:43], off offset:1024
	ds_read_b128 v[124:127], v67 offset:26624
	ds_read_b128 v[128:131], v67 offset:30720
	s_waitcnt lgkmcnt(7)
	v_mul_f32_e32 v43, v41, v101
	v_fmac_f32_e32 v43, v40, v100
	v_fmac_f32_e32 v43, v38, v102
	v_fmac_f32_e32 v43, v39, v103
	v_add_f32_e32 v42, v49, v43
	s_waitcnt lgkmcnt(6)
	v_mul_f32_e32 v43, v41, v105
	v_fmac_f32_e32 v43, v40, v104
	v_fmac_f32_e32 v43, v38, v106
	v_fmac_f32_e32 v43, v39, v107
	ds_read_b128 v[100:103], v67 offset:34816
	v_add_f32_e32 v43, v51, v43
	s_waitcnt lgkmcnt(6)
	v_mul_f32_e32 v44, v41, v109
	v_fmac_f32_e32 v44, v40, v108
	v_fmac_f32_e32 v44, v38, v110
	v_fmac_f32_e32 v44, v39, v111
	ds_read_b128 v[104:107], v67 offset:38912
	v_add_f32_e32 v44, v60, v44
	s_waitcnt lgkmcnt(6)
	v_mul_f32_e32 v45, v41, v113
	v_fmac_f32_e32 v45, v40, v112
	v_fmac_f32_e32 v45, v38, v114
	v_fmac_f32_e32 v45, v39, v115
	ds_read_b128 v[108:111], v67 offset:43008
	v_add_f32_e32 v45, v61, v45
	s_waitcnt lgkmcnt(6)
	v_mul_f32_e32 v48, v41, v117
	v_fmac_f32_e32 v48, v40, v116
	v_fmac_f32_e32 v48, v38, v118
	v_fmac_f32_e32 v48, v39, v119
	ds_read_b128 v[112:115], v67 offset:47104
	v_add_f32_e32 v48, v68, v48
	s_waitcnt lgkmcnt(6)
	v_mul_f32_e32 v49, v41, v121
	v_fmac_f32_e32 v49, v40, v120
	v_fmac_f32_e32 v49, v38, v122
	v_fmac_f32_e32 v49, v39, v123
	ds_read_b128 v[116:119], v67 offset:51200
	v_add_f32_e32 v49, v69, v49
	s_waitcnt lgkmcnt(6)
; #define LAS __attribute__((address_space(3)))
; __device__ __forceinline__ unsigned cvt_pk_bf16(float lo, float hi) { unsigned r; asm volatile("v_cvt_pk_bf16_f32 %0, %1, %2" : "=v"(r) : "v"(lo), "v"(hi)); return r; }
; __device__ void phase_norm_alow(const Params& P, int l, int half, LAS unsigned char* lds) {
;     ...
;         for (int i = 0; i < 4; ++i) { f32x4 h = v[i] * r * gv[i];
;             u32x2 w; w.x = cvt_pk_bf16(h[0], h[1]); w.y = cvt_pk_bf16(h[2], h[3]);
;             *(u32x2*)(H + (size_t)row * DM + i * 256 + lane * 4) = w;
; #pragma unroll
;             for (int c = 0; c < 16; ++c) { const f32x4 wv = *(const LAS f32x4*)(WaT + c * 1024 + i * 256 + lane * 4); a[c] += h[0] * wv[0] + h[1] * wv[1] + h[2] * wv[2] + h[3] * wv[3]; } }
	v_mul_f32_e32 v51, v41, v125
	v_fmac_f32_e32 v51, v40, v124
	v_fmac_f32_e32 v51, v38, v126
	v_fmac_f32_e32 v51, v39, v127
	ds_read_b128 v[120:123], v67 offset:55296
	v_add_f32_e32 v51, v70, v51
	s_waitcnt lgkmcnt(6)
	v_mul_f32_e32 v60, v41, v129
	v_fmac_f32_e32 v60, v40, v128
	v_fmac_f32_e32 v60, v38, v130
	v_fmac_f32_e32 v60, v39, v131
	v_add_f32_e32 v60, v71, v60
	ds_read_b128 v[124:127], v67 offset:59392
	s_waitcnt lgkmcnt(6)
	v_mul_f32_e32 v61, v41, v101
	v_fmac_f32_e32 v61, v40, v100
	v_fmac_f32_e32 v61, v38, v102
	v_fmac_f32_e32 v61, v39, v103
	ds_read_b128 v[128:131], v67 offset:63488
	v_add_f32_e32 v61, v72, v61
	s_waitcnt lgkmcnt(6)
	v_mul_f32_e32 v69, v41, v105
	v_fmac_f32_e32 v69, v40, v104
	v_fmac_f32_e32 v69, v38, v106
	v_fmac_f32_e32 v69, v39, v107
	v_add_f32_e32 v68, v73, v69
	ds_read_b128 v[100:103], v67 offset:3072
	s_waitcnt lgkmcnt(6)
	v_mul_f32_e32 v69, v41, v109
	v_fmac_f32_e32 v69, v40, v108
	v_fmac_f32_e32 v69, v38, v110
	v_fmac_f32_e32 v69, v39, v111
	ds_read_b128 v[104:107], v67 offset:7168
	v_add_f32_e32 v69, v74, v69
	s_waitcnt lgkmcnt(6)
	v_mul_f32_e32 v71, v41, v113
	v_fmac_f32_e32 v71, v40, v112
	v_fmac_f32_e32 v71, v38, v114
	v_fmac_f32_e32 v71, v39, v115
	v_add_f32_e32 v70, v75, v71
	ds_read_b128 v[108:111], v67 offset:11264
	s_waitcnt lgkmcnt(6)
	v_mul_f32_e32 v71, v41, v117
	v_fmac_f32_e32 v71, v40, v116
	v_fmac_f32_e32 v71, v38, v118
	v_fmac_f32_e32 v71, v39, v119
	ds_read_b128 v[112:115], v67 offset:15360
	v_add_f32_e32 v71, v76, v71
	s_waitcnt lgkmcnt(6)
	v_mul_f32_e32 v73, v41, v121
	v_fmac_f32_e32 v73, v40, v120
	v_fmac_f32_e32 v73, v38, v122
	v_fmac_f32_e32 v73, v39, v123
	v_add_f32_e32 v72, v77, v73
	ds_read_b128 v[116:119], v67 offset:19456
	s_waitcnt lgkmcnt(6)
	v_mul_f32_e32 v73, v41, v125
	v_fmac_f32_e32 v73, v40, v124
	v_fmac_f32_e32 v73, v38, v126
	v_fmac_f32_e32 v73, v39, v127
	ds_read_b128 v[120:123], v67 offset:23552
	v_add_f32_e32 v73, v78, v73
	s_waitcnt lgkmcnt(6)
	v_mul_f32_e32 v41, v41, v129
	v_fmac_f32_e32 v41, v40, v128
	v_fmac_f32_e32 v41, v38, v130
	v_fmac_f32_e32 v41, v39, v131
	v_add_f32_e32 v38, v79, v41
	v_pk_mul_f32 v[40:41], v[34:35], v[58:59] op_sel_hi:[1,0]
	v_pk_mul_f32 v[34:35], v[36:37], v[58:59] op_sel_hi:[1,0]
	v_pk_mul_f32 v[36:37], v[2:3], v[40:41]
	v_pk_mul_f32 v[34:35], v[4:5], v[34:35]
	v_cvt_pk_bf16_f32 v40, v36, v37
	s_nop 0
	v_cvt_pk_bf16_f32 v41, v34, v35
	ds_read_b128 v[124:127], v67 offset:27648
	global_store_dwordx2 v[46:47], v[40:41], off offset:1536
	s_waitcnt lgkmcnt(6)
	v_mul_f32_e32 v39, v37, v101
	v_fmac_f32_e32 v39, v36, v100
	v_fmac_f32_e32 v39, v34, v102
	v_fmac_f32_e32 v39, v35, v103
	ds_read_b128 v[128:131], v67 offset:31744
	v_add_f32_e32 v39, v42, v39
	s_waitcnt lgkmcnt(6)
	v_mul_f32_e32 v40, v37, v105
	v_fmac_f32_e32 v40, v36, v104
	v_fmac_f32_e32 v40, v34, v106
	v_fmac_f32_e32 v40, v35, v107
	ds_read_b128 v[100:103], v67 offset:35840
	v_add_f32_e32 v40, v43, v40
	s_waitcnt lgkmcnt(6)
	v_mul_f32_e32 v41, v37, v109
	v_fmac_f32_e32 v41, v36, v108
	v_fmac_f32_e32 v41, v34, v110
	v_fmac_f32_e32 v41, v35, v111
	ds_read_b128 v[104:107], v67 offset:39936
	v_add_f32_e32 v41, v44, v41
	s_waitcnt lgkmcnt(6)
	v_mul_f32_e32 v42, v37, v113
	v_fmac_f32_e32 v42, v36, v112
	v_fmac_f32_e32 v42, v34, v114
	v_fmac_f32_e32 v42, v35, v115
	v_add_f32_e32 v42, v45, v42
	ds_read_b128 v[108:111], v67 offset:44032
	s_waitcnt lgkmcnt(6)
	v_mul_f32_e32 v43, v37, v117
	v_fmac_f32_e32 v43, v36, v116
	v_fmac_f32_e32 v43, v34, v118
	v_fmac_f32_e32 v43, v35, v119
	ds_read_b128 v[112:115], v67 offset:48128
	v_add_f32_e32 v43, v48, v43
	s_waitcnt lgkmcnt(6)
	v_mul_f32_e32 v45, v37, v121
	v_fmac_f32_e32 v45, v36, v120
	v_fmac_f32_e32 v45, v34, v122
	v_fmac_f32_e32 v45, v35, v123
	v_add_f32_e32 v48, v49, v45
	ds_read_b128 v[116:119], v67 offset:52224
	s_waitcnt lgkmcnt(6)
	v_mul_f32_e32 v45, v37, v125
	v_fmac_f32_e32 v45, v36, v124
	v_fmac_f32_e32 v45, v34, v126
	v_fmac_f32_e32 v45, v35, v127
	v_add_f32_e32 v49, v51, v45
	ds_read_b128 v[120:123], v67 offset:56320
	s_waitcnt lgkmcnt(6)
	v_mul_f32_e32 v45, v37, v129
	v_fmac_f32_e32 v45, v36, v128
	v_fmac_f32_e32 v45, v34, v130
	v_fmac_f32_e32 v45, v35, v131
	v_add_f32_e32 v51, v60, v45
	ds_read_b128 v[124:127], v67 offset:60416
	s_waitcnt lgkmcnt(6)
; #define LAS __attribute__((address_space(3)))
; __device__ __forceinline__ unsigned cvt_pk_bf16(float lo, float hi) { unsigned r; asm volatile("v_cvt_pk_bf16_f32 %0, %1, %2" : "=v"(r) : "v"(lo), "v"(hi)); return r; }
; __device__ void phase_norm_alow(const Params& P, int l, int half, LAS unsigned char* lds) {
;     ...
;         for (int i = 0; i < 4; ++i) { f32x4 h = v[i] * r * gv[i];
;             u32x2 w; w.x = cvt_pk_bf16(h[0], h[1]); w.y = cvt_pk_bf16(h[2], h[3]);
;             *(u32x2*)(H + (size_t)row * DM + i * 256 + lane * 4) = w;
; #pragma unroll
;             for (int c = 0; c < 16; ++c) { const f32x4 wv = *(const LAS f32x4*)(WaT + c * 1024 + i * 256 + lane * 4); a[c] += h[0] * wv[0] + h[1] * wv[1] + h[2] * wv[2] + h[3] * wv[3]; } }
;         float b8[8], b4[4], b2[2], b1;
;         { const bool up = (lane & 32) != 0;
; #pragma unroll
;           for (int c = 0; c < 8; ++c) { const float keep = up ? a[c + 8] : a[c], send = up ? a[c] : a[c + 8]; b8[c] = keep + __shfl_xor(send, 32); } }
;         { const bool up = (lane & 16) != 0;
; #pragma unroll
;           for (int c = 0; c < 4; ++c) { const float keep = up ? b8[c + 4] : b8[c], send = up ? b8[c] : b8[c + 4]; b4[c] = keep + __shfl_xor(send, 16); } }
;         { const bool up = (lane & 8) != 0;
; #pragma unroll
;           for (int c = 0; c < 2; ++c) { const float keep = up ? b4[c + 2] : b4[c], send = up ? b4[c] : b4[c + 2]; b2[c] = keep + __shfl_xor(send, 8); } }
;         { const bool up = (lane & 4) != 0; const float keep = up ? b2[1] : b2[0], send = up ? b2[0] : b2[1]; b1 = keep + __shfl_xor(send, 4); }
;         b1 += __shfl_xor(b1, 2); b1 += __shfl_xor(b1, 1);
;         if ((lane & 3) == 0) { const int co = ((lane >> 5) & 1) * 8 + ((lane >> 4) & 1) * 4 + ((lane >> 3) & 1) * 2 + ((lane >> 2) & 1); AL[(size_t)row * 16 + co] = b1; }
	v_mul_f32_e32 v45, v37, v101
	v_fmac_f32_e32 v45, v36, v100
	v_fmac_f32_e32 v45, v34, v102
	v_fmac_f32_e32 v45, v35, v103
	v_add_f32_e32 v58, v61, v45
	ds_read_b128 v[128:131], v67 offset:64512
	s_waitcnt lgkmcnt(6)
	v_mul_f32_e32 v45, v37, v105
	v_fmac_f32_e32 v45, v36, v104
	v_fmac_f32_e32 v45, v34, v106
	v_fmac_f32_e32 v45, v35, v107
	v_add_f32_e32 v60, v68, v45
	s_waitcnt lgkmcnt(5)
	v_mul_f32_e32 v45, v37, v109
	v_fmac_f32_e32 v45, v36, v108
	v_fmac_f32_e32 v45, v34, v110
	v_fmac_f32_e32 v45, v35, v111
	v_add_f32_e32 v61, v69, v45
	s_waitcnt lgkmcnt(4)
	v_mul_f32_e32 v45, v37, v113
	v_fmac_f32_e32 v45, v36, v112
	v_fmac_f32_e32 v45, v34, v114
	v_fmac_f32_e32 v45, v35, v115
	v_add_f32_e32 v68, v70, v45
	s_waitcnt lgkmcnt(3)
	v_mul_f32_e32 v45, v37, v117
	v_fmac_f32_e32 v45, v36, v116
	v_fmac_f32_e32 v45, v34, v118
	v_fmac_f32_e32 v45, v35, v119
	v_add_f32_e32 v69, v71, v45
	s_waitcnt lgkmcnt(2)
	v_mul_f32_e32 v45, v37, v121
	v_fmac_f32_e32 v45, v36, v120
	v_fmac_f32_e32 v45, v34, v122
	v_fmac_f32_e32 v45, v35, v123
	v_add_f32_e32 v70, v72, v45
	s_waitcnt lgkmcnt(1)
	v_mul_f32_e32 v45, v37, v125
	v_fmac_f32_e32 v45, v36, v124
	v_fmac_f32_e32 v45, v34, v126
	v_fmac_f32_e32 v45, v35, v127
	v_add_f32_e32 v71, v73, v45
	s_waitcnt lgkmcnt(0)
	v_mul_f32_e32 v37, v37, v129
	v_fmac_f32_e32 v37, v36, v128
	v_fmac_f32_e32 v37, v34, v130
	v_fmac_f32_e32 v37, v35, v131
	v_cndmask_b32_e32 v36, v39, v58, vcc
	v_add_f32_e32 v34, v38, v37
	ds_bpermute_b32 v36, v59, v36
	v_cndmask_b32_e32 v37, v40, v60, vcc
	ds_bpermute_b32 v37, v59, v37
	v_cndmask_b32_e32 v38, v41, v61, vcc
	ds_bpermute_b32 v38, v59, v38
	v_cndmask_b32_e32 v35, v58, v39, vcc
	v_cndmask_b32_e32 v39, v42, v68, vcc
	s_waitcnt lgkmcnt(2)
	v_add_f32_e32 v35, v35, v36
	v_cndmask_b32_e32 v36, v60, v40, vcc
	ds_bpermute_b32 v39, v59, v39
	v_cndmask_b32_e32 v40, v43, v69, vcc
	s_waitcnt lgkmcnt(2)
	v_add_f32_e32 v36, v36, v37
	v_cndmask_b32_e32 v37, v61, v41, vcc
	ds_bpermute_b32 v40, v59, v40
	v_cndmask_b32_e32 v41, v48, v70, vcc
	s_waitcnt lgkmcnt(2)
	v_add_f32_e32 v37, v37, v38
	v_cndmask_b32_e32 v38, v68, v42, vcc
	ds_bpermute_b32 v41, v59, v41
	v_cndmask_b32_e32 v42, v49, v71, vcc
	ds_bpermute_b32 v42, v59, v42
	s_waitcnt lgkmcnt(3)
	v_add_f32_e32 v38, v38, v39
	v_cndmask_b32_e32 v39, v69, v43, vcc
	s_waitcnt lgkmcnt(2)
	v_add_f32_e32 v39, v39, v40
	v_cndmask_b32_e32 v40, v70, v48, vcc
	s_waitcnt lgkmcnt(1)
	v_add_f32_e32 v40, v40, v41
	v_cndmask_b32_e32 v41, v71, v49, vcc
	s_waitcnt lgkmcnt(0)
	v_add_f32_e32 v41, v41, v42
	v_cndmask_b32_e32 v42, v34, v51, vcc
	v_cndmask_b32_e32 v34, v51, v34, vcc
	ds_bpermute_b32 v34, v59, v34
	s_waitcnt lgkmcnt(0)
	v_add_f32_e32 v34, v42, v34
	v_cndmask_b32_e64 v42, v39, v35, s[36:37]
	v_cndmask_b32_e64 v35, v35, v39, s[36:37]
	v_cndmask_b32_e64 v39, v40, v36, s[36:37]
	v_cndmask_b32_e64 v36, v36, v40, s[36:37]
	ds_bpermute_b32 v36, v62, v36
	ds_bpermute_b32 v35, v62, v35
	s_waitcnt lgkmcnt(1)
	v_add_f32_e32 v36, v39, v36
	v_cndmask_b32_e64 v39, v41, v37, s[36:37]
	v_cndmask_b32_e64 v37, v37, v41, s[36:37]
	ds_bpermute_b32 v37, v62, v37
	s_waitcnt lgkmcnt(1)
	v_add_f32_e32 v35, v42, v35
	s_waitcnt lgkmcnt(0)
	v_add_f32_e32 v37, v39, v37
	v_cndmask_b32_e64 v39, v34, v38, s[36:37]
	v_cndmask_b32_e64 v34, v38, v34, s[36:37]
	ds_bpermute_b32 v34, v62, v34
	v_cndmask_b32_e64 v38, v37, v35, s[38:39]
	v_cndmask_b32_e64 v35, v35, v37, s[38:39]
	ds_bpermute_b32 v35, v63, v35
	s_waitcnt lgkmcnt(1)
	v_add_f32_e32 v34, v39, v34
	v_cndmask_b32_e64 v37, v34, v36, s[38:39]
	v_cndmask_b32_e64 v34, v36, v34, s[38:39]
	ds_bpermute_b32 v34, v63, v34
	s_waitcnt lgkmcnt(1)
	v_add_f32_e32 v35, v38, v35
	s_waitcnt lgkmcnt(0)
	v_add_f32_e32 v34, v37, v34
	v_cndmask_b32_e64 v36, v34, v35, s[40:41]
	v_cndmask_b32_e64 v34, v35, v34, s[40:41]
	ds_bpermute_b32 v34, v64, v34
	s_waitcnt lgkmcnt(0)
	v_add_f32_e32 v34, v36, v34
	s_nop 1
	v_mov_b32_dpp v35, v34 quad_perm:[2,3,0,1] row_mask:0xf bank_mask:0xf
	s_waitcnt lgkmcnt(0)
	v_add_f32_e32 v34, v34, v35
	s_nop 1
	v_mov_b32_dpp v35, v34 quad_perm:[1,0,3,2] row_mask:0xf bank_mask:0xf
	s_and_saveexec_b64 s[0:1], s[42:43]
	s_cbranch_execz .LBB0_677
	v_lshl_add_u64 v[36:37], s[74:75], 0, v[54:55]
	s_waitcnt lgkmcnt(0)
	v_add_f32_e32 v34, v34, v35
	global_store_dword v[36:37], v34, off
	s_branch .LBB0_677

; #define LAS __attribute__((address_space(3)))
; __device__ __forceinline__ unsigned cvt_pk_bf16(float lo, float hi) { unsigned r; asm volatile("v_cvt_pk_bf16_f32 %0, %1, %2" : "=v"(r) : "v"(lo), "v"(hi)); return r; }
; __device__ __forceinline__ float wave_sum(float v) {
; #pragma unroll
;     for (int o = 32; o >= 1; o >>= 1) v += __shfl_xor(v, o);
;     return v;
; }
; __device__ void phase_norm_alow(const Params& P, int l, int half, LAS unsigned char* lds) {
;     ...
;         f32x4 v[4]; float ss = 0.f;
; #pragma unroll
;         for (int i = 0; i < 4; ++i) { v[i] = nv[i]; ss += v[i][0] * v[i][0] + v[i][1] * v[i][1] + v[i][2] * v[i][2] + v[i][3] * v[i][3]; }
;         if (row + rstride < TH) {
; #pragma unroll
;             for (int i = 0; i < 4; ++i) nv[i] = *(const f32x4*)(xs + (size_t)(row + rstride) * DM + i * 256 + lane * 4);
;         }
;         ss = wave_sum(ss);
;         const float r = rsqrtf(ss * (1.0f / DM) + EPS);
;         float a[16];
; #pragma unroll
;         for (int c = 0; c < 16; ++c) a[c] = 0.f;
; #pragma unroll
;         for (int i = 0; i < 4; ++i) { f32x4 h = v[i] * r * gv[i];
;             u32x2 w; w.x = cvt_pk_bf16(h[0], h[1]); w.y = cvt_pk_bf16(h[2], h[3]);
;             *(u32x2*)(H + (size_t)row * DM + i * 256 + lane * 4) = w;
; #pragma unroll
;             for (int c = 0; c < 16; ++c) { const f32x4 wv = *(const LAS f32x4*)(WaT + c * 1024 + i * 256 + lane * 4); a[c] += h[0] * wv[0] + h[1] * wv[1] + h[2] * wv[2] + h[3] * wv[3]; } }
.LBB0_755:
	s_or_b64 exec, exec, s[46:47]
	v_mul_f32_e32 v51, v47, v47
	v_mul_f32_e32 v58, v43, v43
	v_fmac_f32_e32 v51, v46, v46
	v_fmac_f32_e32 v58, v42, v42
	v_fmac_f32_e32 v51, v48, v48
	v_fmac_f32_e32 v58, v44, v44
	v_fmac_f32_e32 v51, v49, v49
	v_fmac_f32_e32 v58, v45, v45
	v_add_f32_e32 v51, v51, v58
	v_mul_f32_e32 v58, v39, v39
	v_fmac_f32_e32 v58, v38, v38
	v_fmac_f32_e32 v58, v40, v40
	v_fmac_f32_e32 v58, v41, v41
	v_add_f32_e32 v51, v51, v58
	v_mul_f32_e32 v58, v35, v35
	v_fmac_f32_e32 v58, v34, v34
	v_fmac_f32_e32 v58, v36, v36
	v_fmac_f32_e32 v58, v37, v37
	v_add_f32_e32 v51, v51, v58
	v_mov_b32_e32 v58, v51
	s_nop 1
	v_permlane32_swap_b32_e32 v58, v51
	s_nop 1
	s_mov_b32 s2, 0x3a88000
	s_waitcnt lgkmcnt(0)
	v_add_f32_e32 v51, v51, v58
	v_mov_b32_e32 v58, v51
	s_nop 1
	v_permlane16_swap_b32_e32 v58, v51
	s_nop 1
	s_waitcnt lgkmcnt(0)
	v_add_f32_e32 v51, v51, v58
	s_nop 1
	v_mov_b32_dpp v58, v51 row_ror:8 row_mask:0xf bank_mask:0xf
	s_waitcnt lgkmcnt(0)
	v_add_f32_e32 v51, v51, v58
	s_nop 1
	v_mov_b32_dpp v58, v51 row_shl:4 row_mask:0xf bank_mask:0x5
	s_nop 1
	v_mov_b32_dpp v58, v51 row_shr:4 row_mask:0xf bank_mask:0xa
	s_waitcnt lgkmcnt(0)
	v_add_f32_e32 v51, v51, v58
	s_nop 1
	v_mov_b32_dpp v58, v51 quad_perm:[2,3,0,1] row_mask:0xf bank_mask:0xf
	s_waitcnt lgkmcnt(0)
	v_add_f32_e32 v51, v51, v58
	s_nop 1
	v_mov_b32_dpp v60, v51 quad_perm:[1,0,3,2] row_mask:0xf bank_mask:0xf
	v_lshl_add_u64 v[58:59], s[74:75], 0, v[52:53]
	v_add_co_u32_e64 v58, s[46:47], s2, v58
	s_waitcnt lgkmcnt(0)
	v_add_f32_e32 v51, v51, v60
	v_fmamk_f32 v51, v51, 0x3a800000, v1
	v_mul_f32_e32 v60, 0x4b800000, v51
	v_cmp_gt_f32_e64 s[0:1], s33, v51
	v_addc_co_u32_e64 v59, s[46:47], 0, v59, s[46:47]
	s_nop 0
	v_cndmask_b32_e64 v51, v51, v60, s[0:1]
	v_rsq_f32_e32 v51, v51
	s_nop 0
	v_mul_f32_e32 v60, 0x45800000, v51
	v_cndmask_b32_e64 v60, v51, v60, s[0:1]
	v_pk_mul_f32 v[46:47], v[46:47], v[60:61] op_sel_hi:[1,0]
	v_pk_mul_f32 v[48:49], v[48:49], v[60:61] op_sel_hi:[1,0]
	s_waitcnt vmcnt(0)
	v_pk_mul_f32 v[82:83], v[14:15], v[46:47]
	v_pk_mul_f32 v[80:81], v[16:17], v[48:49]
	v_cvt_pk_bf16_f32 v84, v82, v83
	v_pk_mul_f32 v[42:43], v[42:43], v[60:61] op_sel_hi:[1,0]
	v_cvt_pk_bf16_f32 v85, v80, v81
	ds_read_b128 v[100:103], v61
	ds_read_b128 v[104:107], v61 offset:4096
	ds_read_b128 v[108:111], v61 offset:8192
	ds_read_b128 v[112:115], v61 offset:12288
	ds_read_b128 v[116:119], v61 offset:16384
	ds_read_b128 v[120:123], v61 offset:20480
	ds_read_b128 v[124:127], v61 offset:24576
	ds_read_b128 v[128:131], v61 offset:28672
	ds_read_b128 v[132:135], v61 offset:32768
	ds_read_b128 v[136:139], v61 offset:36864
	global_store_dwordx2 v[58:59], v[84:85], off
	s_waitcnt lgkmcnt(9)
	v_mul_f32_e32 v47, v101, v83
	v_fmac_f32_e32 v47, v100, v82
	s_waitcnt lgkmcnt(7)
	v_mul_f32_e32 v46, v109, v83
	v_fmac_f32_e32 v46, v108, v82
	v_mul_f32_e32 v51, v105, v83
	v_fmac_f32_e32 v47, v102, v80
	v_fmac_f32_e32 v46, v110, v80
	v_fmac_f32_e32 v51, v104, v82
	v_fmac_f32_e32 v47, v103, v81
	v_fmac_f32_e32 v46, v111, v81
	s_waitcnt lgkmcnt(6)
	v_mul_f32_e32 v68, v113, v83
	v_add_f32_e32 v84, 0, v47
	v_add_f32_e32 v74, 0, v46
	v_fmac_f32_e32 v68, v112, v82
	ds_read_b128 v[100:103], v61 offset:40960
	v_fmac_f32_e32 v68, v114, v80
	v_fmac_f32_e32 v51, v106, v80
	v_fmac_f32_e32 v68, v115, v81
	v_fmac_f32_e32 v51, v107, v81
	v_add_f32_e32 v75, 0, v68
	ds_read_b128 v[104:107], v61 offset:45056
	s_waitcnt lgkmcnt(7)
	v_mul_f32_e32 v47, v117, v83
	v_fmac_f32_e32 v47, v116, v82
	v_fmac_f32_e32 v47, v118, v80
	v_fmac_f32_e32 v47, v119, v81
	s_waitcnt lgkmcnt(6)
	v_mul_f32_e32 v69, v121, v83
	v_add_f32_e32 v76, 0, v47
	v_fmac_f32_e32 v69, v120, v82
	ds_read_b128 v[108:111], v61 offset:49152
	v_fmac_f32_e32 v69, v122, v80
	v_fmac_f32_e32 v69, v123, v81
	v_add_f32_e32 v77, 0, v69
	ds_read_b128 v[112:115], v61 offset:53248
	s_waitcnt lgkmcnt(7)
	v_mul_f32_e32 v47, v125, v83
	v_fmac_f32_e32 v47, v124, v82
	v_fmac_f32_e32 v47, v126, v80
	v_fmac_f32_e32 v47, v127, v81
	s_waitcnt lgkmcnt(6)
	v_mul_f32_e32 v69, v129, v83
	v_add_f32_e32 v78, 0, v47
	v_fmac_f32_e32 v69, v128, v82
	ds_read_b128 v[116:119], v61 offset:57344
	v_fmac_f32_e32 v69, v130, v80
	v_fmac_f32_e32 v69, v131, v81
	v_add_f32_e32 v79, 0, v69
	ds_read_b128 v[120:123], v61 offset:61440
	s_waitcnt lgkmcnt(7)
	v_mul_f32_e32 v47, v133, v83
	v_fmac_f32_e32 v47, v132, v82
	v_fmac_f32_e32 v47, v134, v80
	v_fmac_f32_e32 v47, v135, v81
	s_waitcnt lgkmcnt(6)
	v_mul_f32_e32 v69, v83, v137
	v_add_f32_e32 v85, 0, v47
	v_fmac_f32_e32 v69, v82, v136
	ds_read_b128 v[124:127], v61 offset:1024
	v_fmac_f32_e32 v69, v80, v138
	v_fmac_f32_e32 v69, v81, v139
	v_add_f32_e32 v86, 0, v69
	ds_read_b128 v[128:131], v61 offset:5120
	s_waitcnt lgkmcnt(7)
	v_mul_f32_e32 v47, v83, v101
	v_fmac_f32_e32 v47, v82, v100
	v_fmac_f32_e32 v47, v80, v102
	v_fmac_f32_e32 v47, v81, v103
	s_waitcnt lgkmcnt(6)
	v_mul_f32_e32 v69, v83, v105
	v_add_f32_e32 v87, 0, v47
	v_fmac_f32_e32 v69, v82, v104
	ds_read_b128 v[132:135], v61 offset:9216
	v_fmac_f32_e32 v69, v80, v106
	v_fmac_f32_e32 v69, v81, v107
	v_add_f32_e32 v88, 0, v69
	ds_read_b128 v[136:139], v61 offset:13312
	s_waitcnt lgkmcnt(7)
	v_mul_f32_e32 v47, v83, v109
	v_fmac_f32_e32 v47, v82, v108
	v_fmac_f32_e32 v47, v80, v110
	v_fmac_f32_e32 v47, v81, v111
	s_waitcnt lgkmcnt(6)
	v_mul_f32_e32 v69, v83, v113
	v_add_f32_e32 v89, 0, v47
	v_fmac_f32_e32 v69, v82, v112
	ds_read_b128 v[100:103], v61 offset:17408
	v_fmac_f32_e32 v69, v80, v114
	v_fmac_f32_e32 v69, v81, v115
	v_add_f32_e32 v90, 0, v69
	ds_read_b128 v[104:107], v61 offset:21504
	s_waitcnt lgkmcnt(7)
; #define LAS __attribute__((address_space(3)))
; __device__ __forceinline__ unsigned cvt_pk_bf16(float lo, float hi) { unsigned r; asm volatile("v_cvt_pk_bf16_f32 %0, %1, %2" : "=v"(r) : "v"(lo), "v"(hi)); return r; }
; __device__ void phase_norm_alow(const Params& P, int l, int half, LAS unsigned char* lds) {
;     ...
;         for (int i = 0; i < 4; ++i) { f32x4 h = v[i] * r * gv[i];
;             u32x2 w; w.x = cvt_pk_bf16(h[0], h[1]); w.y = cvt_pk_bf16(h[2], h[3]);
;             *(u32x2*)(H + (size_t)row * DM + i * 256 + lane * 4) = w;
; #pragma unroll
;             for (int c = 0; c < 16; ++c) { const f32x4 wv = *(const LAS f32x4*)(WaT + c * 1024 + i * 256 + lane * 4); a[c] += h[0] * wv[0] + h[1] * wv[1] + h[2] * wv[2] + h[3] * wv[3]; } }
	v_mul_f32_e32 v47, v83, v117
	v_fmac_f32_e32 v47, v82, v116
	v_fmac_f32_e32 v47, v80, v118
	v_fmac_f32_e32 v47, v81, v119
	s_waitcnt lgkmcnt(6)
	v_mul_f32_e32 v48, v83, v121
	v_pk_mul_f32 v[44:45], v[44:45], v[60:61] op_sel_hi:[1,0]
	v_add_f32_e32 v91, 0, v47
	v_fmac_f32_e32 v48, v82, v120
	v_pk_mul_f32 v[68:69], v[12:13], v[44:45]
	v_pk_mul_f32 v[72:73], v[10:11], v[42:43]
	v_fmac_f32_e32 v48, v80, v122
	v_cvt_pk_bf16_f32 v46, v72, v73
	v_cvt_pk_bf16_f32 v47, v68, v69
	ds_read_b128 v[108:111], v61 offset:25600
	v_fmac_f32_e32 v48, v81, v123
	v_add_f32_e32 v80, 0, v48
	global_store_dwordx2 v[58:59], v[46:47], off offset:512
	ds_read_b128 v[112:115], v61 offset:29696
	s_waitcnt lgkmcnt(7)
	v_mul_f32_e32 v43, v73, v125
	v_fmac_f32_e32 v43, v72, v124
	v_fmac_f32_e32 v43, v68, v126
	v_fmac_f32_e32 v43, v69, v127
	s_waitcnt lgkmcnt(6)
	v_mul_f32_e32 v47, v73, v129
	v_add_f32_e32 v81, v84, v43
	v_fmac_f32_e32 v47, v72, v128
	ds_read_b128 v[116:119], v61 offset:33792
	v_fmac_f32_e32 v47, v68, v130
	v_add_f32_e32 v51, 0, v51
	v_fmac_f32_e32 v47, v69, v131
	v_add_f32_e32 v51, v51, v47
	ds_read_b128 v[120:123], v61 offset:37888
	s_waitcnt lgkmcnt(7)
	v_mul_f32_e32 v43, v73, v133
	v_fmac_f32_e32 v43, v72, v132
	v_fmac_f32_e32 v43, v68, v134
	v_fmac_f32_e32 v43, v69, v135
	s_waitcnt lgkmcnt(6)
	v_mul_f32_e32 v47, v73, v137
	v_add_f32_e32 v74, v74, v43
	v_fmac_f32_e32 v47, v72, v136
	ds_read_b128 v[124:127], v61 offset:41984
	v_fmac_f32_e32 v47, v68, v138
	v_fmac_f32_e32 v47, v69, v139
	v_add_f32_e32 v75, v75, v47
	ds_read_b128 v[128:131], v61 offset:46080
	s_waitcnt lgkmcnt(7)
	v_mul_f32_e32 v43, v73, v101
	v_fmac_f32_e32 v43, v72, v100
	v_fmac_f32_e32 v43, v68, v102
	v_fmac_f32_e32 v43, v69, v103
	s_waitcnt lgkmcnt(6)
	v_mul_f32_e32 v47, v73, v105
	v_add_f32_e32 v76, v76, v43
	v_fmac_f32_e32 v47, v72, v104
	ds_read_b128 v[132:135], v61 offset:50176
	v_fmac_f32_e32 v47, v68, v106
	v_fmac_f32_e32 v47, v69, v107
	v_add_f32_e32 v77, v77, v47
	ds_read_b128 v[136:139], v61 offset:54272
	s_waitcnt lgkmcnt(7)
	v_mul_f32_e32 v43, v73, v109
	v_fmac_f32_e32 v43, v72, v108
	v_fmac_f32_e32 v43, v68, v110
	v_fmac_f32_e32 v43, v69, v111
	s_waitcnt lgkmcnt(6)
	v_mul_f32_e32 v47, v73, v113
	v_add_f32_e32 v78, v78, v43
	v_fmac_f32_e32 v47, v72, v112
	ds_read_b128 v[100:103], v61 offset:58368
	v_fmac_f32_e32 v47, v68, v114
	v_fmac_f32_e32 v47, v69, v115
	v_add_f32_e32 v79, v79, v47
	ds_read_b128 v[104:107], v61 offset:62464
	s_waitcnt lgkmcnt(7)
	v_mul_f32_e32 v43, v73, v117
	v_fmac_f32_e32 v43, v72, v116
	v_fmac_f32_e32 v43, v68, v118
	v_fmac_f32_e32 v43, v69, v119
	s_waitcnt lgkmcnt(6)
	v_mul_f32_e32 v47, v73, v121
	v_add_f32_e32 v82, v85, v43
	v_fmac_f32_e32 v47, v72, v120
	ds_read_b128 v[108:111], v61 offset:2048
	v_fmac_f32_e32 v47, v68, v122
	v_fmac_f32_e32 v47, v69, v123
	v_add_f32_e32 v83, v86, v47
	ds_read_b128 v[112:115], v61 offset:6144
	s_waitcnt lgkmcnt(7)
	v_mul_f32_e32 v43, v73, v125
	v_fmac_f32_e32 v43, v72, v124
	v_fmac_f32_e32 v43, v68, v126
	v_fmac_f32_e32 v43, v69, v127
	s_waitcnt lgkmcnt(6)
	v_mul_f32_e32 v47, v73, v129
	v_add_f32_e32 v84, v87, v43
	v_fmac_f32_e32 v47, v72, v128
	ds_read_b128 v[116:119], v61 offset:10240
	v_fmac_f32_e32 v47, v68, v130
	v_fmac_f32_e32 v47, v69, v131
	v_add_f32_e32 v85, v88, v47
	ds_read_b128 v[120:123], v61 offset:14336
	s_waitcnt lgkmcnt(7)
	v_mul_f32_e32 v43, v73, v133
	v_fmac_f32_e32 v43, v72, v132
	v_fmac_f32_e32 v43, v68, v134
	v_fmac_f32_e32 v43, v69, v135
	s_waitcnt lgkmcnt(6)
	v_mul_f32_e32 v47, v73, v137
	v_add_f32_e32 v86, v89, v43
	v_fmac_f32_e32 v47, v72, v136
	ds_read_b128 v[124:127], v61 offset:18432
	v_fmac_f32_e32 v47, v68, v138
	v_fmac_f32_e32 v47, v69, v139
	v_add_f32_e32 v87, v90, v47
	ds_read_b128 v[128:131], v61 offset:22528
	s_waitcnt lgkmcnt(7)
	v_mul_f32_e32 v43, v73, v101
	v_fmac_f32_e32 v43, v72, v100
	v_fmac_f32_e32 v43, v68, v102
	v_fmac_f32_e32 v43, v69, v103
	s_waitcnt lgkmcnt(6)
	v_mul_f32_e32 v44, v73, v105
	v_pk_mul_f32 v[38:39], v[38:39], v[60:61] op_sel_hi:[1,0]
	v_pk_mul_f32 v[40:41], v[40:41], v[60:61] op_sel_hi:[1,0]
	v_add_f32_e32 v88, v91, v43
	v_fmac_f32_e32 v44, v72, v104
	v_pk_mul_f32 v[46:47], v[8:9], v[40:41]
	v_pk_mul_f32 v[70:71], v[6:7], v[38:39]
	v_fmac_f32_e32 v44, v68, v106
	v_cvt_pk_bf16_f32 v42, v70, v71
	v_cvt_pk_bf16_f32 v43, v46, v47
	ds_read_b128 v[132:135], v61 offset:26624
	v_fmac_f32_e32 v44, v69, v107
	v_add_f32_e32 v72, v80, v44
	global_store_dwordx2 v[58:59], v[42:43], off offset:1024
	ds_read_b128 v[136:139], v61 offset:30720
	s_waitcnt lgkmcnt(7)
	v_mul_f32_e32 v39, v71, v109
	v_fmac_f32_e32 v39, v70, v108
	v_fmac_f32_e32 v39, v46, v110
	v_fmac_f32_e32 v39, v47, v111
	v_add_f32_e32 v73, v81, v39
	s_waitcnt lgkmcnt(6)
	v_mul_f32_e32 v43, v71, v113
	ds_read_b128 v[100:103], v61 offset:34816
	v_fmac_f32_e32 v43, v70, v112
	v_fmac_f32_e32 v43, v46, v114
	v_fmac_f32_e32 v43, v47, v115
	v_add_f32_e32 v51, v51, v43
	ds_read_b128 v[104:107], v61 offset:38912
	s_waitcnt lgkmcnt(7)
	v_mul_f32_e32 v39, v71, v117
	v_fmac_f32_e32 v39, v70, v116
	v_fmac_f32_e32 v39, v46, v118
	v_fmac_f32_e32 v39, v47, v119
	v_add_f32_e32 v74, v74, v39
	s_waitcnt lgkmcnt(6)
	v_mul_f32_e32 v43, v71, v121
	ds_read_b128 v[108:111], v61 offset:43008
	v_fmac_f32_e32 v43, v70, v120
	v_fmac_f32_e32 v43, v46, v122
	v_fmac_f32_e32 v43, v47, v123
	v_add_f32_e32 v75, v75, v43
	ds_read_b128 v[112:115], v61 offset:47104
	s_waitcnt lgkmcnt(7)
	v_mul_f32_e32 v39, v71, v125
	v_fmac_f32_e32 v39, v70, v124
	v_fmac_f32_e32 v39, v46, v126
	v_fmac_f32_e32 v39, v47, v127
	v_add_f32_e32 v76, v76, v39
	s_waitcnt lgkmcnt(6)
; #define LAS __attribute__((address_space(3)))
; __device__ __forceinline__ unsigned cvt_pk_bf16(float lo, float hi) { unsigned r; asm volatile("v_cvt_pk_bf16_f32 %0, %1, %2" : "=v"(r) : "v"(lo), "v"(hi)); return r; }
; __device__ void phase_norm_alow(const Params& P, int l, int half, LAS unsigned char* lds) {
;     ...
;         for (int i = 0; i < 4; ++i) { f32x4 h = v[i] * r * gv[i];
;             u32x2 w; w.x = cvt_pk_bf16(h[0], h[1]); w.y = cvt_pk_bf16(h[2], h[3]);
;             *(u32x2*)(H + (size_t)row * DM + i * 256 + lane * 4) = w;
; #pragma unroll
;             for (int c = 0; c < 16; ++c) { const f32x4 wv = *(const LAS f32x4*)(WaT + c * 1024 + i * 256 + lane * 4); a[c] += h[0] * wv[0] + h[1] * wv[1] + h[2] * wv[2] + h[3] * wv[3]; } }
	v_mul_f32_e32 v43, v71, v129
	ds_read_b128 v[116:119], v61 offset:51200
	v_fmac_f32_e32 v43, v70, v128
	v_fmac_f32_e32 v43, v46, v130
	v_fmac_f32_e32 v43, v47, v131
	v_add_f32_e32 v77, v77, v43
	ds_read_b128 v[120:123], v61 offset:55296
	s_waitcnt lgkmcnt(7)
	v_mul_f32_e32 v39, v71, v133
	v_fmac_f32_e32 v39, v70, v132
	v_fmac_f32_e32 v39, v46, v134
	v_fmac_f32_e32 v39, v47, v135
	v_add_f32_e32 v78, v78, v39
	s_waitcnt lgkmcnt(6)
	v_mul_f32_e32 v43, v71, v137
	ds_read_b128 v[124:127], v61 offset:59392
	v_fmac_f32_e32 v43, v70, v136
	v_fmac_f32_e32 v43, v46, v138
	v_fmac_f32_e32 v43, v47, v139
	v_add_f32_e32 v79, v79, v43
	ds_read_b128 v[128:131], v61 offset:63488
	s_waitcnt lgkmcnt(7)
	v_mul_f32_e32 v39, v71, v101
	v_fmac_f32_e32 v39, v70, v100
	v_fmac_f32_e32 v39, v46, v102
	v_fmac_f32_e32 v39, v47, v103
	v_add_f32_e32 v80, v82, v39
	s_waitcnt lgkmcnt(6)
	v_mul_f32_e32 v43, v71, v105
	ds_read_b128 v[132:135], v61 offset:3072
	v_fmac_f32_e32 v43, v70, v104
	v_fmac_f32_e32 v43, v46, v106
	v_fmac_f32_e32 v43, v47, v107
	v_add_f32_e32 v81, v83, v43
	ds_read_b128 v[136:139], v61 offset:7168
	s_waitcnt lgkmcnt(7)
	v_mul_f32_e32 v39, v71, v109
	v_fmac_f32_e32 v39, v70, v108
	v_fmac_f32_e32 v39, v46, v110
	v_fmac_f32_e32 v39, v47, v111
	v_add_f32_e32 v82, v84, v39
	s_waitcnt lgkmcnt(6)
	v_mul_f32_e32 v43, v71, v113
	ds_read_b128 v[100:103], v61 offset:11264
	v_fmac_f32_e32 v43, v70, v112
	v_fmac_f32_e32 v43, v46, v114
	v_fmac_f32_e32 v43, v47, v115
	v_add_f32_e32 v83, v85, v43
	ds_read_b128 v[104:107], v61 offset:15360
	s_waitcnt lgkmcnt(7)
	v_mul_f32_e32 v39, v71, v117
	v_fmac_f32_e32 v39, v70, v116
	v_fmac_f32_e32 v39, v46, v118
	v_fmac_f32_e32 v39, v47, v119
	v_add_f32_e32 v84, v86, v39
	s_waitcnt lgkmcnt(6)
	v_mul_f32_e32 v43, v71, v121
	ds_read_b128 v[108:111], v61 offset:19456
	v_fmac_f32_e32 v43, v70, v120
	v_fmac_f32_e32 v43, v46, v122
	v_fmac_f32_e32 v43, v47, v123
	v_add_f32_e32 v85, v87, v43
	ds_read_b128 v[112:115], v61 offset:23552
	s_waitcnt lgkmcnt(7)
	v_mul_f32_e32 v39, v71, v125
	v_fmac_f32_e32 v39, v70, v124
	v_fmac_f32_e32 v39, v46, v126
	v_fmac_f32_e32 v39, v47, v127
	v_pk_mul_f32 v[34:35], v[34:35], v[60:61] op_sel_hi:[1,0]
	v_pk_mul_f32 v[36:37], v[36:37], v[60:61] op_sel_hi:[1,0]
	v_add_f32_e32 v86, v88, v39
	s_waitcnt lgkmcnt(6)
	v_mul_f32_e32 v40, v71, v129
	v_pk_mul_f32 v[48:49], v[4:5], v[36:37]
	v_pk_mul_f32 v[68:69], v[2:3], v[34:35]
	v_fmac_f32_e32 v40, v70, v128
	v_cvt_pk_bf16_f32 v34, v68, v69
	v_cvt_pk_bf16_f32 v35, v48, v49
	ds_read_b128 v[116:119], v61 offset:27648
	v_fmac_f32_e32 v40, v46, v130
	v_fmac_f32_e32 v40, v47, v131
	v_add_f32_e32 v44, v72, v40
	ds_read_b128 v[120:123], v61 offset:31744
	s_waitcnt lgkmcnt(7)
	v_mul_f32_e32 v37, v69, v133
	v_fmac_f32_e32 v37, v68, v132
	v_fmac_f32_e32 v37, v48, v134
	v_fmac_f32_e32 v37, v49, v135
	v_add_f32_e32 v45, v73, v37
	s_waitcnt lgkmcnt(6)
	v_mul_f32_e32 v41, v69, v137
	ds_read_b128 v[124:127], v61 offset:35840
	v_fmac_f32_e32 v41, v68, v136
	v_fmac_f32_e32 v41, v48, v138
	v_fmac_f32_e32 v41, v49, v139
	v_add_f32_e32 v46, v51, v41
	ds_read_b128 v[128:131], v61 offset:39936
	s_waitcnt lgkmcnt(7)
	v_mul_f32_e32 v37, v69, v101
	v_fmac_f32_e32 v37, v68, v100
	v_fmac_f32_e32 v37, v48, v102
	v_fmac_f32_e32 v37, v49, v103
	v_add_f32_e32 v47, v74, v37
	s_waitcnt lgkmcnt(6)
	v_mul_f32_e32 v41, v69, v105
	ds_read_b128 v[132:135], v61 offset:44032
	v_fmac_f32_e32 v41, v68, v104
	v_fmac_f32_e32 v41, v48, v106
	v_fmac_f32_e32 v41, v49, v107
	v_add_f32_e32 v51, v75, v41
	ds_read_b128 v[136:139], v61 offset:48128
	s_waitcnt lgkmcnt(7)
	v_mul_f32_e32 v37, v69, v109
	v_fmac_f32_e32 v37, v68, v108
	v_fmac_f32_e32 v37, v48, v110
	v_fmac_f32_e32 v37, v49, v111
	v_add_f32_e32 v60, v76, v37
	s_waitcnt lgkmcnt(6)
	v_mul_f32_e32 v41, v69, v113
	ds_read_b128 v[100:103], v61 offset:52224
	v_fmac_f32_e32 v41, v68, v112
	v_fmac_f32_e32 v41, v48, v114
	v_fmac_f32_e32 v41, v49, v115
	v_add_f32_e32 v70, v77, v41
	ds_read_b128 v[104:107], v61 offset:56320
	s_waitcnt lgkmcnt(7)
	v_mul_f32_e32 v37, v69, v117
	v_fmac_f32_e32 v37, v68, v116
	v_fmac_f32_e32 v37, v48, v118
	v_fmac_f32_e32 v37, v49, v119
	v_add_f32_e32 v71, v78, v37
	s_waitcnt lgkmcnt(6)
	v_mul_f32_e32 v41, v69, v121
	ds_read_b128 v[108:111], v61 offset:60416
	v_fmac_f32_e32 v41, v68, v120
	v_fmac_f32_e32 v41, v48, v122
	v_fmac_f32_e32 v41, v49, v123
	v_add_f32_e32 v72, v79, v41
	ds_read_b128 v[112:115], v61 offset:64512
	s_waitcnt lgkmcnt(7)
; #define LAS __attribute__((address_space(3)))
; __device__ __forceinline__ unsigned cvt_pk_bf16(float lo, float hi) { unsigned r; asm volatile("v_cvt_pk_bf16_f32 %0, %1, %2" : "=v"(r) : "v"(lo), "v"(hi)); return r; }
; __device__ void phase_norm_alow(const Params& P, int l, int half, LAS unsigned char* lds) {
;     ...
;         for (int i = 0; i < 4; ++i) { f32x4 h = v[i] * r * gv[i];
;             u32x2 w; w.x = cvt_pk_bf16(h[0], h[1]); w.y = cvt_pk_bf16(h[2], h[3]);
;             *(u32x2*)(H + (size_t)row * DM + i * 256 + lane * 4) = w;
; #pragma unroll
;             for (int c = 0; c < 16; ++c) { const f32x4 wv = *(const LAS f32x4*)(WaT + c * 1024 + i * 256 + lane * 4); a[c] += h[0] * wv[0] + h[1] * wv[1] + h[2] * wv[2] + h[3] * wv[3]; } }
;         float b8[8], b4[4], b2[2], b1;
;         { const bool up = (lane & 32) != 0;
; #pragma unroll
;           for (int c = 0; c < 8; ++c) { const float keep = up ? a[c + 8] : a[c], send = up ? a[c] : a[c + 8]; b8[c] = keep + __shfl_xor(send, 32); } }
;         { const bool up = (lane & 16) != 0;
; #pragma unroll
;           for (int c = 0; c < 4; ++c) { const float keep = up ? b8[c + 4] : b8[c], send = up ? b8[c] : b8[c + 4]; b4[c] = keep + __shfl_xor(send, 16); } }
;         { const bool up = (lane & 8) != 0;
; #pragma unroll
;           for (int c = 0; c < 2; ++c) { const float keep = up ? b4[c + 2] : b4[c], send = up ? b4[c] : b4[c + 2]; b2[c] = keep + __shfl_xor(send, 8); } }
;         { const bool up = (lane & 4) != 0; const float keep = up ? b2[1] : b2[0], send = up ? b2[0] : b2[1]; b1 = keep + __shfl_xor(send, 4); }
;         b1 += __shfl_xor(b1, 2); b1 += __shfl_xor(b1, 1);
;         if ((lane & 3) == 0) { const int co = ((lane >> 5) & 1) * 8 + ((lane >> 4) & 1) * 4 + ((lane >> 3) & 1) * 2 + ((lane >> 2) & 1); AL[(size_t)row * 16 + co] = b1; }
	v_mul_f32_e32 v37, v69, v125
	v_fmac_f32_e32 v37, v68, v124
	v_fmac_f32_e32 v37, v48, v126
	v_fmac_f32_e32 v37, v49, v127
	v_add_f32_e32 v73, v80, v37
	s_waitcnt lgkmcnt(6)
	v_mul_f32_e32 v41, v69, v129
	v_fmac_f32_e32 v41, v68, v128
	v_fmac_f32_e32 v41, v48, v130
	v_fmac_f32_e32 v41, v49, v131
	v_add_f32_e32 v74, v81, v41
	s_waitcnt lgkmcnt(5)
	v_mul_f32_e32 v37, v69, v133
	v_fmac_f32_e32 v37, v68, v132
	v_fmac_f32_e32 v37, v48, v134
	v_fmac_f32_e32 v37, v49, v135
	v_add_f32_e32 v75, v82, v37
	s_waitcnt lgkmcnt(4)
	v_mul_f32_e32 v41, v69, v137
	v_fmac_f32_e32 v41, v68, v136
	v_fmac_f32_e32 v41, v48, v138
	v_fmac_f32_e32 v41, v49, v139
	v_add_f32_e32 v76, v83, v41
	s_waitcnt lgkmcnt(3)
	v_mul_f32_e32 v37, v69, v101
	v_fmac_f32_e32 v37, v68, v100
	v_fmac_f32_e32 v37, v48, v102
	v_fmac_f32_e32 v37, v49, v103
	v_add_f32_e32 v77, v84, v37
	s_waitcnt lgkmcnt(2)
	v_mul_f32_e32 v41, v69, v105
	v_fmac_f32_e32 v41, v68, v104
	v_fmac_f32_e32 v41, v48, v106
	v_fmac_f32_e32 v41, v49, v107
	v_add_f32_e32 v78, v85, v41
	s_waitcnt lgkmcnt(1)
	v_mul_f32_e32 v37, v69, v109
	v_fmac_f32_e32 v37, v68, v108
	v_fmac_f32_e32 v37, v48, v110
	v_fmac_f32_e32 v37, v49, v111
	v_add_f32_e32 v36, v86, v37
	s_waitcnt lgkmcnt(0)
	v_mul_f32_e32 v37, v69, v113
	v_cndmask_b32_e32 v39, v45, v73, vcc
	v_fmac_f32_e32 v37, v68, v112
	ds_bpermute_b32 v39, v62, v39
	v_cndmask_b32_e32 v40, v46, v74, vcc
	ds_bpermute_b32 v40, v62, v40
	v_cndmask_b32_e32 v41, v47, v75, vcc
	v_fmac_f32_e32 v37, v48, v114
	ds_bpermute_b32 v41, v62, v41
	v_cndmask_b32_e32 v42, v51, v76, vcc
	v_fmac_f32_e32 v37, v49, v115
	ds_bpermute_b32 v42, v62, v42
	v_cndmask_b32_e32 v43, v60, v77, vcc
	v_add_f32_e32 v37, v44, v37
	v_cndmask_b32_e32 v38, v73, v45, vcc
	ds_bpermute_b32 v43, v62, v43
	v_cndmask_b32_e32 v44, v70, v78, vcc
	s_waitcnt lgkmcnt(4)
	v_add_f32_e32 v38, v38, v39
	v_cndmask_b32_e32 v39, v74, v46, vcc
	ds_bpermute_b32 v44, v62, v44
	s_waitcnt lgkmcnt(4)
	v_add_f32_e32 v39, v39, v40
	v_cndmask_b32_e32 v40, v75, v47, vcc
	s_waitcnt lgkmcnt(3)
	v_add_f32_e32 v40, v40, v41
	v_cndmask_b32_e32 v41, v76, v51, vcc
	s_waitcnt lgkmcnt(2)
	v_add_f32_e32 v41, v41, v42
	v_cndmask_b32_e32 v42, v77, v60, vcc
	s_waitcnt lgkmcnt(1)
	v_add_f32_e32 v42, v42, v43
	v_cndmask_b32_e32 v43, v78, v70, vcc
	s_waitcnt lgkmcnt(0)
	v_add_f32_e32 v43, v43, v44
	v_cndmask_b32_e32 v44, v36, v71, vcc
	v_cndmask_b32_e32 v36, v71, v36, vcc
	v_cndmask_b32_e32 v45, v72, v37, vcc
	ds_bpermute_b32 v36, v62, v36
	ds_bpermute_b32 v45, v62, v45
	v_cndmask_b32_e32 v37, v37, v72, vcc
	v_cndmask_b32_e64 v46, v38, v42, s[36:37]
	v_cndmask_b32_e64 v38, v42, v38, s[36:37]
	s_waitcnt lgkmcnt(1)
	v_add_f32_e32 v36, v44, v36
	s_waitcnt lgkmcnt(0)
	v_add_f32_e32 v37, v37, v45
	v_cndmask_b32_e64 v42, v43, v39, s[36:37]
	v_cndmask_b32_e64 v39, v39, v43, s[36:37]
	v_cndmask_b32_e64 v43, v40, v36, s[36:37]
	v_cndmask_b32_e64 v44, v41, v37, s[36:37]
	ds_bpermute_b32 v46, v63, v46
	ds_bpermute_b32 v39, v63, v39
	ds_bpermute_b32 v43, v63, v43
	ds_bpermute_b32 v44, v63, v44
	v_cndmask_b32_e64 v36, v36, v40, s[36:37]
	v_cndmask_b32_e64 v37, v37, v41, s[36:37]
	s_waitcnt lgkmcnt(3)
	v_add_f32_e32 v38, v38, v46
	s_waitcnt lgkmcnt(2)
	v_add_f32_e32 v39, v42, v39
	s_waitcnt lgkmcnt(1)
	v_add_f32_e32 v36, v36, v43
	s_waitcnt lgkmcnt(0)
	v_add_f32_e32 v37, v37, v44
	v_cndmask_b32_e64 v40, v38, v36, s[38:39]
	v_cndmask_b32_e64 v41, v39, v37, s[38:39]
	ds_bpermute_b32 v40, v64, v40
	ds_bpermute_b32 v41, v64, v41
	v_cndmask_b32_e64 v36, v36, v38, s[38:39]
	v_cndmask_b32_e64 v37, v37, v39, s[38:39]
	global_store_dwordx2 v[58:59], v[34:35], off offset:1536
	s_waitcnt lgkmcnt(1)
	v_add_f32_e32 v36, v36, v40
	s_waitcnt lgkmcnt(0)
	v_add_f32_e32 v37, v37, v41
	v_cndmask_b32_e64 v38, v36, v37, s[40:41]
	ds_bpermute_b32 v38, v65, v38
	v_cndmask_b32_e64 v36, v37, v36, s[40:41]
	s_waitcnt lgkmcnt(0)
	v_add_f32_e32 v36, v36, v38
	s_nop 1
	v_mov_b32_dpp v37, v36 quad_perm:[2,3,0,1] row_mask:0xf bank_mask:0xf
	s_waitcnt lgkmcnt(0)
	v_add_f32_e32 v36, v36, v37
	s_nop 1
	v_mov_b32_dpp v37, v36 quad_perm:[1,0,3,2] row_mask:0xf bank_mask:0xf
	s_and_saveexec_b64 s[0:1], s[42:43]
	s_cbranch_execz .LBB0_752
	v_lshl_add_u64 v[34:35], s[74:75], 0, v[56:57]
	s_waitcnt lgkmcnt(0)
	v_add_f32_e32 v36, v36, v37
	global_store_dword v[34:35], v36, off
	s_branch .LBB0_752
